# as previous + K-loops: scalar bookkeeping between an MFMA cluster's last MFMA and the next barrier moved to after that barrier
# baseline (speedup 1.0000x reference)
; #define PG8_STAGE(bufoff, gbase, voff) do { _Pragma("unroll") for (int _i = 0; _i < 2; ++_i) \
;         __builtin_amdgcn_global_load_lds((const unsigned*)((const char*)(gbase) + (voff)[_i]), (LAS unsigned*)(lds + (bufoff) + ldsw + _i * 8192), 16, 0, 0); } while (0)
; #define PG8_LDA(dst, b, h) do { _Pragma("unroll") for (int m = 0; m < 4; ++m) _Pragma("unroll") for (int k = 0; k < 2; ++k) dst[m][k] = *(const LAS bf16x8*)(lds + PG8_SA(b, h) + aoff + m * 2048 + k * 1024); } while (0)
; #define PG8_LDB(dst, b, h) do { _Pragma("unroll") for (int n = 0; n < 2; ++n) _Pragma("unroll") for (int k = 0; k < 2; ++k) dst[n][k] = *(const LAS bf16x8*)(lds + PG8_SB(b, h) + boff + n * 2048 + k * 1024); } while (0)
; #define PG8_MMA(ai, bj, At, Bt) do { __builtin_amdgcn_s_setprio(1); _Pragma("unroll") for (int m = 0; m < 4; ++m) _Pragma("unroll") for (int n = 0; n < 2; ++n) _Pragma("unroll") for (int k = 0; k < 2; ++k) \
;         acc[ai][bj][m][n] = __builtin_amdgcn_mfma_f32_16x16x32_bf16(Bt[n][k], At[m][k], acc[ai][bj][m][n], 0, 0, 0); __builtin_amdgcn_s_setprio(0); } while (0)
; #define PG8_WAIT_V(n) asm volatile("s_waitcnt vmcnt(" #n ")" ::: "memory")
; #define PG8_WAIT_L(n) asm volatile("s_waitcnt lgkmcnt(" #n ")" ::: "memory")
; #define PG8_BAR __builtin_amdgcn_s_barrier()
; #define PG8_SCHED __builtin_amdgcn_sched_barrier(0)
; template <class Epi>
; __device__ __forceinline__ void gemm_phase(LAS unsigned char* lds, const Gemm g, const StaticOrder& S, const Epi& E) {
;     ...
;             PG8_LDB(B0, 0, 0); PG8_SCHED; PG8_LDA(At, 0, 0); PG8_STAGE(PG8_SA(1, 1), a1 + hstepA, voffA);
;             PG8_WAIT_L(8); PG8_BAR; PG8_WAIT_L(0); PG8_MMA(0, 0, At, B0); PG8_BAR; PG8_SCHED;
;             PG8_LDB(B1, 0, 1); PG8_STAGE(PG8_SB(0, 0), b2, voffB);
;             PG8_BAR; PG8_WAIT_L(0); PG8_MMA(0, 1, At, B1); PG8_BAR;
;             PG8_LDA(At, 0, 1); PG8_STAGE(PG8_SA(0, 0), a2, voffA);
;             PG8_BAR; PG8_WAIT_L(0); PG8_MMA(1, 0, At, B0); PG8_BAR; PG8_SCHED;
;             PG8_STAGE(PG8_SB(0, 1), b2 + hstepB, voffB);
;             PG8_WAIT_V(6); PG8_BAR; PG8_MMA(1, 1, At, B1); PG8_BAR;
.LBB0_158:
	s_add_u32 s42, s38, 0x100
	s_addc_u32 s43, s39, 0
	s_add_i32 s60, 0, 0x10000
	ds_read_b128 v[146:149], v250
	ds_read_b128 v[162:165], v250 offset:1024
	ds_read_b128 v[166:169], v250 offset:2048
	ds_read_b128 v[170:173], v250 offset:3072
	s_cmp_eq_u32 s59, 28
	s_cselect_b32 s25, s23, s43
	s_cselect_b32 s24, s55, s42
	s_cselect_b32 s5, s21, s58
	s_cselect_b32 s4, s56, s57
	s_add_i32 m0, s46, 0xc000
	ds_read_b128 v[174:177], v154
	ds_read_b128 v[188:191], v154 offset:1024
	ds_read_b128 v[192:195], v154 offset:2048
	ds_read_b128 v[196:199], v154 offset:3072
	ds_read_b128 v[200:203], v154 offset:4096
	ds_read_b128 v[204:207], v154 offset:5120
	ds_read_b128 v[208:211], v154 offset:6144
	ds_read_b128 v[212:215], v154 offset:7168
	global_load_lds_dwordx4 v140, s[38:39]
	s_add_i32 m0, s46, 0xe000
	s_nop 0
	global_load_lds_dwordx4 v142, s[38:39]
	s_waitcnt lgkmcnt(8)
	s_barrier
	s_waitcnt lgkmcnt(0)
	v_mfma_f32_16x16x32_bf16 v[126:129], v[146:149], v[174:177], v[126:129]
	v_mfma_f32_16x16x32_bf16 v[122:125], v[166:169], v[174:177], v[122:125]
	v_mfma_f32_16x16x32_bf16 v[110:113], v[146:149], v[192:195], v[110:113]
	v_mfma_f32_16x16x32_bf16 v[106:109], v[166:169], v[192:195], v[106:109]
	v_mfma_f32_16x16x32_bf16 v[94:97], v[146:149], v[200:203], v[94:97]
	v_mfma_f32_16x16x32_bf16 v[90:93], v[166:169], v[200:203], v[90:93]
	v_mfma_f32_16x16x32_bf16 v[78:81], v[146:149], v[208:211], v[78:81]
	v_mfma_f32_16x16x32_bf16 v[74:77], v[166:169], v[208:211], v[74:77]
	v_mfma_f32_16x16x32_bf16 v[126:129], v[162:165], v[188:191], v[126:129]
	v_mfma_f32_16x16x32_bf16 v[122:125], v[170:173], v[188:191], v[122:125]
	v_mfma_f32_16x16x32_bf16 v[110:113], v[162:165], v[196:199], v[110:113]
	v_mfma_f32_16x16x32_bf16 v[106:109], v[170:173], v[196:199], v[106:109]
	v_mfma_f32_16x16x32_bf16 v[94:97], v[162:165], v[204:207], v[94:97]
	v_mfma_f32_16x16x32_bf16 v[90:93], v[170:173], v[204:207], v[90:93]
	v_mfma_f32_16x16x32_bf16 v[78:81], v[162:165], v[212:215], v[78:81]
	v_mfma_f32_16x16x32_bf16 v[74:77], v[170:173], v[212:215], v[74:77]
	s_barrier
	s_add_i32 s61, 0, 0x14000
	s_add_i32 s38, s60, s45
	s_add_u32 s100, s4, s6
	s_addc_u32 s101, s5, s7
	s_mov_b32 m0, s38
	ds_read_b128 v[216:219], v250 offset:16384
	ds_read_b128 v[220:223], v250 offset:17408
	ds_read_b128 v[224:227], v250 offset:18432
	ds_read_b128 v[228:231], v250 offset:19456
	global_load_lds_dwordx4 v134, s[4:5]
	s_add_i32 m0, s38, 0x2000
	s_nop 0
	global_load_lds_dwordx4 v130, s[4:5]
	s_barrier
	s_waitcnt lgkmcnt(0)
	v_mfma_f32_16x16x32_bf16 v[118:121], v[216:219], v[174:177], v[118:121]
	v_mfma_f32_16x16x32_bf16 v[114:117], v[224:227], v[174:177], v[114:117]
	v_mfma_f32_16x16x32_bf16 v[102:105], v[216:219], v[192:195], v[102:105]
	v_mfma_f32_16x16x32_bf16 v[98:101], v[224:227], v[192:195], v[98:101]
	v_mfma_f32_16x16x32_bf16 v[86:89], v[216:219], v[200:203], v[86:89]
	v_mfma_f32_16x16x32_bf16 v[82:85], v[224:227], v[200:203], v[82:85]
	v_mfma_f32_16x16x32_bf16 v[70:73], v[216:219], v[208:211], v[70:73]
	v_mfma_f32_16x16x32_bf16 v[66:69], v[224:227], v[208:211], v[66:69]
	v_mfma_f32_16x16x32_bf16 v[118:121], v[220:223], v[188:191], v[118:121]
	v_mfma_f32_16x16x32_bf16 v[114:117], v[228:231], v[188:191], v[114:117]
	v_mfma_f32_16x16x32_bf16 v[102:105], v[220:223], v[196:199], v[102:105]
	v_mfma_f32_16x16x32_bf16 v[98:101], v[228:231], v[196:199], v[98:101]
	v_mfma_f32_16x16x32_bf16 v[86:89], v[220:223], v[204:207], v[86:89]
	v_mfma_f32_16x16x32_bf16 v[82:85], v[228:231], v[204:207], v[82:85]
	v_mfma_f32_16x16x32_bf16 v[70:73], v[220:223], v[212:215], v[70:73]
	v_mfma_f32_16x16x32_bf16 v[66:69], v[228:231], v[212:215], v[66:69]
	s_barrier
	s_mov_b32 m0, s46
	s_add_u32 vcc_lo, s24, s6
	s_addc_u32 vcc_hi, s25, s7
	ds_read_b128 v[174:177], v154 offset:16384
	ds_read_b128 v[188:191], v154 offset:17408
	ds_read_b128 v[192:195], v154 offset:18432
	ds_read_b128 v[196:199], v154 offset:19456
	ds_read_b128 v[200:203], v154 offset:20480
	ds_read_b128 v[204:207], v154 offset:21504
	ds_read_b128 v[208:211], v154 offset:22528
	ds_read_b128 v[212:215], v154 offset:23552
	global_load_lds_dwordx4 v136, s[24:25]
	s_mov_b32 m0, s47
	s_nop 0
	global_load_lds_dwordx4 v132, s[24:25]
	s_barrier
	s_waitcnt lgkmcnt(0)
	v_mfma_f32_16x16x32_bf16 v[62:65], v[146:149], v[174:177], v[62:65]
	v_mfma_f32_16x16x32_bf16 v[58:61], v[166:169], v[174:177], v[58:61]
	v_mfma_f32_16x16x32_bf16 v[46:49], v[146:149], v[192:195], v[46:49]
	v_mfma_f32_16x16x32_bf16 v[42:45], v[166:169], v[192:195], v[42:45]
	v_mfma_f32_16x16x32_bf16 v[30:33], v[146:149], v[200:203], v[30:33]
	v_mfma_f32_16x16x32_bf16 v[26:29], v[166:169], v[200:203], v[26:29]
	v_mfma_f32_16x16x32_bf16 v[14:17], v[146:149], v[208:211], v[14:17]
	v_mfma_f32_16x16x32_bf16 v[10:13], v[166:169], v[208:211], v[10:13]
	v_mfma_f32_16x16x32_bf16 v[62:65], v[162:165], v[188:191], v[62:65]
	v_mfma_f32_16x16x32_bf16 v[58:61], v[170:173], v[188:191], v[58:61]
	v_mfma_f32_16x16x32_bf16 v[46:49], v[162:165], v[196:199], v[46:49]
	v_mfma_f32_16x16x32_bf16 v[42:45], v[170:173], v[196:199], v[42:45]
	v_mfma_f32_16x16x32_bf16 v[30:33], v[162:165], v[204:207], v[30:33]
	v_mfma_f32_16x16x32_bf16 v[26:29], v[170:173], v[204:207], v[26:29]
	v_mfma_f32_16x16x32_bf16 v[14:17], v[162:165], v[212:215], v[14:17]
	v_mfma_f32_16x16x32_bf16 v[10:13], v[170:173], v[212:215], v[10:13]
	s_barrier
	s_add_u32 s38, s4, 0x80000
	s_addc_u32 s39, s5, 0
	s_add_i32 s60, s61, s45
	s_mov_b32 m0, s60
	s_nop 0
	global_load_lds_dwordx4 v134, s[38:39]
	s_add_i32 m0, s60, 0x2000
	s_nop 0
	global_load_lds_dwordx4 v130, s[38:39]
	s_waitcnt vmcnt(6)
	s_barrier
; #define PG8_STAGE(bufoff, gbase, voff) do { _Pragma("unroll") for (int _i = 0; _i < 2; ++_i) \
;         __builtin_amdgcn_global_load_lds((const unsigned*)((const char*)(gbase) + (voff)[_i]), (LAS unsigned*)(lds + (bufoff) + ldsw + _i * 8192), 16, 0, 0); } while (0)
; #define PG8_LDA(dst, b, h) do { _Pragma("unroll") for (int m = 0; m < 4; ++m) _Pragma("unroll") for (int k = 0; k < 2; ++k) dst[m][k] = *(const LAS bf16x8*)(lds + PG8_SA(b, h) + aoff + m * 2048 + k * 1024); } while (0)
; #define PG8_LDB(dst, b, h) do { _Pragma("unroll") for (int n = 0; n < 2; ++n) _Pragma("unroll") for (int k = 0; k < 2; ++k) dst[n][k] = *(const LAS bf16x8*)(lds + PG8_SB(b, h) + boff + n * 2048 + k * 1024); } while (0)
; #define PG8_MMA(ai, bj, At, Bt) do { __builtin_amdgcn_s_setprio(1); _Pragma("unroll") for (int m = 0; m < 4; ++m) _Pragma("unroll") for (int n = 0; n < 2; ++n) _Pragma("unroll") for (int k = 0; k < 2; ++k) \
;         acc[ai][bj][m][n] = __builtin_amdgcn_mfma_f32_16x16x32_bf16(Bt[n][k], At[m][k], acc[ai][bj][m][n], 0, 0, 0); __builtin_amdgcn_s_setprio(0); } while (0)
; #define PG8_WAIT_V(n) asm volatile("s_waitcnt vmcnt(" #n ")" ::: "memory")
; #define PG8_WAIT_L(n) asm volatile("s_waitcnt lgkmcnt(" #n ")" ::: "memory")
; #define PG8_BAR __builtin_amdgcn_s_barrier()
; #define PG8_SCHED __builtin_amdgcn_sched_barrier(0)
; template <class Epi>
; __device__ __forceinline__ void gemm_phase(LAS unsigned char* lds, const Gemm g, const StaticOrder& S, const Epi& E) {
;     ...
;             PG8_WAIT_V(6); PG8_BAR; PG8_MMA(1, 1, At, B1); PG8_BAR;
;             PG8_LDB(B0, 1, 0); PG8_SCHED; PG8_LDA(At, 1, 0); PG8_STAGE(PG8_SA(0, 1), a2 + hstepA, voffA);
;             PG8_WAIT_L(8); PG8_BAR; PG8_WAIT_L(0); PG8_MMA(0, 0, At, B0); PG8_BAR; PG8_SCHED;
;             PG8_LDB(B1, 1, 1); PG8_STAGE(PG8_SB(1, 0), b3, voffB);
;             PG8_BAR; PG8_WAIT_L(0); PG8_MMA(0, 1, At, B1); PG8_BAR;
;             PG8_LDA(At, 1, 1); PG8_STAGE(PG8_SA(1, 0), a3, voffA);
;             PG8_BAR; PG8_WAIT_L(0); PG8_MMA(1, 0, At, B0); PG8_BAR; PG8_SCHED;
	v_mfma_f32_16x16x32_bf16 v[54:57], v[216:219], v[174:177], v[54:57]
	v_mfma_f32_16x16x32_bf16 v[50:53], v[224:227], v[174:177], v[50:53]
	v_mfma_f32_16x16x32_bf16 v[38:41], v[216:219], v[192:195], v[38:41]
	v_mfma_f32_16x16x32_bf16 v[34:37], v[224:227], v[192:195], v[34:37]
	v_mfma_f32_16x16x32_bf16 v[22:25], v[216:219], v[200:203], v[22:25]
	v_mfma_f32_16x16x32_bf16 v[18:21], v[224:227], v[200:203], v[18:21]
	v_mfma_f32_16x16x32_bf16 v[6:9], v[216:219], v[208:211], v[6:9]
	v_mfma_f32_16x16x32_bf16 v[2:5], v[224:227], v[208:211], v[2:5]
	v_mfma_f32_16x16x32_bf16 v[54:57], v[220:223], v[188:191], v[54:57]
	v_mfma_f32_16x16x32_bf16 v[50:53], v[228:231], v[188:191], v[50:53]
	v_mfma_f32_16x16x32_bf16 v[38:41], v[220:223], v[196:199], v[38:41]
	v_mfma_f32_16x16x32_bf16 v[34:37], v[228:231], v[196:199], v[34:37]
	v_mfma_f32_16x16x32_bf16 v[22:25], v[220:223], v[204:207], v[22:25]
	v_mfma_f32_16x16x32_bf16 v[18:21], v[228:231], v[204:207], v[18:21]
	v_mfma_f32_16x16x32_bf16 v[6:9], v[220:223], v[212:215], v[6:9]
	v_mfma_f32_16x16x32_bf16 v[2:5], v[228:231], v[212:215], v[2:5]
	s_barrier
	s_add_i32 s38, 0, 0x18000
	ds_read_b128 v[146:149], v250 offset:32768
	ds_read_b128 v[162:165], v250 offset:33792
	ds_read_b128 v[166:169], v250 offset:34816
	ds_read_b128 v[170:173], v250 offset:35840
	s_add_u32 s24, s24, 0x80000
	s_addc_u32 s25, s25, 0
	s_mov_b32 m0, s48
	ds_read_b128 v[174:177], v154 offset:32768
	ds_read_b128 v[188:191], v154 offset:33792
	ds_read_b128 v[192:195], v154 offset:34816
	ds_read_b128 v[196:199], v154 offset:35840
	ds_read_b128 v[200:203], v154 offset:36864
	ds_read_b128 v[204:207], v154 offset:37888
	ds_read_b128 v[208:211], v154 offset:38912
	ds_read_b128 v[212:215], v154 offset:39936
	global_load_lds_dwordx4 v136, s[24:25]
	s_mov_b32 m0, s49
	s_nop 0
	global_load_lds_dwordx4 v132, s[24:25]
	s_waitcnt lgkmcnt(8)
	s_barrier
	s_waitcnt lgkmcnt(0)
	v_mfma_f32_16x16x32_bf16 v[126:129], v[146:149], v[174:177], v[126:129]
	v_mfma_f32_16x16x32_bf16 v[122:125], v[166:169], v[174:177], v[122:125]
	v_mfma_f32_16x16x32_bf16 v[110:113], v[146:149], v[192:195], v[110:113]
	v_mfma_f32_16x16x32_bf16 v[106:109], v[166:169], v[192:195], v[106:109]
	v_mfma_f32_16x16x32_bf16 v[94:97], v[146:149], v[200:203], v[94:97]
	v_mfma_f32_16x16x32_bf16 v[90:93], v[166:169], v[200:203], v[90:93]
	v_mfma_f32_16x16x32_bf16 v[78:81], v[146:149], v[208:211], v[78:81]
	v_mfma_f32_16x16x32_bf16 v[74:77], v[166:169], v[208:211], v[74:77]
	v_mfma_f32_16x16x32_bf16 v[126:129], v[162:165], v[188:191], v[126:129]
	v_mfma_f32_16x16x32_bf16 v[122:125], v[170:173], v[188:191], v[122:125]
	v_mfma_f32_16x16x32_bf16 v[110:113], v[162:165], v[196:199], v[110:113]
	v_mfma_f32_16x16x32_bf16 v[106:109], v[170:173], v[196:199], v[106:109]
	v_mfma_f32_16x16x32_bf16 v[94:97], v[162:165], v[204:207], v[94:97]
	v_mfma_f32_16x16x32_bf16 v[90:93], v[170:173], v[204:207], v[90:93]
	v_mfma_f32_16x16x32_bf16 v[78:81], v[162:165], v[212:215], v[78:81]
	v_mfma_f32_16x16x32_bf16 v[74:77], v[170:173], v[212:215], v[74:77]
	s_barrier
	s_add_i32 s24, 0, 0x1c000
	s_add_i32 s25, s38, s45
	s_mov_b32 m0, s25
	ds_read_b128 v[216:219], v250 offset:49152
	ds_read_b128 v[220:223], v250 offset:50176
	ds_read_b128 v[224:227], v250 offset:51200
	ds_read_b128 v[228:231], v250 offset:52224
	global_load_lds_dwordx4 v134, s[100:101]
	s_add_i32 m0, s25, 0x2000
	s_nop 0
	global_load_lds_dwordx4 v130, s[100:101]
	s_barrier
	s_waitcnt lgkmcnt(0)
	v_mfma_f32_16x16x32_bf16 v[118:121], v[216:219], v[174:177], v[118:121]
	v_mfma_f32_16x16x32_bf16 v[114:117], v[224:227], v[174:177], v[114:117]
	v_mfma_f32_16x16x32_bf16 v[102:105], v[216:219], v[192:195], v[102:105]
	v_mfma_f32_16x16x32_bf16 v[98:101], v[224:227], v[192:195], v[98:101]
	v_mfma_f32_16x16x32_bf16 v[86:89], v[216:219], v[200:203], v[86:89]
	v_mfma_f32_16x16x32_bf16 v[82:85], v[224:227], v[200:203], v[82:85]
	v_mfma_f32_16x16x32_bf16 v[70:73], v[216:219], v[208:211], v[70:73]
	v_mfma_f32_16x16x32_bf16 v[66:69], v[224:227], v[208:211], v[66:69]
	v_mfma_f32_16x16x32_bf16 v[118:121], v[220:223], v[188:191], v[118:121]
	v_mfma_f32_16x16x32_bf16 v[114:117], v[228:231], v[188:191], v[114:117]
	v_mfma_f32_16x16x32_bf16 v[102:105], v[220:223], v[196:199], v[102:105]
	v_mfma_f32_16x16x32_bf16 v[98:101], v[228:231], v[196:199], v[98:101]
	v_mfma_f32_16x16x32_bf16 v[86:89], v[220:223], v[204:207], v[86:89]
	v_mfma_f32_16x16x32_bf16 v[82:85], v[228:231], v[204:207], v[82:85]
	v_mfma_f32_16x16x32_bf16 v[70:73], v[220:223], v[212:215], v[70:73]
	v_mfma_f32_16x16x32_bf16 v[66:69], v[228:231], v[212:215], v[66:69]
	s_barrier
; __device__ __forceinline__ unsigned cvt_pk_bf16(float lo, float hi) { unsigned r; asm volatile("v_cvt_pk_bf16_f32 %0, %1, %2" : "=v"(r) : "v"(lo), "v"(hi)); return r; }
; #define PG8_STAGE(bufoff, gbase, voff) do { _Pragma("unroll") for (int _i = 0; _i < 2; ++_i) \
;         __builtin_amdgcn_global_load_lds((const unsigned*)((const char*)(gbase) + (voff)[_i]), (LAS unsigned*)(lds + (bufoff) + ldsw + _i * 8192), 16, 0, 0); } while (0)
; #define PG8_MMA(ai, bj, At, Bt) do { __builtin_amdgcn_s_setprio(1); _Pragma("unroll") for (int m = 0; m < 4; ++m) _Pragma("unroll") for (int n = 0; n < 2; ++n) _Pragma("unroll") for (int k = 0; k < 2; ++k) \
;         acc[ai][bj][m][n] = __builtin_amdgcn_mfma_f32_16x16x32_bf16(Bt[n][k], At[m][k], acc[ai][bj][m][n], 0, 0, 0); __builtin_amdgcn_s_setprio(0); } while (0)
; #define PG8_WAIT_V(n) asm volatile("s_waitcnt vmcnt(" #n ")" ::: "memory")
; #define PG8_WAIT_L(n) asm volatile("s_waitcnt lgkmcnt(" #n ")" ::: "memory")
; #define PG8_BAR __builtin_amdgcn_s_barrier()
; #define PG8_SCHED __builtin_amdgcn_sched_barrier(0)
; template <class Epi>
; __device__ __forceinline__ void gemm_phase(LAS unsigned char* lds, const Gemm g, const StaticOrder& S, const Epi& E) {
;     ...
;             PG8_BAR; PG8_WAIT_L(0); PG8_MMA(1, 0, At, B0); PG8_BAR; PG8_SCHED;
;             PG8_STAGE(PG8_SB(1, 1), b3 + hstepB, voffB);
;             PG8_WAIT_V(6); PG8_BAR; PG8_MMA(1, 1, At, B1); PG8_BAR;
;         }
;     __device__ __forceinline__ void operator()(const f32x4 (&acc)[2][2][4][2], const Unit& u, int wr, int wc, int fr, int fq, const Pre& pp) const {
;     ...
;             for (int m = 0; m < 4; ++m) { const int r = row0 + ai * HALF + m * 16; const float inv = rsqrtf(rs[ai * 4 + m] * (1.0f / DM) + EPS);
; #pragma unroll
;                 for (int bj = 0; bj < 2; ++bj) { const f32x4 v0 = acc[ai][bj][m][0] * inv, v1 = acc[ai][bj][m][1] * inv; const int c = col0 + bj * HALF;
;                     u32x4 w; w.x = cvt_pk_bf16(v0[0], v0[1]); w.y = cvt_pk_bf16(v0[2], v0[3]); w.z = cvt_pk_bf16(v1[0], v1[1]); w.w = cvt_pk_bf16(v1[2], v1[3]);
;                     bf16_t* dst = gm ? UG + (size_t)(c >> 4) * GSTR + r * 16 + (c & 15) : O + (size_t)r * DE2 + c;
	s_mov_b32 m0, s50
	ds_read_b128 v[174:177], v154 offset:49152
	ds_read_b128 v[188:191], v154 offset:50176
	ds_read_b128 v[192:195], v154 offset:51200
	ds_read_b128 v[196:199], v154 offset:52224
	ds_read_b128 v[200:203], v154 offset:53248
	ds_read_b128 v[204:207], v154 offset:54272
	ds_read_b128 v[208:211], v154 offset:55296
	ds_read_b128 v[212:215], v154 offset:56320
	global_load_lds_dwordx4 v136, vcc
	s_mov_b32 m0, s51
	s_nop 0
	global_load_lds_dwordx4 v132, vcc
	s_barrier
	s_waitcnt lgkmcnt(0)
	v_mfma_f32_16x16x32_bf16 v[62:65], v[146:149], v[174:177], v[62:65]
	v_mfma_f32_16x16x32_bf16 v[58:61], v[166:169], v[174:177], v[58:61]
	v_mfma_f32_16x16x32_bf16 v[46:49], v[146:149], v[192:195], v[46:49]
	v_mfma_f32_16x16x32_bf16 v[42:45], v[166:169], v[192:195], v[42:45]
	v_mfma_f32_16x16x32_bf16 v[30:33], v[146:149], v[200:203], v[30:33]
	v_mfma_f32_16x16x32_bf16 v[26:29], v[166:169], v[200:203], v[26:29]
	v_mfma_f32_16x16x32_bf16 v[14:17], v[146:149], v[208:211], v[14:17]
	v_mfma_f32_16x16x32_bf16 v[10:13], v[166:169], v[208:211], v[10:13]
	v_mfma_f32_16x16x32_bf16 v[62:65], v[162:165], v[188:191], v[62:65]
	v_mfma_f32_16x16x32_bf16 v[58:61], v[170:173], v[188:191], v[58:61]
	v_mfma_f32_16x16x32_bf16 v[46:49], v[162:165], v[196:199], v[46:49]
	v_mfma_f32_16x16x32_bf16 v[42:45], v[170:173], v[196:199], v[42:45]
	v_mfma_f32_16x16x32_bf16 v[30:33], v[162:165], v[204:207], v[30:33]
	v_mfma_f32_16x16x32_bf16 v[26:29], v[170:173], v[204:207], v[26:29]
	v_mfma_f32_16x16x32_bf16 v[14:17], v[162:165], v[212:215], v[14:17]
	v_mfma_f32_16x16x32_bf16 v[10:13], v[170:173], v[212:215], v[10:13]
	s_barrier
	s_add_u32 s4, s4, 0x80080
	s_addc_u32 s5, s5, 0
	s_add_i32 s24, s24, s45
	s_mov_b32 m0, s24
	s_nop 0
	global_load_lds_dwordx4 v134, s[4:5]
	s_add_i32 m0, s24, 0x2000
	s_nop 0
	global_load_lds_dwordx4 v130, s[4:5]
	s_waitcnt vmcnt(6)
	s_barrier
	v_mfma_f32_16x16x32_bf16 v[54:57], v[216:219], v[174:177], v[54:57]
	v_mfma_f32_16x16x32_bf16 v[50:53], v[224:227], v[174:177], v[50:53]
	v_mfma_f32_16x16x32_bf16 v[38:41], v[216:219], v[192:195], v[38:41]
	v_mfma_f32_16x16x32_bf16 v[34:37], v[224:227], v[192:195], v[34:37]
	v_mfma_f32_16x16x32_bf16 v[22:25], v[216:219], v[200:203], v[22:25]
	v_mfma_f32_16x16x32_bf16 v[18:21], v[224:227], v[200:203], v[18:21]
	v_mfma_f32_16x16x32_bf16 v[6:9], v[216:219], v[208:211], v[6:9]
	v_mfma_f32_16x16x32_bf16 v[2:5], v[224:227], v[208:211], v[2:5]
	v_mfma_f32_16x16x32_bf16 v[54:57], v[220:223], v[188:191], v[54:57]
	v_mfma_f32_16x16x32_bf16 v[50:53], v[228:231], v[188:191], v[50:53]
	v_mfma_f32_16x16x32_bf16 v[38:41], v[220:223], v[196:199], v[38:41]
	v_mfma_f32_16x16x32_bf16 v[34:37], v[228:231], v[196:199], v[34:37]
	v_mfma_f32_16x16x32_bf16 v[22:25], v[220:223], v[204:207], v[22:25]
	v_mfma_f32_16x16x32_bf16 v[18:21], v[228:231], v[204:207], v[18:21]
	v_mfma_f32_16x16x32_bf16 v[6:9], v[220:223], v[212:215], v[6:9]
	v_mfma_f32_16x16x32_bf16 v[2:5], v[228:231], v[212:215], v[2:5]
	s_barrier
	s_add_i32 s59, s59, 2
	s_add_u32 s57, s57, 0x100
	s_addc_u32 s58, s58, 0
	s_cmp_gt_u32 s59, 29
	s_mov_b64 s[38:39], s[42:43]
	s_cbranch_scc0 .LBB0_158
	v_fmamk_f32 v0, v145, 0x3a000000, v233
	v_cmp_gt_f32_e32 vcc, s66, v0
	v_mul_f32_e32 v145, 0x4b800000, v0
	v_readlane_b32 s38, v254, 47
	v_cndmask_b32_e32 v0, v0, v145, vcc
	v_rsq_f32_e32 v0, v0
	v_lshl_add_u32 v146, s54, 8, v139
	s_cmp_gt_i32 s53, 15
	v_readlane_b32 s39, v254, 48
	v_mul_f32_e32 v145, 0x45800000, v0
	s_cselect_b64 s[4:5], -1, 0
	s_xor_b64 s[38:39], s[38:39], -1
	v_cndmask_b32_e32 v148, v0, v145, vcc
	v_ashrrev_i32_e32 v147, 31, v146
	s_or_b64 s[4:5], s[38:39], s[4:5]
	v_lshl_or_b32 v144, s53, 8, v153
	v_lshlrev_b64 v[150:151], 14, v[146:147]
	v_pk_mul_f32 v[128:129], v[148:149], v[128:129] op_sel_hi:[0,1]
	s_mov_b64 s[24:25], -1
	v_pk_mul_f32 v[126:127], v[148:149], v[126:127] op_sel_hi:[0,1]
	v_pk_mul_f32 v[162:163], v[148:149], v[124:125] op_sel_hi:[0,1]
	v_pk_mul_f32 v[124:125], v[148:149], v[122:123] op_sel_hi:[0,1]
	v_cvt_pk_bf16_f32 v122, v126, v127
	v_cvt_pk_bf16_f32 v123, v128, v129
	s_and_b64 vcc, exec, s[4:5]
	v_lshl_add_u64 v[128:129], s[16:17], 0, v[150:151]
	v_ashrrev_i32_e32 v145, 31, v144
	v_cvt_pk_bf16_f32 v124, v124, v125
	v_cvt_pk_bf16_f32 v125, v162, v163
	s_cbranch_vccz .LBB0_161
	v_lshl_add_u64 v[150:151], v[144:145], 1, v[128:129]
	s_mov_b64 s[24:25], 0

; #define PG8_STAGE(bufoff, gbase, voff) do { _Pragma("unroll") for (int _i = 0; _i < 2; ++_i) \
;         __builtin_amdgcn_global_load_lds((const unsigned*)((const char*)(gbase) + (voff)[_i]), (LAS unsigned*)(lds + (bufoff) + ldsw + _i * 8192), 16, 0, 0); } while (0)
; #define PG8_LDA(dst, b, h) do { _Pragma("unroll") for (int m = 0; m < 4; ++m) _Pragma("unroll") for (int k = 0; k < 2; ++k) dst[m][k] = *(const LAS bf16x8*)(lds + PG8_SA(b, h) + aoff + m * 2048 + k * 1024); } while (0)
; #define PG8_LDB(dst, b, h) do { _Pragma("unroll") for (int n = 0; n < 2; ++n) _Pragma("unroll") for (int k = 0; k < 2; ++k) dst[n][k] = *(const LAS bf16x8*)(lds + PG8_SB(b, h) + boff + n * 2048 + k * 1024); } while (0)
; #define PG8_MMA(ai, bj, At, Bt) do { __builtin_amdgcn_s_setprio(1); _Pragma("unroll") for (int m = 0; m < 4; ++m) _Pragma("unroll") for (int n = 0; n < 2; ++n) _Pragma("unroll") for (int k = 0; k < 2; ++k) \
;         acc[ai][bj][m][n] = __builtin_amdgcn_mfma_f32_16x16x32_bf16(Bt[n][k], At[m][k], acc[ai][bj][m][n], 0, 0, 0); __builtin_amdgcn_s_setprio(0); } while (0)
; #define PG8_WAIT_V(n) asm volatile("s_waitcnt vmcnt(" #n ")" ::: "memory")
; #define PG8_WAIT_L(n) asm volatile("s_waitcnt lgkmcnt(" #n ")" ::: "memory")
; #define PG8_BAR __builtin_amdgcn_s_barrier()
; #define PG8_SCHED __builtin_amdgcn_sched_barrier(0)
; template <class Epi>
; __device__ __forceinline__ void gemm_phase(LAS unsigned char* lds, const Gemm g, const StaticOrder& S, const Epi& E) {
;     ...
;             PG8_LDB(B0, 0, 0); PG8_SCHED; PG8_LDA(At, 0, 0); PG8_STAGE(PG8_SA(1, 1), a1 + hstepA, voffA);
;             PG8_WAIT_L(8); PG8_BAR; PG8_WAIT_L(0); PG8_MMA(0, 0, At, B0); PG8_BAR; PG8_SCHED;
;             PG8_LDB(B1, 0, 1); PG8_STAGE(PG8_SB(0, 0), b2, voffB);
;             PG8_BAR; PG8_WAIT_L(0); PG8_MMA(0, 1, At, B1); PG8_BAR;
;             PG8_LDA(At, 0, 1); PG8_STAGE(PG8_SA(0, 0), a2, voffA);
;             PG8_BAR; PG8_WAIT_L(0); PG8_MMA(1, 0, At, B0); PG8_BAR; PG8_SCHED;
;             PG8_STAGE(PG8_SB(0, 1), b2 + hstepB, voffB);
;             PG8_WAIT_V(6); PG8_BAR; PG8_MMA(1, 1, At, B1); PG8_BAR;
.LBB0_359:
	s_add_u32 s26, s22, 0x100
	s_addc_u32 s27, s23, 0
	s_add_i32 s65, 0, 0x10000
	ds_read_b128 v[70:73], v250
	ds_read_b128 v[74:77], v250 offset:1024
	ds_read_b128 v[82:85], v250 offset:2048
	ds_read_b128 v[86:89], v250 offset:3072
	s_cmp_eq_u32 s64, 60
	s_cselect_b32 s25, s17, s27
	s_cselect_b32 s24, s60, s26
	s_cselect_b32 s37, s15, s63
	s_cselect_b32 s36, s61, s62
	s_add_i32 m0, s53, 0xc000
	ds_read_b128 v[146:149], v211
	ds_read_b128 v[150:153], v211 offset:1024
	ds_read_b128 v[154:157], v211 offset:2048
	ds_read_b128 v[158:161], v211 offset:3072
	ds_read_b128 v[162:165], v211 offset:4096
	ds_read_b128 v[166:169], v211 offset:5120
	ds_read_b128 v[170:173], v211 offset:6144
	ds_read_b128 v[184:187], v211 offset:7168
	global_load_lds_dwordx4 v190, s[22:23]
	s_add_i32 m0, s53, 0xe000
	s_nop 0
	global_load_lds_dwordx4 v192, s[22:23]
	s_waitcnt lgkmcnt(8)
	s_barrier
	s_waitcnt lgkmcnt(0)
	v_mfma_f32_16x16x32_bf16 v[142:145], v[70:73], v[146:149], v[142:145]
	v_mfma_f32_16x16x32_bf16 v[138:141], v[82:85], v[146:149], v[138:141]
	v_mfma_f32_16x16x32_bf16 v[126:129], v[70:73], v[154:157], v[126:129]
	v_mfma_f32_16x16x32_bf16 v[122:125], v[82:85], v[154:157], v[122:125]
	v_mfma_f32_16x16x32_bf16 v[110:113], v[70:73], v[162:165], v[110:113]
	v_mfma_f32_16x16x32_bf16 v[106:109], v[82:85], v[162:165], v[106:109]
	v_mfma_f32_16x16x32_bf16 v[94:97], v[70:73], v[170:173], v[94:97]
	v_mfma_f32_16x16x32_bf16 v[90:93], v[82:85], v[170:173], v[90:93]
	v_mfma_f32_16x16x32_bf16 v[142:145], v[74:77], v[150:153], v[142:145]
	v_mfma_f32_16x16x32_bf16 v[138:141], v[86:89], v[150:153], v[138:141]
	v_mfma_f32_16x16x32_bf16 v[126:129], v[74:77], v[158:161], v[126:129]
	v_mfma_f32_16x16x32_bf16 v[122:125], v[86:89], v[158:161], v[122:125]
	v_mfma_f32_16x16x32_bf16 v[110:113], v[74:77], v[166:169], v[110:113]
	v_mfma_f32_16x16x32_bf16 v[106:109], v[86:89], v[166:169], v[106:109]
	v_mfma_f32_16x16x32_bf16 v[94:97], v[74:77], v[184:187], v[94:97]
	v_mfma_f32_16x16x32_bf16 v[90:93], v[86:89], v[184:187], v[90:93]
	s_barrier
	s_add_i32 s66, 0, 0x14000
	s_add_i32 s22, s65, s52
	ds_read_b128 v[194:197], v250 offset:16384
	ds_read_b128 v[198:201], v250 offset:17408
	ds_read_b128 v[202:205], v250 offset:18432
	ds_read_b128 v[212:215], v250 offset:19456
	s_add_u32 s100, s36, s6
	s_addc_u32 s101, s37, s7
	s_mov_b32 m0, s22
	s_nop 0
	global_load_lds_dwordx4 v0, s[36:37]
	s_add_i32 m0, s22, 0x2000
	s_nop 0
	global_load_lds_dwordx4 v174, s[36:37]
	s_barrier
	s_waitcnt lgkmcnt(0)
	v_mfma_f32_16x16x32_bf16 v[134:137], v[194:197], v[146:149], v[134:137]
	v_mfma_f32_16x16x32_bf16 v[130:133], v[202:205], v[146:149], v[130:133]
	v_mfma_f32_16x16x32_bf16 v[118:121], v[194:197], v[154:157], v[118:121]
	v_mfma_f32_16x16x32_bf16 v[114:117], v[202:205], v[154:157], v[114:117]
	v_mfma_f32_16x16x32_bf16 v[102:105], v[194:197], v[162:165], v[102:105]
	v_mfma_f32_16x16x32_bf16 v[98:101], v[202:205], v[162:165], v[98:101]
	v_mfma_f32_16x16x32_bf16 v[78:81], v[194:197], v[170:173], v[78:81]
	v_mfma_f32_16x16x32_bf16 v[66:69], v[202:205], v[170:173], v[66:69]
	v_mfma_f32_16x16x32_bf16 v[134:137], v[198:201], v[150:153], v[134:137]
	v_mfma_f32_16x16x32_bf16 v[130:133], v[212:215], v[150:153], v[130:133]
	v_mfma_f32_16x16x32_bf16 v[118:121], v[198:201], v[158:161], v[118:121]
	v_mfma_f32_16x16x32_bf16 v[114:117], v[212:215], v[158:161], v[114:117]
	v_mfma_f32_16x16x32_bf16 v[102:105], v[198:201], v[166:169], v[102:105]
	v_mfma_f32_16x16x32_bf16 v[98:101], v[212:215], v[166:169], v[98:101]
	v_mfma_f32_16x16x32_bf16 v[78:81], v[198:201], v[184:187], v[78:81]
	v_mfma_f32_16x16x32_bf16 v[66:69], v[212:215], v[184:187], v[66:69]
	s_barrier
	s_mov_b32 m0, s53
	s_add_u32 vcc_lo, s24, s6
	s_addc_u32 vcc_hi, s25, s7
	ds_read_b128 v[146:149], v211 offset:16384
	ds_read_b128 v[150:153], v211 offset:17408
	ds_read_b128 v[154:157], v211 offset:18432
	ds_read_b128 v[158:161], v211 offset:19456
	ds_read_b128 v[162:165], v211 offset:20480
	ds_read_b128 v[166:169], v211 offset:21504
	ds_read_b128 v[170:173], v211 offset:22528
	ds_read_b128 v[184:187], v211 offset:23552
	global_load_lds_dwordx4 v188, s[24:25]
	s_mov_b32 m0, s54
	s_nop 0
	global_load_lds_dwordx4 v176, s[24:25]
	s_barrier
	s_waitcnt lgkmcnt(0)
	v_mfma_f32_16x16x32_bf16 v[62:65], v[70:73], v[146:149], v[62:65]
	v_mfma_f32_16x16x32_bf16 v[58:61], v[82:85], v[146:149], v[58:61]
	v_mfma_f32_16x16x32_bf16 v[46:49], v[70:73], v[154:157], v[46:49]
	v_mfma_f32_16x16x32_bf16 v[42:45], v[82:85], v[154:157], v[42:45]
	v_mfma_f32_16x16x32_bf16 v[30:33], v[70:73], v[162:165], v[30:33]
	v_mfma_f32_16x16x32_bf16 v[26:29], v[82:85], v[162:165], v[26:29]
	v_mfma_f32_16x16x32_bf16 v[14:17], v[70:73], v[170:173], v[14:17]
	v_mfma_f32_16x16x32_bf16 v[10:13], v[82:85], v[170:173], v[10:13]
	v_mfma_f32_16x16x32_bf16 v[62:65], v[74:77], v[150:153], v[62:65]
	v_mfma_f32_16x16x32_bf16 v[58:61], v[86:89], v[150:153], v[58:61]
	v_mfma_f32_16x16x32_bf16 v[46:49], v[74:77], v[158:161], v[46:49]
	v_mfma_f32_16x16x32_bf16 v[42:45], v[86:89], v[158:161], v[42:45]
	v_mfma_f32_16x16x32_bf16 v[30:33], v[74:77], v[166:169], v[30:33]
	v_mfma_f32_16x16x32_bf16 v[26:29], v[86:89], v[166:169], v[26:29]
	v_mfma_f32_16x16x32_bf16 v[14:17], v[74:77], v[184:187], v[14:17]
	v_mfma_f32_16x16x32_bf16 v[10:13], v[86:89], v[184:187], v[10:13]
	s_barrier
	s_add_u32 s22, s36, 0x100000
	s_addc_u32 s23, s37, 0
	s_add_i32 s65, s66, s52
	s_mov_b32 m0, s65
	s_nop 0
	global_load_lds_dwordx4 v0, s[22:23]
	s_add_i32 m0, s65, 0x2000
	s_nop 0
	global_load_lds_dwordx4 v174, s[22:23]
	s_waitcnt vmcnt(6)
	s_barrier
; #define PG8_STAGE(bufoff, gbase, voff) do { _Pragma("unroll") for (int _i = 0; _i < 2; ++_i) \
;         __builtin_amdgcn_global_load_lds((const unsigned*)((const char*)(gbase) + (voff)[_i]), (LAS unsigned*)(lds + (bufoff) + ldsw + _i * 8192), 16, 0, 0); } while (0)
; #define PG8_LDA(dst, b, h) do { _Pragma("unroll") for (int m = 0; m < 4; ++m) _Pragma("unroll") for (int k = 0; k < 2; ++k) dst[m][k] = *(const LAS bf16x8*)(lds + PG8_SA(b, h) + aoff + m * 2048 + k * 1024); } while (0)
; #define PG8_LDB(dst, b, h) do { _Pragma("unroll") for (int n = 0; n < 2; ++n) _Pragma("unroll") for (int k = 0; k < 2; ++k) dst[n][k] = *(const LAS bf16x8*)(lds + PG8_SB(b, h) + boff + n * 2048 + k * 1024); } while (0)
; #define PG8_MMA(ai, bj, At, Bt) do { __builtin_amdgcn_s_setprio(1); _Pragma("unroll") for (int m = 0; m < 4; ++m) _Pragma("unroll") for (int n = 0; n < 2; ++n) _Pragma("unroll") for (int k = 0; k < 2; ++k) \
;         acc[ai][bj][m][n] = __builtin_amdgcn_mfma_f32_16x16x32_bf16(Bt[n][k], At[m][k], acc[ai][bj][m][n], 0, 0, 0); __builtin_amdgcn_s_setprio(0); } while (0)
; #define PG8_WAIT_V(n) asm volatile("s_waitcnt vmcnt(" #n ")" ::: "memory")
; #define PG8_WAIT_L(n) asm volatile("s_waitcnt lgkmcnt(" #n ")" ::: "memory")
; #define PG8_BAR __builtin_amdgcn_s_barrier()
; #define PG8_SCHED __builtin_amdgcn_sched_barrier(0)
; template <class Epi>
; __device__ __forceinline__ void gemm_phase(LAS unsigned char* lds, const Gemm g, const StaticOrder& S, const Epi& E) {
;     ...
;             PG8_WAIT_V(6); PG8_BAR; PG8_MMA(1, 1, At, B1); PG8_BAR;
;             PG8_LDB(B0, 1, 0); PG8_SCHED; PG8_LDA(At, 1, 0); PG8_STAGE(PG8_SA(0, 1), a2 + hstepA, voffA);
;             PG8_WAIT_L(8); PG8_BAR; PG8_WAIT_L(0); PG8_MMA(0, 0, At, B0); PG8_BAR; PG8_SCHED;
;             PG8_LDB(B1, 1, 1); PG8_STAGE(PG8_SB(1, 0), b3, voffB);
;             PG8_BAR; PG8_WAIT_L(0); PG8_MMA(0, 1, At, B1); PG8_BAR;
;             PG8_LDA(At, 1, 1); PG8_STAGE(PG8_SA(1, 0), a3, voffA);
;             PG8_BAR; PG8_WAIT_L(0); PG8_MMA(1, 0, At, B0); PG8_BAR; PG8_SCHED;
	v_mfma_f32_16x16x32_bf16 v[54:57], v[194:197], v[146:149], v[54:57]
	v_mfma_f32_16x16x32_bf16 v[50:53], v[202:205], v[146:149], v[50:53]
	v_mfma_f32_16x16x32_bf16 v[38:41], v[194:197], v[154:157], v[38:41]
	v_mfma_f32_16x16x32_bf16 v[34:37], v[202:205], v[154:157], v[34:37]
	v_mfma_f32_16x16x32_bf16 v[22:25], v[194:197], v[162:165], v[22:25]
	v_mfma_f32_16x16x32_bf16 v[18:21], v[202:205], v[162:165], v[18:21]
	v_mfma_f32_16x16x32_bf16 v[6:9], v[194:197], v[170:173], v[6:9]
	v_mfma_f32_16x16x32_bf16 v[2:5], v[202:205], v[170:173], v[2:5]
	v_mfma_f32_16x16x32_bf16 v[54:57], v[198:201], v[150:153], v[54:57]
	v_mfma_f32_16x16x32_bf16 v[50:53], v[212:215], v[150:153], v[50:53]
	v_mfma_f32_16x16x32_bf16 v[38:41], v[198:201], v[158:161], v[38:41]
	v_mfma_f32_16x16x32_bf16 v[34:37], v[212:215], v[158:161], v[34:37]
	v_mfma_f32_16x16x32_bf16 v[22:25], v[198:201], v[166:169], v[22:25]
	v_mfma_f32_16x16x32_bf16 v[18:21], v[212:215], v[166:169], v[18:21]
	v_mfma_f32_16x16x32_bf16 v[6:9], v[198:201], v[184:187], v[6:9]
	v_mfma_f32_16x16x32_bf16 v[2:5], v[212:215], v[184:187], v[2:5]
	s_barrier
	s_add_i32 s65, 0, 0x18000
	ds_read_b128 v[70:73], v250 offset:32768
	ds_read_b128 v[74:77], v250 offset:33792
	ds_read_b128 v[82:85], v250 offset:34816
	ds_read_b128 v[86:89], v250 offset:35840
	s_add_u32 s22, s24, 0x100000
	s_addc_u32 s23, s25, 0
	s_mov_b32 m0, s55
	ds_read_b128 v[146:149], v211 offset:32768
	ds_read_b128 v[150:153], v211 offset:33792
	ds_read_b128 v[154:157], v211 offset:34816
	ds_read_b128 v[158:161], v211 offset:35840
	ds_read_b128 v[162:165], v211 offset:36864
	ds_read_b128 v[166:169], v211 offset:37888
	ds_read_b128 v[170:173], v211 offset:38912
	ds_read_b128 v[184:187], v211 offset:39936
	global_load_lds_dwordx4 v188, s[22:23]
	s_mov_b32 m0, s56
	s_nop 0
	global_load_lds_dwordx4 v176, s[22:23]
	s_waitcnt lgkmcnt(8)
	s_barrier
	s_waitcnt lgkmcnt(0)
	v_mfma_f32_16x16x32_bf16 v[142:145], v[70:73], v[146:149], v[142:145]
	v_mfma_f32_16x16x32_bf16 v[138:141], v[82:85], v[146:149], v[138:141]
	v_mfma_f32_16x16x32_bf16 v[126:129], v[70:73], v[154:157], v[126:129]
	v_mfma_f32_16x16x32_bf16 v[122:125], v[82:85], v[154:157], v[122:125]
	v_mfma_f32_16x16x32_bf16 v[110:113], v[70:73], v[162:165], v[110:113]
	v_mfma_f32_16x16x32_bf16 v[106:109], v[82:85], v[162:165], v[106:109]
	v_mfma_f32_16x16x32_bf16 v[94:97], v[70:73], v[170:173], v[94:97]
	v_mfma_f32_16x16x32_bf16 v[90:93], v[82:85], v[170:173], v[90:93]
	v_mfma_f32_16x16x32_bf16 v[142:145], v[74:77], v[150:153], v[142:145]
	v_mfma_f32_16x16x32_bf16 v[138:141], v[86:89], v[150:153], v[138:141]
	v_mfma_f32_16x16x32_bf16 v[126:129], v[74:77], v[158:161], v[126:129]
	v_mfma_f32_16x16x32_bf16 v[122:125], v[86:89], v[158:161], v[122:125]
	v_mfma_f32_16x16x32_bf16 v[110:113], v[74:77], v[166:169], v[110:113]
	v_mfma_f32_16x16x32_bf16 v[106:109], v[86:89], v[166:169], v[106:109]
	v_mfma_f32_16x16x32_bf16 v[94:97], v[74:77], v[184:187], v[94:97]
	v_mfma_f32_16x16x32_bf16 v[90:93], v[86:89], v[184:187], v[90:93]
	s_barrier
	s_add_i32 s24, 0, 0x1c000
	s_add_i32 s22, s65, s52
	s_mov_b32 m0, s22
	ds_read_b128 v[194:197], v250 offset:49152
	ds_read_b128 v[198:201], v250 offset:50176
	ds_read_b128 v[202:205], v250 offset:51200
	ds_read_b128 v[212:215], v250 offset:52224
	global_load_lds_dwordx4 v0, s[100:101]
	s_add_i32 m0, s22, 0x2000
	s_nop 0
	global_load_lds_dwordx4 v174, s[100:101]
	s_barrier
	s_waitcnt lgkmcnt(0)
	v_mfma_f32_16x16x32_bf16 v[134:137], v[194:197], v[146:149], v[134:137]
	v_mfma_f32_16x16x32_bf16 v[130:133], v[202:205], v[146:149], v[130:133]
	v_mfma_f32_16x16x32_bf16 v[118:121], v[194:197], v[154:157], v[118:121]
	v_mfma_f32_16x16x32_bf16 v[114:117], v[202:205], v[154:157], v[114:117]
	v_mfma_f32_16x16x32_bf16 v[102:105], v[194:197], v[162:165], v[102:105]
	v_mfma_f32_16x16x32_bf16 v[98:101], v[202:205], v[162:165], v[98:101]
	v_mfma_f32_16x16x32_bf16 v[78:81], v[194:197], v[170:173], v[78:81]
	v_mfma_f32_16x16x32_bf16 v[66:69], v[202:205], v[170:173], v[66:69]
	v_mfma_f32_16x16x32_bf16 v[134:137], v[198:201], v[150:153], v[134:137]
	v_mfma_f32_16x16x32_bf16 v[130:133], v[212:215], v[150:153], v[130:133]
	v_mfma_f32_16x16x32_bf16 v[118:121], v[198:201], v[158:161], v[118:121]
	v_mfma_f32_16x16x32_bf16 v[114:117], v[212:215], v[158:161], v[114:117]
	v_mfma_f32_16x16x32_bf16 v[102:105], v[198:201], v[166:169], v[102:105]
	v_mfma_f32_16x16x32_bf16 v[98:101], v[212:215], v[166:169], v[98:101]
	v_mfma_f32_16x16x32_bf16 v[78:81], v[198:201], v[184:187], v[78:81]
	v_mfma_f32_16x16x32_bf16 v[66:69], v[212:215], v[184:187], v[66:69]
	s_barrier
	s_mov_b32 m0, s58
	ds_read_b128 v[146:149], v211 offset:49152
	ds_read_b128 v[150:153], v211 offset:50176
	ds_read_b128 v[154:157], v211 offset:51200
	ds_read_b128 v[158:161], v211 offset:52224
	ds_read_b128 v[162:165], v211 offset:53248
	ds_read_b128 v[166:169], v211 offset:54272
	ds_read_b128 v[170:173], v211 offset:55296
	ds_read_b128 v[184:187], v211 offset:56320
	global_load_lds_dwordx4 v188, vcc
	s_mov_b32 m0, s59
	s_nop 0
	global_load_lds_dwordx4 v176, vcc
	s_barrier
; __device__ __forceinline__ unsigned cvt_pk_bf16(float lo, float hi) { unsigned r; asm volatile("v_cvt_pk_bf16_f32 %0, %1, %2" : "=v"(r) : "v"(lo), "v"(hi)); return r; }
; #define PG8_STAGE(bufoff, gbase, voff) do { _Pragma("unroll") for (int _i = 0; _i < 2; ++_i) \
;         __builtin_amdgcn_global_load_lds((const unsigned*)((const char*)(gbase) + (voff)[_i]), (LAS unsigned*)(lds + (bufoff) + ldsw + _i * 8192), 16, 0, 0); } while (0)
; #define PG8_WAIT_V(n) asm volatile("s_waitcnt vmcnt(" #n ")" ::: "memory")
; #define PG8_WAIT_L(n) asm volatile("s_waitcnt lgkmcnt(" #n ")" ::: "memory")
; #define PG8_BAR __builtin_amdgcn_s_barrier()
; template <class Epi>
; __device__ __forceinline__ void gemm_phase(LAS unsigned char* lds, const Gemm g, const StaticOrder& S, const Epi& E) {
;     ...
;             PG8_BAR; PG8_WAIT_L(0); PG8_MMA(1, 0, At, B0); PG8_BAR; PG8_SCHED;
;             PG8_STAGE(PG8_SB(1, 1), b3 + hstepB, voffB);
;             PG8_WAIT_V(6); PG8_BAR; PG8_MMA(1, 1, At, B1); PG8_BAR;
;     __device__ __forceinline__ void operator()(const f32x4 (&acc)[2][2][4][2], const Unit& u, int wr, int wc, int fr, int fq, const Pre&) const {
;     ...
;             for (int n = 0; n < 2; ++n) xb[0][bj][n] = *(const f32x4*)(Xin + (size_t)row0 * DM + col0 + bj * HALF + n * 16);
; #pragma unroll
;         for (int grp = 0; grp < 8; ++grp) { const int ai = grp >> 2, m = grp & 3, cur = grp & 1; const int r = row0 + ai * HALF + m * 16; float ss = 0.f;
;             if (grp < 7) { const int rn = row0 + ((grp + 1) >> 2) * HALF + ((grp + 1) & 3) * 16;
; #pragma unroll
;                 for (int bj = 0; bj < 2; ++bj)
; #pragma unroll
;                     for (int n = 0; n < 2; ++n) xb[cur ^ 1][bj][n] = *(const f32x4*)(Xin + (size_t)rn * DM + col0 + bj * HALF + n * 16); }
; #pragma unroll
;             for (int bj = 0; bj < 2; ++bj)
; #pragma unroll
;                 for (int n = 0; n < 2; ++n) { const int c = col0 + bj * HALF + n * 16;
;                     const f32x4 xv = xb[cur][bj][n] + acc[ai][bj][m][n]; *(f32x4*)(X + (size_t)r * DM + c) = xv;
;                     ss += (xv[0] * xv[0] + xv[1] * xv[1]) + (xv[2] * xv[2] + xv[3] * xv[3]);
;                     if (H) { const f32x4 hv = xv * gv[bj][n]; u32x2 w; w.x = cvt_pk_bf16(hv[0], hv[1]); w.y = cvt_pk_bf16(hv[2], hv[3]);
;                         *(u32x2*)(H + (size_t)r * DM + c) = w; } }
	s_waitcnt lgkmcnt(0)
	v_mfma_f32_16x16x32_bf16 v[62:65], v[70:73], v[146:149], v[62:65]
	v_mfma_f32_16x16x32_bf16 v[58:61], v[82:85], v[146:149], v[58:61]
	v_mfma_f32_16x16x32_bf16 v[46:49], v[70:73], v[154:157], v[46:49]
	v_mfma_f32_16x16x32_bf16 v[42:45], v[82:85], v[154:157], v[42:45]
	v_mfma_f32_16x16x32_bf16 v[30:33], v[70:73], v[162:165], v[30:33]
	v_mfma_f32_16x16x32_bf16 v[26:29], v[82:85], v[162:165], v[26:29]
	v_mfma_f32_16x16x32_bf16 v[14:17], v[70:73], v[170:173], v[14:17]
	v_mfma_f32_16x16x32_bf16 v[10:13], v[82:85], v[170:173], v[10:13]
	v_mfma_f32_16x16x32_bf16 v[62:65], v[74:77], v[150:153], v[62:65]
	v_mfma_f32_16x16x32_bf16 v[58:61], v[86:89], v[150:153], v[58:61]
	v_mfma_f32_16x16x32_bf16 v[46:49], v[74:77], v[158:161], v[46:49]
	v_mfma_f32_16x16x32_bf16 v[42:45], v[86:89], v[158:161], v[42:45]
	v_mfma_f32_16x16x32_bf16 v[30:33], v[74:77], v[166:169], v[30:33]
	v_mfma_f32_16x16x32_bf16 v[26:29], v[86:89], v[166:169], v[26:29]
	v_mfma_f32_16x16x32_bf16 v[14:17], v[74:77], v[184:187], v[14:17]
	v_mfma_f32_16x16x32_bf16 v[10:13], v[86:89], v[184:187], v[10:13]
	s_barrier
	s_add_u32 s22, s36, 0x100080
	s_addc_u32 s23, s37, 0
	s_add_i32 s24, s24, s52
	s_mov_b32 m0, s24
	s_nop 0
	global_load_lds_dwordx4 v0, s[22:23]
	s_add_i32 m0, s24, 0x2000
	s_nop 0
	global_load_lds_dwordx4 v174, s[22:23]
	s_waitcnt vmcnt(6)
	s_barrier
	v_mfma_f32_16x16x32_bf16 v[54:57], v[194:197], v[146:149], v[54:57]
	v_mfma_f32_16x16x32_bf16 v[50:53], v[202:205], v[146:149], v[50:53]
	v_mfma_f32_16x16x32_bf16 v[38:41], v[194:197], v[154:157], v[38:41]
	v_mfma_f32_16x16x32_bf16 v[34:37], v[202:205], v[154:157], v[34:37]
	v_mfma_f32_16x16x32_bf16 v[22:25], v[194:197], v[162:165], v[22:25]
	v_mfma_f32_16x16x32_bf16 v[18:21], v[202:205], v[162:165], v[18:21]
	v_mfma_f32_16x16x32_bf16 v[6:9], v[194:197], v[170:173], v[6:9]
	v_mfma_f32_16x16x32_bf16 v[2:5], v[202:205], v[170:173], v[2:5]
	v_mfma_f32_16x16x32_bf16 v[54:57], v[198:201], v[150:153], v[54:57]
	v_mfma_f32_16x16x32_bf16 v[50:53], v[212:215], v[150:153], v[50:53]
	v_mfma_f32_16x16x32_bf16 v[38:41], v[198:201], v[158:161], v[38:41]
	v_mfma_f32_16x16x32_bf16 v[34:37], v[212:215], v[158:161], v[34:37]
	v_mfma_f32_16x16x32_bf16 v[22:25], v[198:201], v[166:169], v[22:25]
	v_mfma_f32_16x16x32_bf16 v[18:21], v[212:215], v[166:169], v[18:21]
	v_mfma_f32_16x16x32_bf16 v[6:9], v[198:201], v[184:187], v[6:9]
	v_mfma_f32_16x16x32_bf16 v[2:5], v[212:215], v[184:187], v[2:5]
	s_barrier
	s_add_i32 s64, s64, 2
	s_add_u32 s62, s62, 0x100
	s_addc_u32 s63, s63, 0
	s_cmp_gt_u32 s64, 61
	s_mov_b64 s[22:23], s[26:27]
	s_cbranch_scc0 .LBB0_359
	v_lshl_add_u32 v198, s44, 8, v208
	v_lshl_or_b32 v194, s45, 8, v210
	v_ashrrev_i32_e32 v199, 31, v198
	v_ashrrev_i32_e32 v195, 31, v194
	v_lshlrev_b64 v[204:205], 13, v[198:199]
	v_or_b32_e32 v202, 16, v198
	v_lshlrev_b64 v[196:197], 2, v[194:195]
	v_lshl_add_u64 v[146:147], s[0:1], 0, v[204:205]
	v_ashrrev_i32_e32 v203, 31, v202
	v_lshl_add_u64 v[70:71], s[4:5], 0, v[196:197]
	v_lshl_add_u64 v[146:147], v[146:147], 0, v[196:197]
	v_lshlrev_b64 v[200:201], 13, v[202:203]
	global_load_dwordx4 v[86:89], v[70:71], off
	global_load_dwordx4 v[82:85], v[70:71], off offset:64
	global_load_dwordx4 v[74:77], v[70:71], off offset:512
	s_nop 0
	global_load_dwordx4 v[70:73], v[70:71], off offset:576
	s_nop 0
	global_load_dwordx4 v[184:187], v[146:147], off
	global_load_dwordx4 v[170:173], v[146:147], off offset:64
	global_load_dwordx4 v[166:169], v[146:147], off offset:512
	global_load_dwordx4 v[162:165], v[146:147], off offset:576
	v_lshl_add_u64 v[146:147], s[0:1], 0, v[200:201]
	v_lshl_add_u64 v[146:147], v[146:147], 0, v[196:197]
	global_load_dwordx4 v[158:161], v[146:147], off
	global_load_dwordx4 v[154:157], v[146:147], off offset:64
	global_load_dwordx4 v[150:153], v[146:147], off offset:512
	s_nop 0
	global_load_dwordx4 v[146:149], v[146:147], off offset:576
	v_cndmask_b32_e64 v206, 0, 1, s[10:11]
	v_lshlrev_b64 v[212:213], 11, v[198:199]
	v_lshl_add_u64 v[204:205], s[48:49], 0, v[204:205]
	v_cmp_ne_u32_e64 s[44:45], 1, v206
	s_andn2_b64 vcc, exec, s[10:11]
	v_lshl_add_u64 v[206:207], v[204:205], 0, v[196:197]
	v_lshl_add_u64 v[204:205], v[212:213], 1, s[50:51]
	s_waitcnt vmcnt(0)
	v_pk_add_f32 v[144:145], v[144:145], v[186:187]
	v_pk_add_f32 v[142:143], v[142:143], v[184:185]
	global_store_dwordx4 v[206:207], v[142:145], off
	s_cbranch_vccnz .LBB0_362
	v_pk_mul_f32 v[184:185], v[88:89], v[144:145]
	v_pk_mul_f32 v[186:187], v[86:87], v[142:143]
	s_nop 0
	v_cvt_pk_bf16_f32 v186, v186, v187
	v_cvt_pk_bf16_f32 v187, v184, v185
	v_lshl_add_u64 v[184:185], v[194:195], 1, v[204:205]
	global_store_dwordx2 v[184:185], v[186:187], off

; #define PG8_STAGE(bufoff, gbase, voff) do { _Pragma("unroll") for (int _i = 0; _i < 2; ++_i) \
;         __builtin_amdgcn_global_load_lds((const unsigned*)((const char*)(gbase) + (voff)[_i]), (LAS unsigned*)(lds + (bufoff) + ldsw + _i * 8192), 16, 0, 0); } while (0)
; #define PG8_LDA(dst, b, h) do { _Pragma("unroll") for (int m = 0; m < 4; ++m) _Pragma("unroll") for (int k = 0; k < 2; ++k) dst[m][k] = *(const LAS bf16x8*)(lds + PG8_SA(b, h) + aoff + m * 2048 + k * 1024); } while (0)
; #define PG8_LDB(dst, b, h) do { _Pragma("unroll") for (int n = 0; n < 2; ++n) _Pragma("unroll") for (int k = 0; k < 2; ++k) dst[n][k] = *(const LAS bf16x8*)(lds + PG8_SB(b, h) + boff + n * 2048 + k * 1024); } while (0)
; #define PG8_MMA(ai, bj, At, Bt) do { __builtin_amdgcn_s_setprio(1); _Pragma("unroll") for (int m = 0; m < 4; ++m) _Pragma("unroll") for (int n = 0; n < 2; ++n) _Pragma("unroll") for (int k = 0; k < 2; ++k) \
;         acc[ai][bj][m][n] = __builtin_amdgcn_mfma_f32_16x16x32_bf16(Bt[n][k], At[m][k], acc[ai][bj][m][n], 0, 0, 0); __builtin_amdgcn_s_setprio(0); } while (0)
; #define PG8_WAIT_V(n) asm volatile("s_waitcnt vmcnt(" #n ")" ::: "memory")
; #define PG8_WAIT_L(n) asm volatile("s_waitcnt lgkmcnt(" #n ")" ::: "memory")
; #define PG8_BAR __builtin_amdgcn_s_barrier()
; #define PG8_SCHED __builtin_amdgcn_sched_barrier(0)
; template <class Epi>
; __device__ __forceinline__ void gemm_phase(LAS unsigned char* lds, const Gemm g, const StaticOrder& S, const Epi& E) {
;     ...
;             PG8_LDB(B0, 0, 0); PG8_SCHED; PG8_LDA(At, 0, 0); PG8_STAGE(PG8_SA(1, 1), a1 + hstepA, voffA);
;             PG8_WAIT_L(8); PG8_BAR; PG8_WAIT_L(0); PG8_MMA(0, 0, At, B0); PG8_BAR; PG8_SCHED;
;             PG8_LDB(B1, 0, 1); PG8_STAGE(PG8_SB(0, 0), b2, voffB);
;             PG8_BAR; PG8_WAIT_L(0); PG8_MMA(0, 1, At, B1); PG8_BAR;
;             PG8_LDA(At, 0, 1); PG8_STAGE(PG8_SA(0, 0), a2, voffA);
;             PG8_BAR; PG8_WAIT_L(0); PG8_MMA(1, 0, At, B0); PG8_BAR; PG8_SCHED;
;             PG8_STAGE(PG8_SB(0, 1), b2 + hstepB, voffB);
;             PG8_WAIT_V(6); PG8_BAR; PG8_MMA(1, 1, At, B1); PG8_BAR;
.LBB0_472:
	s_add_u32 s22, s4, s20
	s_addc_u32 s23, s5, s21
	s_add_u32 s22, s22, 0x100
	s_addc_u32 s23, s23, 0
	s_add_u32 s62, s17, s20
	s_addc_u32 s63, s58, s21
	s_add_i32 s64, 0, 0x10000
	ds_read_b128 v[148:151], v250
	ds_read_b128 v[152:155], v250 offset:1024
	ds_read_b128 v[156:159], v250 offset:2048
	ds_read_b128 v[160:163], v250 offset:3072
	s_cmpk_eq_i32 s20, 0x1f00
	s_cselect_b32 s25, s11, s23
	s_cselect_b32 s24, s59, s22
	s_cselect_b32 s23, s9, s63
	s_cselect_b32 s22, s60, s62
	v_lshl_add_u64 v[176:177], v[140:141], 0, s[20:21]
	s_add_i32 m0, s48, 0xc000
	ds_read_b128 v[164:167], v147
	ds_read_b128 v[168:171], v147 offset:1024
	ds_read_b128 v[172:175], v147 offset:2048
	ds_read_b128 v[184:187], v147 offset:3072
	ds_read_b128 v[188:191], v147 offset:4096
	ds_read_b128 v[192:195], v147 offset:5120
	ds_read_b128 v[196:199], v147 offset:6144
	ds_read_b128 v[200:203], v147 offset:7168
	global_load_lds_dwordx4 v[176:177], off
	v_lshl_add_u64 v[176:177], v[142:143], 0, s[20:21]
	s_add_i32 m0, s48, 0xe000
	s_nop 0
	global_load_lds_dwordx4 v[176:177], off
	s_waitcnt lgkmcnt(8)
	s_barrier
	s_waitcnt lgkmcnt(0)
	v_mfma_f32_16x16x32_bf16 v[126:129], v[148:151], v[164:167], v[126:129]
	v_mfma_f32_16x16x32_bf16 v[122:125], v[156:159], v[164:167], v[122:125]
	v_mfma_f32_16x16x32_bf16 v[110:113], v[148:151], v[172:175], v[110:113]
	v_mfma_f32_16x16x32_bf16 v[106:109], v[156:159], v[172:175], v[106:109]
	v_mfma_f32_16x16x32_bf16 v[94:97], v[148:151], v[188:191], v[94:97]
	v_mfma_f32_16x16x32_bf16 v[90:93], v[156:159], v[188:191], v[90:93]
	v_mfma_f32_16x16x32_bf16 v[78:81], v[148:151], v[196:199], v[78:81]
	v_mfma_f32_16x16x32_bf16 v[74:77], v[156:159], v[196:199], v[74:77]
	v_mfma_f32_16x16x32_bf16 v[126:129], v[152:155], v[168:171], v[126:129]
	v_mfma_f32_16x16x32_bf16 v[122:125], v[160:163], v[168:171], v[122:125]
	v_mfma_f32_16x16x32_bf16 v[110:113], v[152:155], v[184:187], v[110:113]
	v_mfma_f32_16x16x32_bf16 v[106:109], v[160:163], v[184:187], v[106:109]
	v_mfma_f32_16x16x32_bf16 v[94:97], v[152:155], v[192:195], v[94:97]
	v_mfma_f32_16x16x32_bf16 v[90:93], v[160:163], v[192:195], v[90:93]
	v_mfma_f32_16x16x32_bf16 v[78:81], v[152:155], v[200:203], v[78:81]
	v_mfma_f32_16x16x32_bf16 v[74:77], v[160:163], v[200:203], v[74:77]
	s_barrier
	s_add_i32 s65, 0, 0x14000
	s_add_i32 s62, s64, s39
	ds_read_b128 v[204:207], v250 offset:16384
	ds_read_b128 v[208:211], v250 offset:17408
	ds_read_b128 v[212:215], v250 offset:18432
	ds_read_b128 v[216:219], v250 offset:19456
	s_add_u32 s100, s22, s6
	s_addc_u32 s101, s23, s7
	s_mov_b32 m0, s62
	s_nop 0
	global_load_lds_dwordx4 v0, s[22:23]
	s_add_i32 m0, s62, 0x2000
	s_nop 0
	global_load_lds_dwordx4 v130, s[22:23]
	s_barrier
	s_waitcnt lgkmcnt(0)
	v_mfma_f32_16x16x32_bf16 v[118:121], v[204:207], v[164:167], v[118:121]
	v_mfma_f32_16x16x32_bf16 v[114:117], v[212:215], v[164:167], v[114:117]
	v_mfma_f32_16x16x32_bf16 v[102:105], v[204:207], v[172:175], v[102:105]
	v_mfma_f32_16x16x32_bf16 v[98:101], v[212:215], v[172:175], v[98:101]
	v_mfma_f32_16x16x32_bf16 v[86:89], v[204:207], v[188:191], v[86:89]
	v_mfma_f32_16x16x32_bf16 v[82:85], v[212:215], v[188:191], v[82:85]
	v_mfma_f32_16x16x32_bf16 v[70:73], v[204:207], v[196:199], v[70:73]
	v_mfma_f32_16x16x32_bf16 v[66:69], v[212:215], v[196:199], v[66:69]
	v_mfma_f32_16x16x32_bf16 v[118:121], v[208:211], v[168:171], v[118:121]
	v_mfma_f32_16x16x32_bf16 v[114:117], v[216:219], v[168:171], v[114:117]
	v_mfma_f32_16x16x32_bf16 v[102:105], v[208:211], v[184:187], v[102:105]
	v_mfma_f32_16x16x32_bf16 v[98:101], v[216:219], v[184:187], v[98:101]
	v_mfma_f32_16x16x32_bf16 v[86:89], v[208:211], v[192:195], v[86:89]
	v_mfma_f32_16x16x32_bf16 v[82:85], v[216:219], v[192:195], v[82:85]
	v_mfma_f32_16x16x32_bf16 v[70:73], v[208:211], v[200:203], v[70:73]
	v_mfma_f32_16x16x32_bf16 v[66:69], v[216:219], v[200:203], v[66:69]
	s_barrier
	s_mov_b32 m0, s48
	s_add_u32 vcc_lo, s24, s6
	s_addc_u32 vcc_hi, s25, s7
	ds_read_b128 v[164:167], v147 offset:16384
	ds_read_b128 v[168:171], v147 offset:17408
	ds_read_b128 v[172:175], v147 offset:18432
	ds_read_b128 v[184:187], v147 offset:19456
	ds_read_b128 v[188:191], v147 offset:20480
	ds_read_b128 v[192:195], v147 offset:21504
	ds_read_b128 v[196:199], v147 offset:22528
	ds_read_b128 v[200:203], v147 offset:23552
	global_load_lds_dwordx4 v134, s[24:25]
	s_mov_b32 m0, s49
	s_nop 0
	global_load_lds_dwordx4 v132, s[24:25]
	s_barrier
	s_waitcnt lgkmcnt(0)
	v_mfma_f32_16x16x32_bf16 v[62:65], v[148:151], v[164:167], v[62:65]
	v_mfma_f32_16x16x32_bf16 v[58:61], v[156:159], v[164:167], v[58:61]
	v_mfma_f32_16x16x32_bf16 v[46:49], v[148:151], v[172:175], v[46:49]
	v_mfma_f32_16x16x32_bf16 v[42:45], v[156:159], v[172:175], v[42:45]
	v_mfma_f32_16x16x32_bf16 v[30:33], v[148:151], v[188:191], v[30:33]
	v_mfma_f32_16x16x32_bf16 v[26:29], v[156:159], v[188:191], v[26:29]
	v_mfma_f32_16x16x32_bf16 v[18:21], v[148:151], v[196:199], v[18:21]
	v_mfma_f32_16x16x32_bf16 v[10:13], v[156:159], v[196:199], v[10:13]
	v_mfma_f32_16x16x32_bf16 v[62:65], v[152:155], v[168:171], v[62:65]
	v_mfma_f32_16x16x32_bf16 v[58:61], v[160:163], v[168:171], v[58:61]
	v_mfma_f32_16x16x32_bf16 v[46:49], v[152:155], v[184:187], v[46:49]
	v_mfma_f32_16x16x32_bf16 v[42:45], v[160:163], v[184:187], v[42:45]
	v_mfma_f32_16x16x32_bf16 v[30:33], v[152:155], v[192:195], v[30:33]
	v_mfma_f32_16x16x32_bf16 v[26:29], v[160:163], v[192:195], v[26:29]
	v_mfma_f32_16x16x32_bf16 v[18:21], v[152:155], v[200:203], v[18:21]
	v_mfma_f32_16x16x32_bf16 v[10:13], v[160:163], v[200:203], v[10:13]
	s_barrier
; #define PG8_STAGE(bufoff, gbase, voff) do { _Pragma("unroll") for (int _i = 0; _i < 2; ++_i) \
;         __builtin_amdgcn_global_load_lds((const unsigned*)((const char*)(gbase) + (voff)[_i]), (LAS unsigned*)(lds + (bufoff) + ldsw + _i * 8192), 16, 0, 0); } while (0)
; #define PG8_LDA(dst, b, h) do { _Pragma("unroll") for (int m = 0; m < 4; ++m) _Pragma("unroll") for (int k = 0; k < 2; ++k) dst[m][k] = *(const LAS bf16x8*)(lds + PG8_SA(b, h) + aoff + m * 2048 + k * 1024); } while (0)
; #define PG8_LDB(dst, b, h) do { _Pragma("unroll") for (int n = 0; n < 2; ++n) _Pragma("unroll") for (int k = 0; k < 2; ++k) dst[n][k] = *(const LAS bf16x8*)(lds + PG8_SB(b, h) + boff + n * 2048 + k * 1024); } while (0)
; #define PG8_MMA(ai, bj, At, Bt) do { __builtin_amdgcn_s_setprio(1); _Pragma("unroll") for (int m = 0; m < 4; ++m) _Pragma("unroll") for (int n = 0; n < 2; ++n) _Pragma("unroll") for (int k = 0; k < 2; ++k) \
;         acc[ai][bj][m][n] = __builtin_amdgcn_mfma_f32_16x16x32_bf16(Bt[n][k], At[m][k], acc[ai][bj][m][n], 0, 0, 0); __builtin_amdgcn_s_setprio(0); } while (0)
; #define PG8_WAIT_V(n) asm volatile("s_waitcnt vmcnt(" #n ")" ::: "memory")
; #define PG8_WAIT_L(n) asm volatile("s_waitcnt lgkmcnt(" #n ")" ::: "memory")
; #define PG8_BAR __builtin_amdgcn_s_barrier()
; #define PG8_SCHED __builtin_amdgcn_sched_barrier(0)
; template <class Epi>
; __device__ __forceinline__ void gemm_phase(LAS unsigned char* lds, const Gemm g, const StaticOrder& S, const Epi& E) {
;     ...
;             PG8_WAIT_V(6); PG8_BAR; PG8_MMA(1, 1, At, B1); PG8_BAR;
;             PG8_LDB(B0, 1, 0); PG8_SCHED; PG8_LDA(At, 1, 0); PG8_STAGE(PG8_SA(0, 1), a2 + hstepA, voffA);
;             PG8_WAIT_L(8); PG8_BAR; PG8_WAIT_L(0); PG8_MMA(0, 0, At, B0); PG8_BAR; PG8_SCHED;
;             PG8_LDB(B1, 1, 1); PG8_STAGE(PG8_SB(1, 0), b3, voffB);
;             PG8_BAR; PG8_WAIT_L(0); PG8_MMA(0, 1, At, B1); PG8_BAR;
;             PG8_LDA(At, 1, 1); PG8_STAGE(PG8_SA(1, 0), a3, voffA);
;             PG8_BAR; PG8_WAIT_L(0); PG8_MMA(1, 0, At, B0); PG8_BAR; PG8_SCHED;
	s_add_u32 s62, s22, 0x100000
	s_addc_u32 s63, s23, 0
	s_add_i32 s64, s65, s39
	s_mov_b32 m0, s64
	s_nop 0
	global_load_lds_dwordx4 v0, s[62:63]
	s_add_i32 m0, s64, 0x2000
	s_nop 0
	global_load_lds_dwordx4 v130, s[62:63]
	s_waitcnt vmcnt(6)
	s_barrier
	v_mfma_f32_16x16x32_bf16 v[54:57], v[204:207], v[164:167], v[54:57]
	v_mfma_f32_16x16x32_bf16 v[50:53], v[212:215], v[164:167], v[50:53]
	v_mfma_f32_16x16x32_bf16 v[38:41], v[204:207], v[172:175], v[38:41]
	v_mfma_f32_16x16x32_bf16 v[34:37], v[212:215], v[172:175], v[34:37]
	v_mfma_f32_16x16x32_bf16 v[22:25], v[204:207], v[188:191], v[22:25]
	v_mfma_f32_16x16x32_bf16 v[14:17], v[212:215], v[188:191], v[14:17]
	v_mfma_f32_16x16x32_bf16 v[6:9], v[204:207], v[196:199], v[6:9]
	v_mfma_f32_16x16x32_bf16 v[2:5], v[212:215], v[196:199], v[2:5]
	v_mfma_f32_16x16x32_bf16 v[54:57], v[208:211], v[168:171], v[54:57]
	v_mfma_f32_16x16x32_bf16 v[50:53], v[216:219], v[168:171], v[50:53]
	v_mfma_f32_16x16x32_bf16 v[38:41], v[208:211], v[184:187], v[38:41]
	v_mfma_f32_16x16x32_bf16 v[34:37], v[216:219], v[184:187], v[34:37]
	v_mfma_f32_16x16x32_bf16 v[22:25], v[208:211], v[192:195], v[22:25]
	v_mfma_f32_16x16x32_bf16 v[14:17], v[216:219], v[192:195], v[14:17]
	v_mfma_f32_16x16x32_bf16 v[6:9], v[208:211], v[200:203], v[6:9]
	v_mfma_f32_16x16x32_bf16 v[2:5], v[216:219], v[200:203], v[2:5]
	s_barrier
	s_add_i32 s62, 0, 0x18000
	ds_read_b128 v[148:151], v250 offset:32768
	ds_read_b128 v[152:155], v250 offset:33792
	ds_read_b128 v[156:159], v250 offset:34816
	ds_read_b128 v[160:163], v250 offset:35840
	s_add_u32 s24, s24, 0x100000
	s_addc_u32 s25, s25, 0
	s_mov_b32 m0, s50
	ds_read_b128 v[164:167], v147 offset:32768
	ds_read_b128 v[168:171], v147 offset:33792
	ds_read_b128 v[172:175], v147 offset:34816
	ds_read_b128 v[184:187], v147 offset:35840
	ds_read_b128 v[188:191], v147 offset:36864
	ds_read_b128 v[192:195], v147 offset:37888
	ds_read_b128 v[196:199], v147 offset:38912
	ds_read_b128 v[200:203], v147 offset:39936
	global_load_lds_dwordx4 v134, s[24:25]
	s_mov_b32 m0, s51
	s_nop 0
	global_load_lds_dwordx4 v132, s[24:25]
	s_waitcnt lgkmcnt(8)
	s_barrier
	s_waitcnt lgkmcnt(0)
	v_mfma_f32_16x16x32_bf16 v[126:129], v[148:151], v[164:167], v[126:129]
	v_mfma_f32_16x16x32_bf16 v[122:125], v[156:159], v[164:167], v[122:125]
	v_mfma_f32_16x16x32_bf16 v[110:113], v[148:151], v[172:175], v[110:113]
	v_mfma_f32_16x16x32_bf16 v[106:109], v[156:159], v[172:175], v[106:109]
	v_mfma_f32_16x16x32_bf16 v[94:97], v[148:151], v[188:191], v[94:97]
	v_mfma_f32_16x16x32_bf16 v[90:93], v[156:159], v[188:191], v[90:93]
	v_mfma_f32_16x16x32_bf16 v[78:81], v[148:151], v[196:199], v[78:81]
	v_mfma_f32_16x16x32_bf16 v[74:77], v[156:159], v[196:199], v[74:77]
	v_mfma_f32_16x16x32_bf16 v[126:129], v[152:155], v[168:171], v[126:129]
	v_mfma_f32_16x16x32_bf16 v[122:125], v[160:163], v[168:171], v[122:125]
	v_mfma_f32_16x16x32_bf16 v[110:113], v[152:155], v[184:187], v[110:113]
	v_mfma_f32_16x16x32_bf16 v[106:109], v[160:163], v[184:187], v[106:109]
	v_mfma_f32_16x16x32_bf16 v[94:97], v[152:155], v[192:195], v[94:97]
	v_mfma_f32_16x16x32_bf16 v[90:93], v[160:163], v[192:195], v[90:93]
	v_mfma_f32_16x16x32_bf16 v[78:81], v[152:155], v[200:203], v[78:81]
	v_mfma_f32_16x16x32_bf16 v[74:77], v[160:163], v[200:203], v[74:77]
	s_barrier
	s_add_i32 s24, 0, 0x1c000
	s_add_i32 s25, s62, s39
	s_mov_b32 m0, s25
	ds_read_b128 v[204:207], v250 offset:49152
	ds_read_b128 v[208:211], v250 offset:50176
	ds_read_b128 v[212:215], v250 offset:51200
	ds_read_b128 v[216:219], v250 offset:52224
	global_load_lds_dwordx4 v0, s[100:101]
	s_add_i32 m0, s25, 0x2000
	s_nop 0
	global_load_lds_dwordx4 v130, s[100:101]
	s_barrier
	s_waitcnt lgkmcnt(0)
	v_mfma_f32_16x16x32_bf16 v[118:121], v[204:207], v[164:167], v[118:121]
	v_mfma_f32_16x16x32_bf16 v[114:117], v[212:215], v[164:167], v[114:117]
	v_mfma_f32_16x16x32_bf16 v[102:105], v[204:207], v[172:175], v[102:105]
	v_mfma_f32_16x16x32_bf16 v[98:101], v[212:215], v[172:175], v[98:101]
	v_mfma_f32_16x16x32_bf16 v[86:89], v[204:207], v[188:191], v[86:89]
	v_mfma_f32_16x16x32_bf16 v[82:85], v[212:215], v[188:191], v[82:85]
	v_mfma_f32_16x16x32_bf16 v[70:73], v[204:207], v[196:199], v[70:73]
	v_mfma_f32_16x16x32_bf16 v[66:69], v[212:215], v[196:199], v[66:69]
	v_mfma_f32_16x16x32_bf16 v[118:121], v[208:211], v[168:171], v[118:121]
	v_mfma_f32_16x16x32_bf16 v[114:117], v[216:219], v[168:171], v[114:117]
	v_mfma_f32_16x16x32_bf16 v[102:105], v[208:211], v[184:187], v[102:105]
	v_mfma_f32_16x16x32_bf16 v[98:101], v[216:219], v[184:187], v[98:101]
	v_mfma_f32_16x16x32_bf16 v[86:89], v[208:211], v[192:195], v[86:89]
	v_mfma_f32_16x16x32_bf16 v[82:85], v[216:219], v[192:195], v[82:85]
	v_mfma_f32_16x16x32_bf16 v[70:73], v[208:211], v[200:203], v[70:73]
	v_mfma_f32_16x16x32_bf16 v[66:69], v[216:219], v[200:203], v[66:69]
	s_barrier
	s_mov_b32 m0, s54
	ds_read_b128 v[164:167], v147 offset:49152
	ds_read_b128 v[168:171], v147 offset:50176
	ds_read_b128 v[172:175], v147 offset:51200
	ds_read_b128 v[184:187], v147 offset:52224
	ds_read_b128 v[188:191], v147 offset:53248
	ds_read_b128 v[192:195], v147 offset:54272
	ds_read_b128 v[196:199], v147 offset:55296
	ds_read_b128 v[200:203], v147 offset:56320
	global_load_lds_dwordx4 v134, vcc
	s_mov_b32 m0, s55
	s_nop 0
	global_load_lds_dwordx4 v132, vcc
	s_barrier
; #define PG8_STAGE(bufoff, gbase, voff) do { _Pragma("unroll") for (int _i = 0; _i < 2; ++_i) \
;         __builtin_amdgcn_global_load_lds((const unsigned*)((const char*)(gbase) + (voff)[_i]), (LAS unsigned*)(lds + (bufoff) + ldsw + _i * 8192), 16, 0, 0); } while (0)
; #define PG8_MMA(ai, bj, At, Bt) do { __builtin_amdgcn_s_setprio(1); _Pragma("unroll") for (int m = 0; m < 4; ++m) _Pragma("unroll") for (int n = 0; n < 2; ++n) _Pragma("unroll") for (int k = 0; k < 2; ++k) \
;         acc[ai][bj][m][n] = __builtin_amdgcn_mfma_f32_16x16x32_bf16(Bt[n][k], At[m][k], acc[ai][bj][m][n], 0, 0, 0); __builtin_amdgcn_s_setprio(0); } while (0)
; #define PG8_WAIT_V(n) asm volatile("s_waitcnt vmcnt(" #n ")" ::: "memory")
; #define PG8_WAIT_L(n) asm volatile("s_waitcnt lgkmcnt(" #n ")" ::: "memory")
; #define PG8_BAR __builtin_amdgcn_s_barrier()
; #define PG8_SCHED __builtin_amdgcn_sched_barrier(0)
; template <class Epi>
; __device__ __forceinline__ void gemm_phase(LAS unsigned char* lds, const Gemm g, const StaticOrder& S, const Epi& E) {
;     ...
;             PG8_BAR; PG8_WAIT_L(0); PG8_MMA(1, 0, At, B0); PG8_BAR; PG8_SCHED;
;             PG8_STAGE(PG8_SB(1, 1), b3 + hstepB, voffB);
;             PG8_WAIT_V(6); PG8_BAR; PG8_MMA(1, 1, At, B1); PG8_BAR;
;         }
;         if constexpr (!Epi::AFTER_DRAIN) E(acc, cur, wr, wc, fr, fq, pre);
;         if (!has_next) break;
; #pragma unroll
;         for (int a = 0; a < 2; ++a)
; #pragma unroll
;             for (int b = 0; b < 2; ++b)
; #pragma unroll
;                 for (int m = 0; m < 4; ++m)
; #pragma unroll
;                     for (int n = 0; n < 2; ++n) acc[a][b][m][n] = (f32x4){0.f, 0.f, 0.f, 0.f};
	s_waitcnt lgkmcnt(0)
	v_mfma_f32_16x16x32_bf16 v[62:65], v[148:151], v[164:167], v[62:65]
	v_mfma_f32_16x16x32_bf16 v[58:61], v[156:159], v[164:167], v[58:61]
	v_mfma_f32_16x16x32_bf16 v[46:49], v[148:151], v[172:175], v[46:49]
	v_mfma_f32_16x16x32_bf16 v[42:45], v[156:159], v[172:175], v[42:45]
	v_mfma_f32_16x16x32_bf16 v[30:33], v[148:151], v[188:191], v[30:33]
	v_mfma_f32_16x16x32_bf16 v[26:29], v[156:159], v[188:191], v[26:29]
	v_mfma_f32_16x16x32_bf16 v[18:21], v[148:151], v[196:199], v[18:21]
	v_mfma_f32_16x16x32_bf16 v[10:13], v[156:159], v[196:199], v[10:13]
	v_mfma_f32_16x16x32_bf16 v[62:65], v[152:155], v[168:171], v[62:65]
	v_mfma_f32_16x16x32_bf16 v[58:61], v[160:163], v[168:171], v[58:61]
	v_mfma_f32_16x16x32_bf16 v[46:49], v[152:155], v[184:187], v[46:49]
	v_mfma_f32_16x16x32_bf16 v[42:45], v[160:163], v[184:187], v[42:45]
	v_mfma_f32_16x16x32_bf16 v[30:33], v[152:155], v[192:195], v[30:33]
	v_mfma_f32_16x16x32_bf16 v[26:29], v[160:163], v[192:195], v[26:29]
	v_mfma_f32_16x16x32_bf16 v[18:21], v[152:155], v[200:203], v[18:21]
	v_mfma_f32_16x16x32_bf16 v[10:13], v[160:163], v[200:203], v[10:13]
	s_barrier
	s_add_u32 s22, s22, 0x100080
	s_addc_u32 s23, s23, 0
	s_add_i32 s24, s24, s39
	s_mov_b32 m0, s24
	s_nop 0
	global_load_lds_dwordx4 v0, s[22:23]
	s_add_i32 m0, s24, 0x2000
	s_nop 0
	global_load_lds_dwordx4 v130, s[22:23]
	s_waitcnt vmcnt(6)
	s_barrier
	v_mfma_f32_16x16x32_bf16 v[54:57], v[204:207], v[164:167], v[54:57]
	v_mfma_f32_16x16x32_bf16 v[50:53], v[212:215], v[164:167], v[50:53]
	v_mfma_f32_16x16x32_bf16 v[38:41], v[204:207], v[172:175], v[38:41]
	v_mfma_f32_16x16x32_bf16 v[34:37], v[212:215], v[172:175], v[34:37]
	v_mfma_f32_16x16x32_bf16 v[22:25], v[204:207], v[188:191], v[22:25]
	v_mfma_f32_16x16x32_bf16 v[14:17], v[212:215], v[188:191], v[14:17]
	v_mfma_f32_16x16x32_bf16 v[6:9], v[204:207], v[196:199], v[6:9]
	v_mfma_f32_16x16x32_bf16 v[2:5], v[212:215], v[196:199], v[2:5]
	v_mfma_f32_16x16x32_bf16 v[54:57], v[208:211], v[168:171], v[54:57]
	v_mfma_f32_16x16x32_bf16 v[50:53], v[216:219], v[168:171], v[50:53]
	v_mfma_f32_16x16x32_bf16 v[38:41], v[208:211], v[184:187], v[38:41]
	v_mfma_f32_16x16x32_bf16 v[34:37], v[216:219], v[184:187], v[34:37]
	v_mfma_f32_16x16x32_bf16 v[22:25], v[208:211], v[192:195], v[22:25]
	v_mfma_f32_16x16x32_bf16 v[14:17], v[216:219], v[192:195], v[14:17]
	v_mfma_f32_16x16x32_bf16 v[6:9], v[208:211], v[200:203], v[6:9]
	v_mfma_f32_16x16x32_bf16 v[2:5], v[216:219], v[200:203], v[2:5]
	s_barrier
	s_add_i32 s61, s61, 2
	s_add_u32 s20, s20, 0x100
	s_addc_u32 s21, s21, 0
	s_cmp_gt_u32 s61, 61
	s_cbranch_scc0 .LBB0_472
	s_add_u32 s20, s17, 0xffffff00
	s_addc_u32 s21, s58, -1
	s_andn2_b64 vcc, exec, s[42:43]
	s_cbranch_vccnz .LBB0_463
	v_mov_b32_e32 v2, 0
	s_mov_b32 s57, s8
	s_mov_b32 s26, s10
	s_mov_b64 s[4:5], s[18:19]
	s_mov_b32 s56, s16
	v_mov_b32_e32 v3, v2
	v_mov_b32_e32 v4, v2
	v_mov_b32_e32 v5, v2
	v_mov_b32_e32 v6, v2
	v_mov_b32_e32 v7, v2
	v_mov_b32_e32 v8, v2
	v_mov_b32_e32 v9, v2
	v_mov_b32_e32 v14, v2
	v_mov_b32_e32 v15, v2
	v_mov_b32_e32 v16, v2
	v_mov_b32_e32 v17, v2
	v_mov_b32_e32 v22, v2
	v_mov_b32_e32 v23, v2
	v_mov_b32_e32 v24, v2
	v_mov_b32_e32 v25, v2
	v_mov_b32_e32 v34, v2
	v_mov_b32_e32 v35, v2
	v_mov_b32_e32 v36, v2
	v_mov_b32_e32 v37, v2
	v_mov_b32_e32 v38, v2
	v_mov_b32_e32 v39, v2
	v_mov_b32_e32 v40, v2
	v_mov_b32_e32 v41, v2
	v_mov_b32_e32 v50, v2
	v_mov_b32_e32 v51, v2
	v_mov_b32_e32 v52, v2
	v_mov_b32_e32 v53, v2
	v_mov_b32_e32 v54, v2
	v_mov_b32_e32 v55, v2
	v_mov_b32_e32 v56, v2
	v_mov_b32_e32 v57, v2
	v_mov_b32_e32 v10, v2
	v_mov_b32_e32 v11, v2
	v_mov_b32_e32 v12, v2
	v_mov_b32_e32 v13, v2
	v_mov_b32_e32 v18, v2
	v_mov_b32_e32 v19, v2
	v_mov_b32_e32 v20, v2
	v_mov_b32_e32 v21, v2
	v_mov_b32_e32 v26, v2
	v_mov_b32_e32 v27, v2
	v_mov_b32_e32 v28, v2
	v_mov_b32_e32 v29, v2
	v_mov_b32_e32 v30, v2
	v_mov_b32_e32 v31, v2
	v_mov_b32_e32 v32, v2
	v_mov_b32_e32 v33, v2
	v_mov_b32_e32 v42, v2
	v_mov_b32_e32 v43, v2
	v_mov_b32_e32 v44, v2
	v_mov_b32_e32 v45, v2
	v_mov_b32_e32 v46, v2
	v_mov_b32_e32 v47, v2
	v_mov_b32_e32 v48, v2
	v_mov_b32_e32 v49, v2
	v_mov_b32_e32 v58, v2
	v_mov_b32_e32 v59, v2
	v_mov_b32_e32 v60, v2
	v_mov_b32_e32 v61, v2
	v_mov_b32_e32 v62, v2
	v_mov_b32_e32 v63, v2
	v_mov_b32_e32 v64, v2
	v_mov_b32_e32 v65, v2
	v_mov_b32_e32 v66, v2
	v_mov_b32_e32 v67, v2
	v_mov_b32_e32 v68, v2
	v_mov_b32_e32 v69, v2
	v_mov_b32_e32 v70, v2
	v_mov_b32_e32 v71, v2
	v_mov_b32_e32 v72, v2
	v_mov_b32_e32 v73, v2
	v_mov_b32_e32 v82, v2
	v_mov_b32_e32 v83, v2
	v_mov_b32_e32 v84, v2
	v_mov_b32_e32 v85, v2
	v_mov_b32_e32 v86, v2
	v_mov_b32_e32 v87, v2
	v_mov_b32_e32 v88, v2
	v_mov_b32_e32 v89, v2
	v_mov_b32_e32 v98, v2
	v_mov_b32_e32 v99, v2
	v_mov_b32_e32 v100, v2
	v_mov_b32_e32 v101, v2
	v_mov_b32_e32 v102, v2
	v_mov_b32_e32 v103, v2
	v_mov_b32_e32 v104, v2
	v_mov_b32_e32 v105, v2
	v_mov_b32_e32 v114, v2
	v_mov_b32_e32 v115, v2
	v_mov_b32_e32 v116, v2
	v_mov_b32_e32 v117, v2
	v_mov_b32_e32 v118, v2
	v_mov_b32_e32 v119, v2
	v_mov_b32_e32 v120, v2
	v_mov_b32_e32 v121, v2
	v_mov_b32_e32 v74, v2
	v_mov_b32_e32 v75, v2
	v_mov_b32_e32 v76, v2
	v_mov_b32_e32 v77, v2
	v_mov_b32_e32 v78, v2
	v_mov_b32_e32 v79, v2
	v_mov_b32_e32 v80, v2
	v_mov_b32_e32 v81, v2
	v_mov_b32_e32 v90, v2
	v_mov_b32_e32 v91, v2
	v_mov_b32_e32 v92, v2
	v_mov_b32_e32 v93, v2
	v_mov_b32_e32 v94, v2
	v_mov_b32_e32 v95, v2
	v_mov_b32_e32 v96, v2
	v_mov_b32_e32 v97, v2
	v_mov_b32_e32 v106, v2
	v_mov_b32_e32 v107, v2
	v_mov_b32_e32 v108, v2
	v_mov_b32_e32 v109, v2
	v_mov_b32_e32 v110, v2
	v_mov_b32_e32 v111, v2
	v_mov_b32_e32 v112, v2
	v_mov_b32_e32 v113, v2
	v_mov_b32_e32 v122, v2
	v_mov_b32_e32 v123, v2
	v_mov_b32_e32 v124, v2
	v_mov_b32_e32 v125, v2
	v_mov_b32_e32 v126, v2
	v_mov_b32_e32 v127, v2
	v_mov_b32_e32 v128, v2
	v_mov_b32_e32 v129, v2
	s_andn2_b64 vcc, exec, s[40:41]
	s_cbranch_vccnz .LBB0_464

; #define PG8_STAGE(bufoff, gbase, voff) do { _Pragma("unroll") for (int _i = 0; _i < 2; ++_i) \
;         __builtin_amdgcn_global_load_lds((const unsigned*)((const char*)(gbase) + (voff)[_i]), (LAS unsigned*)(lds + (bufoff) + ldsw + _i * 8192), 16, 0, 0); } while (0)
; #define PG8_LDA(dst, b, h) do { _Pragma("unroll") for (int m = 0; m < 4; ++m) _Pragma("unroll") for (int k = 0; k < 2; ++k) dst[m][k] = *(const LAS bf16x8*)(lds + PG8_SA(b, h) + aoff + m * 2048 + k * 1024); } while (0)
; #define PG8_LDB(dst, b, h) do { _Pragma("unroll") for (int n = 0; n < 2; ++n) _Pragma("unroll") for (int k = 0; k < 2; ++k) dst[n][k] = *(const LAS bf16x8*)(lds + PG8_SB(b, h) + boff + n * 2048 + k * 1024); } while (0)
; #define PG8_MMA(ai, bj, At, Bt) do { __builtin_amdgcn_s_setprio(1); _Pragma("unroll") for (int m = 0; m < 4; ++m) _Pragma("unroll") for (int n = 0; n < 2; ++n) _Pragma("unroll") for (int k = 0; k < 2; ++k) \
;         acc[ai][bj][m][n] = __builtin_amdgcn_mfma_f32_16x16x32_bf16(Bt[n][k], At[m][k], acc[ai][bj][m][n], 0, 0, 0); __builtin_amdgcn_s_setprio(0); } while (0)
; #define PG8_WAIT_V(n) asm volatile("s_waitcnt vmcnt(" #n ")" ::: "memory")
; #define PG8_WAIT_L(n) asm volatile("s_waitcnt lgkmcnt(" #n ")" ::: "memory")
; #define PG8_BAR __builtin_amdgcn_s_barrier()
; #define PG8_SCHED __builtin_amdgcn_sched_barrier(0)
; template <class Epi>
; __device__ __forceinline__ void gemm_phase(LAS unsigned char* lds, const Gemm g, const StaticOrder& S, const Epi& E) {
;     ...
;             PG8_LDB(B0, 0, 0); PG8_SCHED; PG8_LDA(At, 0, 0); PG8_STAGE(PG8_SA(1, 1), a1 + hstepA, voffA);
;             PG8_WAIT_L(8); PG8_BAR; PG8_WAIT_L(0); PG8_MMA(0, 0, At, B0); PG8_BAR; PG8_SCHED;
;             PG8_LDB(B1, 0, 1); PG8_STAGE(PG8_SB(0, 0), b2, voffB);
;             PG8_BAR; PG8_WAIT_L(0); PG8_MMA(0, 1, At, B1); PG8_BAR;
;             PG8_LDA(At, 0, 1); PG8_STAGE(PG8_SA(0, 0), a2, voffA);
;             PG8_BAR; PG8_WAIT_L(0); PG8_MMA(1, 0, At, B0); PG8_BAR; PG8_SCHED;
;             PG8_STAGE(PG8_SB(0, 1), b2 + hstepB, voffB);
;             PG8_WAIT_V(6); PG8_BAR; PG8_MMA(1, 1, At, B1); PG8_BAR;
.LBB0_603:
	s_add_u32 s8, s0, 0x100
	s_addc_u32 s9, s1, 0
	s_add_i32 s60, 0, 0x10000
	ds_read_b128 v[34:37], v250
	ds_read_b128 v[38:41], v250 offset:1024
	ds_read_b128 v[98:101], v250 offset:2048
	ds_read_b128 v[102:105], v250 offset:3072
	s_cmp_eq_u32 s59, 12
	s_cselect_b32 s11, s35, s9
	s_cselect_b32 s10, s36, s8
	s_cselect_b32 s5, s37, s58
	s_cselect_b32 s4, s51, s53
	s_add_i32 m0, s20, 0xc000
	ds_read_b128 v[106:109], v231
	ds_read_b128 v[118:121], v231 offset:1024
	ds_read_b128 v[130:133], v231 offset:2048
	ds_read_b128 v[142:145], v231 offset:3072
	ds_read_b128 v[154:157], v231 offset:4096
	ds_read_b128 v[158:161], v231 offset:5120
	ds_read_b128 v[170:173], v231 offset:6144
	ds_read_b128 v[174:177], v231 offset:7168
	global_load_lds_dwordx4 v194, s[0:1]
	s_add_i32 m0, s20, 0xe000
	s_nop 0
	global_load_lds_dwordx4 v196, s[0:1]
	s_waitcnt lgkmcnt(8)
	s_barrier
	s_waitcnt lgkmcnt(0)
	v_mfma_f32_16x16x32_bf16 v[166:169], v[34:37], v[106:109], v[166:169]
	v_mfma_f32_16x16x32_bf16 v[162:165], v[98:101], v[106:109], v[162:165]
	v_mfma_f32_16x16x32_bf16 v[150:153], v[34:37], v[130:133], v[150:153]
	v_mfma_f32_16x16x32_bf16 v[146:149], v[98:101], v[130:133], v[146:149]
	v_mfma_f32_16x16x32_bf16 v[138:141], v[34:37], v[154:157], v[138:141]
	v_mfma_f32_16x16x32_bf16 v[134:137], v[98:101], v[154:157], v[134:137]
	v_mfma_f32_16x16x32_bf16 v[126:129], v[34:37], v[170:173], v[126:129]
	v_mfma_f32_16x16x32_bf16 v[122:125], v[98:101], v[170:173], v[122:125]
	v_mfma_f32_16x16x32_bf16 v[166:169], v[38:41], v[118:121], v[166:169]
	v_mfma_f32_16x16x32_bf16 v[162:165], v[102:105], v[118:121], v[162:165]
	v_mfma_f32_16x16x32_bf16 v[150:153], v[38:41], v[142:145], v[150:153]
	v_mfma_f32_16x16x32_bf16 v[146:149], v[102:105], v[142:145], v[146:149]
	v_mfma_f32_16x16x32_bf16 v[138:141], v[38:41], v[158:161], v[138:141]
	v_mfma_f32_16x16x32_bf16 v[134:137], v[102:105], v[158:161], v[134:137]
	v_mfma_f32_16x16x32_bf16 v[126:129], v[38:41], v[174:177], v[126:129]
	v_mfma_f32_16x16x32_bf16 v[122:125], v[102:105], v[174:177], v[122:125]
	s_barrier
	s_add_i32 s61, 0, 0x14000
	s_add_i32 s0, s60, s19
	ds_read_b128 v[198:201], v250 offset:16384
	ds_read_b128 v[202:205], v250 offset:17408
	ds_read_b128 v[206:209], v250 offset:18432
	ds_read_b128 v[210:213], v250 offset:19456
	s_add_u32 s100, s4, s6
	s_addc_u32 s101, s5, s7
	s_mov_b32 m0, s0
	s_nop 0
	global_load_lds_dwordx4 v0, s[4:5]
	s_add_i32 m0, s0, 0x2000
	s_nop 0
	global_load_lds_dwordx4 v188, s[4:5]
	s_barrier
	s_waitcnt lgkmcnt(0)
	v_mfma_f32_16x16x32_bf16 v[70:73], v[198:201], v[106:109], v[70:73]
	v_mfma_f32_16x16x32_bf16 v[66:69], v[206:209], v[106:109], v[66:69]
	v_mfma_f32_16x16x32_bf16 v[62:65], v[198:201], v[130:133], v[62:65]
	v_mfma_f32_16x16x32_bf16 v[58:61], v[206:209], v[130:133], v[58:61]
	v_mfma_f32_16x16x32_bf16 v[54:57], v[198:201], v[154:157], v[54:57]
	v_mfma_f32_16x16x32_bf16 v[50:53], v[206:209], v[154:157], v[50:53]
	v_mfma_f32_16x16x32_bf16 v[46:49], v[198:201], v[170:173], v[46:49]
	v_mfma_f32_16x16x32_bf16 v[42:45], v[206:209], v[170:173], v[42:45]
	v_mfma_f32_16x16x32_bf16 v[70:73], v[202:205], v[118:121], v[70:73]
	v_mfma_f32_16x16x32_bf16 v[66:69], v[210:213], v[118:121], v[66:69]
	v_mfma_f32_16x16x32_bf16 v[62:65], v[202:205], v[142:145], v[62:65]
	v_mfma_f32_16x16x32_bf16 v[58:61], v[210:213], v[142:145], v[58:61]
	v_mfma_f32_16x16x32_bf16 v[54:57], v[202:205], v[158:161], v[54:57]
	v_mfma_f32_16x16x32_bf16 v[50:53], v[210:213], v[158:161], v[50:53]
	v_mfma_f32_16x16x32_bf16 v[46:49], v[202:205], v[174:177], v[46:49]
	v_mfma_f32_16x16x32_bf16 v[42:45], v[210:213], v[174:177], v[42:45]
	s_barrier
	s_mov_b32 m0, s20
	s_add_u32 vcc_lo, s10, s6
	s_addc_u32 vcc_hi, s11, s7
	ds_read_b128 v[106:109], v231 offset:16384
	ds_read_b128 v[118:121], v231 offset:17408
	ds_read_b128 v[130:133], v231 offset:18432
	ds_read_b128 v[142:145], v231 offset:19456
	ds_read_b128 v[154:157], v231 offset:20480
	ds_read_b128 v[158:161], v231 offset:21504
	ds_read_b128 v[170:173], v231 offset:22528
	ds_read_b128 v[174:177], v231 offset:23552
	global_load_lds_dwordx4 v192, s[10:11]
	s_mov_b32 m0, s21
	s_nop 0
	global_load_lds_dwordx4 v190, s[10:11]
	s_barrier
	s_waitcnt lgkmcnt(0)
	v_mfma_f32_16x16x32_bf16 v[114:117], v[34:37], v[106:109], v[114:117]
	v_mfma_f32_16x16x32_bf16 v[110:113], v[98:101], v[106:109], v[110:113]
	v_mfma_f32_16x16x32_bf16 v[94:97], v[34:37], v[130:133], v[94:97]
	v_mfma_f32_16x16x32_bf16 v[90:93], v[98:101], v[130:133], v[90:93]
	v_mfma_f32_16x16x32_bf16 v[86:89], v[34:37], v[154:157], v[86:89]
	v_mfma_f32_16x16x32_bf16 v[82:85], v[98:101], v[154:157], v[82:85]
	v_mfma_f32_16x16x32_bf16 v[34:37], v[34:37], v[170:173], v[78:81]
	v_mfma_f32_16x16x32_bf16 v[114:117], v[38:41], v[118:121], v[114:117]
	v_mfma_f32_16x16x32_bf16 v[110:113], v[102:105], v[118:121], v[110:113]
	v_mfma_f32_16x16x32_bf16 v[94:97], v[38:41], v[142:145], v[94:97]
	v_mfma_f32_16x16x32_bf16 v[90:93], v[102:105], v[142:145], v[90:93]
	v_mfma_f32_16x16x32_bf16 v[86:89], v[38:41], v[158:161], v[86:89]
	v_mfma_f32_16x16x32_bf16 v[82:85], v[102:105], v[158:161], v[82:85]
	v_mfma_f32_16x16x32_bf16 v[34:37], v[38:41], v[174:177], v[34:37]
	v_mfma_f32_16x16x32_bf16 v[38:41], v[98:101], v[170:173], v[74:77]
	v_mfma_f32_16x16x32_bf16 v[38:41], v[102:105], v[174:177], v[38:41]
	s_barrier
	s_add_u32 s0, s4, 0x40000
	s_addc_u32 s1, s5, 0
	s_add_i32 s60, s61, s19
	s_mov_b32 m0, s60
	s_nop 0
	global_load_lds_dwordx4 v0, s[0:1]
	s_add_i32 m0, s60, 0x2000
	s_nop 0
	global_load_lds_dwordx4 v188, s[0:1]
	s_waitcnt vmcnt(6)
	s_barrier
; #define PG8_STAGE(bufoff, gbase, voff) do { _Pragma("unroll") for (int _i = 0; _i < 2; ++_i) \
;         __builtin_amdgcn_global_load_lds((const unsigned*)((const char*)(gbase) + (voff)[_i]), (LAS unsigned*)(lds + (bufoff) + ldsw + _i * 8192), 16, 0, 0); } while (0)
; #define PG8_LDA(dst, b, h) do { _Pragma("unroll") for (int m = 0; m < 4; ++m) _Pragma("unroll") for (int k = 0; k < 2; ++k) dst[m][k] = *(const LAS bf16x8*)(lds + PG8_SA(b, h) + aoff + m * 2048 + k * 1024); } while (0)
; #define PG8_LDB(dst, b, h) do { _Pragma("unroll") for (int n = 0; n < 2; ++n) _Pragma("unroll") for (int k = 0; k < 2; ++k) dst[n][k] = *(const LAS bf16x8*)(lds + PG8_SB(b, h) + boff + n * 2048 + k * 1024); } while (0)
; #define PG8_MMA(ai, bj, At, Bt) do { __builtin_amdgcn_s_setprio(1); _Pragma("unroll") for (int m = 0; m < 4; ++m) _Pragma("unroll") for (int n = 0; n < 2; ++n) _Pragma("unroll") for (int k = 0; k < 2; ++k) \
;         acc[ai][bj][m][n] = __builtin_amdgcn_mfma_f32_16x16x32_bf16(Bt[n][k], At[m][k], acc[ai][bj][m][n], 0, 0, 0); __builtin_amdgcn_s_setprio(0); } while (0)
; #define PG8_WAIT_V(n) asm volatile("s_waitcnt vmcnt(" #n ")" ::: "memory")
; #define PG8_WAIT_L(n) asm volatile("s_waitcnt lgkmcnt(" #n ")" ::: "memory")
; #define PG8_BAR __builtin_amdgcn_s_barrier()
; #define PG8_SCHED __builtin_amdgcn_sched_barrier(0)
; template <class Epi>
; __device__ __forceinline__ void gemm_phase(LAS unsigned char* lds, const Gemm g, const StaticOrder& S, const Epi& E) {
;     ...
;             PG8_WAIT_V(6); PG8_BAR; PG8_MMA(1, 1, At, B1); PG8_BAR;
;             PG8_LDB(B0, 1, 0); PG8_SCHED; PG8_LDA(At, 1, 0); PG8_STAGE(PG8_SA(0, 1), a2 + hstepA, voffA);
;             PG8_WAIT_L(8); PG8_BAR; PG8_WAIT_L(0); PG8_MMA(0, 0, At, B0); PG8_BAR; PG8_SCHED;
;             PG8_LDB(B1, 1, 1); PG8_STAGE(PG8_SB(1, 0), b3, voffB);
;             PG8_BAR; PG8_WAIT_L(0); PG8_MMA(0, 1, At, B1); PG8_BAR;
;             PG8_LDA(At, 1, 1); PG8_STAGE(PG8_SA(1, 0), a3, voffA);
;             PG8_BAR; PG8_WAIT_L(0); PG8_MMA(1, 0, At, B0); PG8_BAR; PG8_SCHED;
	v_mfma_f32_16x16x32_bf16 v[30:33], v[198:201], v[106:109], v[30:33]
	v_mfma_f32_16x16x32_bf16 v[26:29], v[206:209], v[106:109], v[26:29]
	v_mfma_f32_16x16x32_bf16 v[22:25], v[198:201], v[130:133], v[22:25]
	v_mfma_f32_16x16x32_bf16 v[18:21], v[206:209], v[130:133], v[18:21]
	v_mfma_f32_16x16x32_bf16 v[14:17], v[198:201], v[154:157], v[14:17]
	v_mfma_f32_16x16x32_bf16 v[10:13], v[206:209], v[154:157], v[10:13]
	v_mfma_f32_16x16x32_bf16 v[6:9], v[198:201], v[170:173], v[6:9]
	v_mfma_f32_16x16x32_bf16 v[2:5], v[206:209], v[170:173], v[2:5]
	v_mfma_f32_16x16x32_bf16 v[30:33], v[202:205], v[118:121], v[30:33]
	v_mfma_f32_16x16x32_bf16 v[26:29], v[210:213], v[118:121], v[26:29]
	v_mfma_f32_16x16x32_bf16 v[22:25], v[202:205], v[142:145], v[22:25]
	v_mfma_f32_16x16x32_bf16 v[18:21], v[210:213], v[142:145], v[18:21]
	v_mfma_f32_16x16x32_bf16 v[14:17], v[202:205], v[158:161], v[14:17]
	v_mfma_f32_16x16x32_bf16 v[10:13], v[210:213], v[158:161], v[10:13]
	v_mfma_f32_16x16x32_bf16 v[6:9], v[202:205], v[174:177], v[6:9]
	v_mfma_f32_16x16x32_bf16 v[2:5], v[210:213], v[174:177], v[2:5]
	s_barrier
	s_add_i32 s60, 0, 0x18000
	ds_read_b128 v[74:77], v250 offset:32768
	ds_read_b128 v[78:81], v250 offset:33792
	ds_read_b128 v[98:101], v250 offset:34816
	ds_read_b128 v[102:105], v250 offset:35840
	s_add_u32 s0, s10, 0x100000
	s_addc_u32 s1, s11, 0
	s_mov_b32 m0, s22
	ds_read_b128 v[106:109], v231 offset:32768
	ds_read_b128 v[118:121], v231 offset:33792
	ds_read_b128 v[130:133], v231 offset:34816
	ds_read_b128 v[142:145], v231 offset:35840
	ds_read_b128 v[154:157], v231 offset:36864
	ds_read_b128 v[158:161], v231 offset:37888
	ds_read_b128 v[170:173], v231 offset:38912
	ds_read_b128 v[174:177], v231 offset:39936
	global_load_lds_dwordx4 v192, s[0:1]
	s_mov_b32 m0, s23
	s_nop 0
	global_load_lds_dwordx4 v190, s[0:1]
	s_waitcnt lgkmcnt(8)
	s_barrier
	s_waitcnt lgkmcnt(0)
	v_mfma_f32_16x16x32_bf16 v[166:169], v[74:77], v[106:109], v[166:169]
	v_mfma_f32_16x16x32_bf16 v[162:165], v[98:101], v[106:109], v[162:165]
	v_mfma_f32_16x16x32_bf16 v[150:153], v[74:77], v[130:133], v[150:153]
	v_mfma_f32_16x16x32_bf16 v[146:149], v[98:101], v[130:133], v[146:149]
	v_mfma_f32_16x16x32_bf16 v[138:141], v[74:77], v[154:157], v[138:141]
	v_mfma_f32_16x16x32_bf16 v[134:137], v[98:101], v[154:157], v[134:137]
	v_mfma_f32_16x16x32_bf16 v[126:129], v[74:77], v[170:173], v[126:129]
	v_mfma_f32_16x16x32_bf16 v[122:125], v[98:101], v[170:173], v[122:125]
	v_mfma_f32_16x16x32_bf16 v[166:169], v[78:81], v[118:121], v[166:169]
	v_mfma_f32_16x16x32_bf16 v[162:165], v[102:105], v[118:121], v[162:165]
	v_mfma_f32_16x16x32_bf16 v[150:153], v[78:81], v[142:145], v[150:153]
	v_mfma_f32_16x16x32_bf16 v[146:149], v[102:105], v[142:145], v[146:149]
	v_mfma_f32_16x16x32_bf16 v[138:141], v[78:81], v[158:161], v[138:141]
	v_mfma_f32_16x16x32_bf16 v[134:137], v[102:105], v[158:161], v[134:137]
	v_mfma_f32_16x16x32_bf16 v[126:129], v[78:81], v[174:177], v[126:129]
	v_mfma_f32_16x16x32_bf16 v[122:125], v[102:105], v[174:177], v[122:125]
	s_barrier
	s_add_i32 s10, 0, 0x1c000
	s_add_i32 s0, s60, s19
	s_mov_b32 m0, s0
	ds_read_b128 v[198:201], v250 offset:49152
	ds_read_b128 v[202:205], v250 offset:50176
	ds_read_b128 v[206:209], v250 offset:51200
	ds_read_b128 v[210:213], v250 offset:52224
	global_load_lds_dwordx4 v0, s[100:101]
	s_add_i32 m0, s0, 0x2000
	s_nop 0
	global_load_lds_dwordx4 v188, s[100:101]
	s_barrier
	s_waitcnt lgkmcnt(0)
	v_mfma_f32_16x16x32_bf16 v[70:73], v[198:201], v[106:109], v[70:73]
	v_mfma_f32_16x16x32_bf16 v[66:69], v[206:209], v[106:109], v[66:69]
	v_mfma_f32_16x16x32_bf16 v[62:65], v[198:201], v[130:133], v[62:65]
	v_mfma_f32_16x16x32_bf16 v[58:61], v[206:209], v[130:133], v[58:61]
	v_mfma_f32_16x16x32_bf16 v[54:57], v[198:201], v[154:157], v[54:57]
	v_mfma_f32_16x16x32_bf16 v[50:53], v[206:209], v[154:157], v[50:53]
	v_mfma_f32_16x16x32_bf16 v[46:49], v[198:201], v[170:173], v[46:49]
	v_mfma_f32_16x16x32_bf16 v[42:45], v[206:209], v[170:173], v[42:45]
	v_mfma_f32_16x16x32_bf16 v[70:73], v[202:205], v[118:121], v[70:73]
	v_mfma_f32_16x16x32_bf16 v[66:69], v[210:213], v[118:121], v[66:69]
	v_mfma_f32_16x16x32_bf16 v[62:65], v[202:205], v[142:145], v[62:65]
	v_mfma_f32_16x16x32_bf16 v[58:61], v[210:213], v[142:145], v[58:61]
	v_mfma_f32_16x16x32_bf16 v[54:57], v[202:205], v[158:161], v[54:57]
	v_mfma_f32_16x16x32_bf16 v[50:53], v[210:213], v[158:161], v[50:53]
	v_mfma_f32_16x16x32_bf16 v[46:49], v[202:205], v[174:177], v[46:49]
	v_mfma_f32_16x16x32_bf16 v[42:45], v[210:213], v[174:177], v[42:45]
	s_barrier
	s_mov_b32 m0, s24
	ds_read_b128 v[106:109], v231 offset:49152
	ds_read_b128 v[118:121], v231 offset:50176
	ds_read_b128 v[130:133], v231 offset:51200
	ds_read_b128 v[142:145], v231 offset:52224
	ds_read_b128 v[154:157], v231 offset:53248
	ds_read_b128 v[158:161], v231 offset:54272
	ds_read_b128 v[170:173], v231 offset:55296
	ds_read_b128 v[174:177], v231 offset:56320
	global_load_lds_dwordx4 v192, vcc
	s_mov_b32 m0, s25
	s_nop 0
	global_load_lds_dwordx4 v190, vcc
	s_barrier
	s_waitcnt lgkmcnt(0)
	v_mfma_f32_16x16x32_bf16 v[114:117], v[74:77], v[106:109], v[114:117]
	v_mfma_f32_16x16x32_bf16 v[94:97], v[74:77], v[130:133], v[94:97]
	v_mfma_f32_16x16x32_bf16 v[86:89], v[74:77], v[154:157], v[86:89]
	v_mfma_f32_16x16x32_bf16 v[34:37], v[74:77], v[170:173], v[34:37]
	v_mfma_f32_16x16x32_bf16 v[114:117], v[78:81], v[118:121], v[114:117]
	v_mfma_f32_16x16x32_bf16 v[110:113], v[98:101], v[106:109], v[110:113]
	v_mfma_f32_16x16x32_bf16 v[94:97], v[78:81], v[142:145], v[94:97]
	v_mfma_f32_16x16x32_bf16 v[90:93], v[98:101], v[130:133], v[90:93]
	v_mfma_f32_16x16x32_bf16 v[86:89], v[78:81], v[158:161], v[86:89]
	v_mfma_f32_16x16x32_bf16 v[82:85], v[98:101], v[154:157], v[82:85]
	v_mfma_f32_16x16x32_bf16 v[78:81], v[78:81], v[174:177], v[34:37]
	v_mfma_f32_16x16x32_bf16 v[34:37], v[98:101], v[170:173], v[38:41]
	v_mfma_f32_16x16x32_bf16 v[110:113], v[102:105], v[118:121], v[110:113]
	v_mfma_f32_16x16x32_bf16 v[90:93], v[102:105], v[142:145], v[90:93]
	v_mfma_f32_16x16x32_bf16 v[82:85], v[102:105], v[158:161], v[82:85]
	v_mfma_f32_16x16x32_bf16 v[74:77], v[102:105], v[174:177], v[34:37]
	s_barrier
; __device__ __forceinline__ unsigned cvt_pk_bf16(float lo, float hi) { unsigned r; asm volatile("v_cvt_pk_bf16_f32 %0, %1, %2" : "=v"(r) : "v"(lo), "v"(hi)); return r; }
; __device__ __forceinline__ float bf_lo(unsigned w) { return __uint_as_float(w << 16); }
; __device__ __forceinline__ float bf_hi(unsigned w) { return __uint_as_float(w & 0xffff0000u); }
; __device__ __forceinline__ float silu_f(float z) { return z * fast_rcp(1.0f + __builtin_amdgcn_exp2f(z * -1.44269504f)); }
; #define PG8_WAIT_V(n) asm volatile("s_waitcnt vmcnt(" #n ")" ::: "memory")
; #define PG8_BAR __builtin_amdgcn_s_barrier()
; template <class Epi>
; __device__ __forceinline__ void gemm_phase(LAS unsigned char* lds, const Gemm g, const StaticOrder& S, const Epi& E) {
;     ...
;             PG8_WAIT_V(6); PG8_BAR; PG8_MMA(1, 1, At, B1); PG8_BAR;
;     __device__ __forceinline__ void operator()(const f32x4 (&acc)[2][2][4][2], const Unit& u, int wr, int wc, int fr, int fq, const Pre&) const {
;     ...
;         for (int bj = 0; bj < 2; ++bj) { sc[bj][0] = *(const f32x4*)(scale + col0 + bj * HALF); sc[bj][1] = *(const f32x4*)(scale + col0 + bj * HALF + 4); }
; #pragma unroll
;         for (int bj = 0; bj < 2; ++bj) { const int c = col0 + bj * HALF;
;             u32x4 zv[8];
; #pragma unroll
;             for (int g8 = 0; g8 < 8; ++g8) zv[g8] = *(const u32x4*)(Z + (size_t)(row0 + (g8 >> 2) * HALF + (g8 & 3) * 16) * DE2 + c);
; #pragma unroll
;             for (int ai = 0; ai < 2; ++ai)
; #pragma unroll
;                 for (int m = 0; m < 4; ++m) { const int r = row0 + ai * HALF + m * 16;
;                     const u32x4 zw = zv[ai * 4 + m];
;                     const f32x4 a0 = acc[ai][bj][m][0] * sc[bj][0], a1 = acc[ai][bj][m][1] * sc[bj][1];
;                     u32x4 w;
;                     w.x = cvt_pk_bf16(a0[0] * silu_f(bf_lo(zw.x)), a0[1] * silu_f(bf_hi(zw.x)));
;                     w.y = cvt_pk_bf16(a0[2] * silu_f(bf_lo(zw.y)), a0[3] * silu_f(bf_hi(zw.y)));
;                     w.z = cvt_pk_bf16(a1[0] * silu_f(bf_lo(zw.z)), a1[1] * silu_f(bf_hi(zw.z)));
;                     w.w = cvt_pk_bf16(a1[2] * silu_f(bf_lo(zw.w)), a1[3] * silu_f(bf_hi(zw.w)));
;                     *(u32x4*)(O + (size_t)r * DE + c) = w; } }
	s_add_u32 s0, s4, 0x40080
	s_addc_u32 s1, s5, 0
	s_add_i32 s4, s10, s19
	s_mov_b32 m0, s4
	s_nop 0
	global_load_lds_dwordx4 v0, s[0:1]
	s_add_i32 m0, s4, 0x2000
	s_nop 0
	global_load_lds_dwordx4 v188, s[0:1]
	s_waitcnt vmcnt(6)
	s_barrier
	v_mfma_f32_16x16x32_bf16 v[30:33], v[198:201], v[106:109], v[30:33]
	v_mfma_f32_16x16x32_bf16 v[26:29], v[206:209], v[106:109], v[26:29]
	v_mfma_f32_16x16x32_bf16 v[22:25], v[198:201], v[130:133], v[22:25]
	v_mfma_f32_16x16x32_bf16 v[18:21], v[206:209], v[130:133], v[18:21]
	v_mfma_f32_16x16x32_bf16 v[14:17], v[198:201], v[154:157], v[14:17]
	v_mfma_f32_16x16x32_bf16 v[10:13], v[206:209], v[154:157], v[10:13]
	v_mfma_f32_16x16x32_bf16 v[6:9], v[198:201], v[170:173], v[6:9]
	v_mfma_f32_16x16x32_bf16 v[2:5], v[206:209], v[170:173], v[2:5]
	v_mfma_f32_16x16x32_bf16 v[30:33], v[202:205], v[118:121], v[30:33]
	v_mfma_f32_16x16x32_bf16 v[26:29], v[210:213], v[118:121], v[26:29]
	v_mfma_f32_16x16x32_bf16 v[22:25], v[202:205], v[142:145], v[22:25]
	v_mfma_f32_16x16x32_bf16 v[18:21], v[210:213], v[142:145], v[18:21]
	v_mfma_f32_16x16x32_bf16 v[14:17], v[202:205], v[158:161], v[14:17]
	v_mfma_f32_16x16x32_bf16 v[10:13], v[210:213], v[158:161], v[10:13]
	v_mfma_f32_16x16x32_bf16 v[6:9], v[202:205], v[174:177], v[6:9]
	v_mfma_f32_16x16x32_bf16 v[2:5], v[210:213], v[174:177], v[2:5]
	s_barrier
	s_add_i32 s59, s59, 2
	s_add_u32 s53, s53, 0x100
	s_addc_u32 s58, s58, 0
	s_cmp_gt_u32 s59, 13
	s_mov_b64 s[0:1], s[8:9]
	s_cbranch_scc0 .LBB0_603
	v_lshl_or_b32 v200, s34, 8, v230
	v_ashrrev_i32_e32 v201, 31, v200
	v_lshl_add_u32 v226, s27, 8, v228
	v_lshlrev_b64 v[216:217], 1, v[200:201]
	v_ashrrev_i32_e32 v227, 31, v226
	v_lshl_add_u64 v[106:107], s[46:47], 0, v[216:217]
	v_lshlrev_b64 v[204:205], 14, v[226:227]
	v_lshl_add_u64 v[38:39], v[200:201], 2, s[48:49]
	v_lshl_add_u64 v[108:109], v[106:107], 0, v[204:205]
	global_load_dwordx4 v[98:101], v[38:39], off offset:16
	global_load_dwordx4 v[102:105], v[38:39], off
	global_load_dwordx4 v[34:37], v[38:39], off offset:528
	s_nop 0
	global_load_dwordx4 v[38:41], v[38:39], off offset:512
	v_or_b32_e32 v224, 16, v226
	global_load_dwordx4 v[174:177], v[108:109], off
	v_ashrrev_i32_e32 v225, 31, v224
	v_or_b32_e32 v222, 32, v226
	v_lshlrev_b64 v[198:199], 14, v[224:225]
	v_ashrrev_i32_e32 v223, 31, v222
	v_or_b32_e32 v220, 48, v226
	v_lshl_add_u64 v[108:109], v[106:107], 0, v[198:199]
	v_lshlrev_b64 v[202:203], 14, v[222:223]
	v_ashrrev_i32_e32 v221, 31, v220
	v_add_u32_e32 v218, 0x80, v226
	global_load_dwordx4 v[170:173], v[108:109], off
	v_lshl_add_u64 v[108:109], v[106:107], 0, v[202:203]
	v_lshlrev_b64 v[206:207], 14, v[220:221]
	v_ashrrev_i32_e32 v219, 31, v218
	global_load_dwordx4 v[158:161], v[108:109], off
	v_lshl_add_u64 v[108:109], v[106:107], 0, v[206:207]
	v_lshlrev_b64 v[208:209], 14, v[218:219]
	global_load_dwordx4 v[154:157], v[108:109], off
	v_lshl_add_u64 v[108:109], v[106:107], 0, v[208:209]
	global_load_dwordx4 v[142:145], v[108:109], off
	v_add_u32_e32 v108, 0x90, v226
	v_ashrrev_i32_e32 v109, 31, v108
	v_lshlrev_b64 v[210:211], 14, v[108:109]
	v_lshl_add_u64 v[108:109], v[106:107], 0, v[210:211]
	global_load_dwordx4 v[130:133], v[108:109], off
	v_add_u32_e32 v108, 0xa0, v226
	v_ashrrev_i32_e32 v109, 31, v108
	v_lshlrev_b64 v[212:213], 14, v[108:109]
	v_lshl_add_u64 v[108:109], v[106:107], 0, v[212:213]
	global_load_dwordx4 v[118:121], v[108:109], off
	v_add_u32_e32 v108, 0xb0, v226
	v_ashrrev_i32_e32 v109, 31, v108
	v_lshlrev_b64 v[214:215], 14, v[108:109]
	v_lshl_add_u64 v[106:107], v[106:107], 0, v[214:215]
	global_load_dwordx4 v[106:109], v[106:107], off
	s_mov_b64 s[0:1], 0x120000
	s_mov_b32 s27, s52
	s_mov_b32 s34, s50
	s_mov_b64 s[8:9], s[56:57]
	s_waitcnt vmcnt(0)
	v_pk_mul_f32 v[146:147], v[146:147], v[98:99]
	v_pk_mul_f32 v[184:185], v[166:167], v[102:103]
	v_pk_mul_f32 v[166:167], v[164:165], v[100:101]
	v_pk_mul_f32 v[164:165], v[162:163], v[98:99]
	v_pk_mul_f32 v[168:169], v[168:169], v[104:105]
	v_lshlrev_b32_e32 v162, 16, v174
	v_mul_f32_e32 v163, 0xbfb8aa3b, v162
	v_exp_f32_e32 v163, v163
	v_pk_mul_f32 v[150:151], v[150:151], v[102:103]
	v_pk_mul_f32 v[152:153], v[152:153], v[104:105]
	v_pk_mul_f32 v[148:149], v[148:149], v[100:101]
	v_add_f32_e32 v163, 1.0, v163
	v_rcp_f32_e32 v163, v163
	v_pk_mul_f32 v[138:139], v[138:139], v[102:103]
	v_pk_mul_f32 v[140:141], v[140:141], v[104:105]
	v_pk_mul_f32 v[134:135], v[134:135], v[98:99]
	v_mul_f32_e32 v162, v163, v162
	v_and_b32_e32 v163, 0xffff0000, v174
	v_mul_f32_e32 v174, 0xbfb8aa3b, v163
	v_exp_f32_e32 v174, v174
	v_mul_f32_e32 v162, v184, v162
	v_pk_mul_f32 v[136:137], v[136:137], v[100:101]
	v_pk_mul_f32 v[126:127], v[126:127], v[102:103]
	v_add_f32_e32 v174, 1.0, v174
	v_rcp_f32_e32 v174, v174
	v_pk_mul_f32 v[128:129], v[128:129], v[104:105]
	v_pk_mul_f32 v[122:123], v[122:123], v[98:99]
	v_pk_mul_f32 v[124:125], v[124:125], v[100:101]
	v_mul_f32_e32 v163, v174, v163
	v_mul_f32_e32 v163, v185, v163
	v_cvt_pk_bf16_f32 v162, v162, v163
	v_lshlrev_b32_e32 v163, 16, v175
	v_mul_f32_e32 v174, 0xbfb8aa3b, v163
	v_exp_f32_e32 v174, v174
	v_pk_mul_f32 v[114:115], v[114:115], v[102:103]
	v_pk_mul_f32 v[116:117], v[116:117], v[104:105]
	v_pk_mul_f32 v[110:111], v[110:111], v[98:99]
	v_add_f32_e32 v174, 1.0, v174
	v_rcp_f32_e32 v174, v174
	v_pk_mul_f32 v[112:113], v[112:113], v[100:101]
	v_pk_mul_f32 v[94:95], v[94:95], v[102:103]
	v_pk_mul_f32 v[96:97], v[96:97], v[104:105]
	v_mul_f32_e32 v163, v174, v163
	v_mul_f32_e32 v163, v168, v163
	v_and_b32_e32 v168, 0xffff0000, v175
	v_mul_f32_e32 v174, 0xbfb8aa3b, v168
	v_exp_f32_e32 v174, v174
	v_pk_mul_f32 v[90:91], v[90:91], v[98:99]
; __device__ __forceinline__ unsigned cvt_pk_bf16(float lo, float hi) { unsigned r; asm volatile("v_cvt_pk_bf16_f32 %0, %1, %2" : "=v"(r) : "v"(lo), "v"(hi)); return r; }
; __device__ __forceinline__ float bf_lo(unsigned w) { return __uint_as_float(w << 16); }
; __device__ __forceinline__ float bf_hi(unsigned w) { return __uint_as_float(w & 0xffff0000u); }
; __device__ __forceinline__ float fast_rcp(float x) { return __builtin_amdgcn_rcpf(x); }
; __device__ __forceinline__ float silu_f(float z) { return z * fast_rcp(1.0f + __builtin_amdgcn_exp2f(z * -1.44269504f)); }
;     __device__ __forceinline__ void operator()(const f32x4 (&acc)[2][2][4][2], const Unit& u, int wr, int wc, int fr, int fq, const Pre&) const {
;     ...
;             for (int g8 = 0; g8 < 8; ++g8) zv[g8] = *(const u32x4*)(Z + (size_t)(row0 + (g8 >> 2) * HALF + (g8 & 3) * 16) * DE2 + c);
; #pragma unroll
;             for (int ai = 0; ai < 2; ++ai)
; #pragma unroll
;                 for (int m = 0; m < 4; ++m) { const int r = row0 + ai * HALF + m * 16;
;                     const u32x4 zw = zv[ai * 4 + m];
;                     const f32x4 a0 = acc[ai][bj][m][0] * sc[bj][0], a1 = acc[ai][bj][m][1] * sc[bj][1];
;                     u32x4 w;
;                     w.x = cvt_pk_bf16(a0[0] * silu_f(bf_lo(zw.x)), a0[1] * silu_f(bf_hi(zw.x)));
;                     w.y = cvt_pk_bf16(a0[2] * silu_f(bf_lo(zw.y)), a0[3] * silu_f(bf_hi(zw.y)));
;                     w.z = cvt_pk_bf16(a1[0] * silu_f(bf_lo(zw.z)), a1[1] * silu_f(bf_hi(zw.z)));
;                     w.w = cvt_pk_bf16(a1[2] * silu_f(bf_lo(zw.w)), a1[3] * silu_f(bf_hi(zw.w)));
;                     *(u32x4*)(O + (size_t)r * DE + c) = w; } }
	v_pk_mul_f32 v[92:93], v[92:93], v[100:101]
	v_pk_mul_f32 v[86:87], v[86:87], v[102:103]
	v_add_f32_e32 v174, 1.0, v174
	v_rcp_f32_e32 v174, v174
	v_pk_mul_f32 v[88:89], v[88:89], v[104:105]
	v_pk_mul_f32 v[82:83], v[82:83], v[98:99]
	v_pk_mul_f32 v[84:85], v[84:85], v[100:101]
	v_mul_f32_e32 v168, v174, v168
	v_mul_f32_e32 v168, v169, v168
	v_cvt_pk_bf16_f32 v163, v163, v168
	v_lshlrev_b32_e32 v168, 16, v176
	v_mul_f32_e32 v169, 0xbfb8aa3b, v168
	v_exp_f32_e32 v169, v169
	v_pk_mul_f32 v[78:79], v[78:79], v[102:103]
	v_pk_mul_f32 v[80:81], v[80:81], v[104:105]
	v_pk_mul_f32 v[74:75], v[74:75], v[98:99]
	v_add_f32_e32 v169, 1.0, v169
	v_rcp_f32_e32 v169, v169
	v_pk_mul_f32 v[76:77], v[76:77], v[100:101]
	v_pk_mul_f32 v[70:71], v[70:71], v[38:39]
	v_pk_mul_f32 v[72:73], v[72:73], v[40:41]
	v_mul_f32_e32 v168, v169, v168
	v_mul_f32_e32 v164, v164, v168
	v_and_b32_e32 v168, 0xffff0000, v176
	v_mul_f32_e32 v169, 0xbfb8aa3b, v168
	v_exp_f32_e32 v169, v169
	v_pk_mul_f32 v[66:67], v[66:67], v[34:35]
	v_pk_mul_f32 v[68:69], v[68:69], v[36:37]
	v_pk_mul_f32 v[62:63], v[62:63], v[38:39]
	v_add_f32_e32 v169, 1.0, v169
	v_rcp_f32_e32 v169, v169
	v_pk_mul_f32 v[64:65], v[64:65], v[40:41]
	v_pk_mul_f32 v[58:59], v[58:59], v[34:35]
	v_pk_mul_f32 v[60:61], v[60:61], v[36:37]
	v_mul_f32_e32 v168, v169, v168
	v_mul_f32_e32 v165, v165, v168
	v_cvt_pk_bf16_f32 v164, v164, v165
	v_lshlrev_b32_e32 v165, 16, v177
	v_mul_f32_e32 v168, 0xbfb8aa3b, v165
	v_exp_f32_e32 v168, v168
	v_pk_mul_f32 v[54:55], v[54:55], v[38:39]
	v_pk_mul_f32 v[56:57], v[56:57], v[40:41]
	v_pk_mul_f32 v[50:51], v[50:51], v[34:35]
	v_add_f32_e32 v168, 1.0, v168
	v_rcp_f32_e32 v168, v168
	v_pk_mul_f32 v[52:53], v[52:53], v[36:37]
	v_pk_mul_f32 v[46:47], v[46:47], v[38:39]
	v_pk_mul_f32 v[48:49], v[48:49], v[40:41]
	v_mul_f32_e32 v165, v168, v165
	v_mul_f32_e32 v165, v166, v165
	v_and_b32_e32 v166, 0xffff0000, v177
	v_mul_f32_e32 v168, 0xbfb8aa3b, v166
	v_exp_f32_e32 v168, v168
	v_pk_mul_f32 v[42:43], v[42:43], v[34:35]
	v_pk_mul_f32 v[44:45], v[44:45], v[36:37]
	v_pk_mul_f32 v[30:31], v[30:31], v[38:39]
	v_add_f32_e32 v168, 1.0, v168
	v_rcp_f32_e32 v168, v168
	v_pk_mul_f32 v[32:33], v[32:33], v[40:41]
	v_pk_mul_f32 v[26:27], v[26:27], v[34:35]
	v_pk_mul_f32 v[28:29], v[28:29], v[36:37]
	v_mul_f32_e32 v166, v168, v166
	v_mul_f32_e32 v166, v167, v166
	v_cvt_pk_bf16_f32 v165, v165, v166
	v_lshlrev_b64 v[166:167], 13, v[226:227]
	v_lshl_add_u64 v[166:167], s[44:45], 0, v[166:167]
	v_lshl_add_u64 v[166:167], v[166:167], 0, v[216:217]
	global_store_dwordx4 v[166:167], v[162:165], off
	v_pk_mul_f32 v[22:23], v[22:23], v[38:39]
	v_pk_mul_f32 v[24:25], v[24:25], v[40:41]
	v_lshlrev_b32_e32 v162, 16, v170
	v_mul_f32_e32 v163, 0xbfb8aa3b, v162
	v_exp_f32_e32 v163, v163
	v_pk_mul_f32 v[18:19], v[18:19], v[34:35]
	v_pk_mul_f32 v[20:21], v[20:21], v[36:37]
	v_pk_mul_f32 v[14:15], v[14:15], v[38:39]
	v_add_f32_e32 v163, 1.0, v163
	v_rcp_f32_e32 v163, v163
	v_pk_mul_f32 v[16:17], v[16:17], v[40:41]
	v_pk_mul_f32 v[10:11], v[10:11], v[34:35]
	v_pk_mul_f32 v[12:13], v[12:13], v[36:37]
	v_mul_f32_e32 v162, v163, v162
	v_mul_f32_e32 v150, v150, v162
	v_and_b32_e32 v162, 0xffff0000, v170
	v_mul_f32_e32 v163, 0xbfb8aa3b, v162
	v_exp_f32_e32 v163, v163
	v_pk_mul_f32 v[6:7], v[6:7], v[38:39]
	v_pk_mul_f32 v[8:9], v[8:9], v[40:41]
	v_pk_mul_f32 v[2:3], v[2:3], v[34:35]
	v_add_f32_e32 v163, 1.0, v163
	v_rcp_f32_e32 v163, v163
	v_pk_mul_f32 v[4:5], v[4:5], v[36:37]
	v_mul_f32_e32 v162, v163, v162
	v_mul_f32_e32 v151, v151, v162
	v_cvt_pk_bf16_f32 v150, v150, v151
	v_lshlrev_b32_e32 v151, 16, v171
	v_mul_f32_e32 v162, 0xbfb8aa3b, v151
	v_exp_f32_e32 v162, v162
	s_nop 0
	v_add_f32_e32 v162, 1.0, v162
	v_rcp_f32_e32 v162, v162
	s_nop 0
	v_mul_f32_e32 v151, v162, v151
	v_mul_f32_e32 v151, v152, v151
	v_and_b32_e32 v152, 0xffff0000, v171
	v_mul_f32_e32 v162, 0xbfb8aa3b, v152
	v_exp_f32_e32 v162, v162
	s_nop 0
	v_add_f32_e32 v162, 1.0, v162
	v_rcp_f32_e32 v162, v162
	s_nop 0
	v_mul_f32_e32 v152, v162, v152
	v_mul_f32_e32 v152, v153, v152
	v_cvt_pk_bf16_f32 v151, v151, v152
	v_lshlrev_b32_e32 v152, 16, v172
	v_mul_f32_e32 v153, 0xbfb8aa3b, v152
	v_exp_f32_e32 v153, v153
	s_nop 0
	v_add_f32_e32 v153, 1.0, v153
	v_rcp_f32_e32 v153, v153
	s_nop 0
	v_mul_f32_e32 v152, v153, v152
	v_mul_f32_e32 v146, v146, v152
	v_and_b32_e32 v152, 0xffff0000, v172
	v_mul_f32_e32 v153, 0xbfb8aa3b, v152
	v_exp_f32_e32 v153, v153
	s_nop 0
	v_add_f32_e32 v153, 1.0, v153
	v_rcp_f32_e32 v153, v153
	s_nop 0
	v_mul_f32_e32 v152, v153, v152
	v_mul_f32_e32 v147, v147, v152
	v_cvt_pk_bf16_f32 v152, v146, v147
	v_lshlrev_b32_e32 v146, 16, v173
	v_mul_f32_e32 v147, 0xbfb8aa3b, v146
	v_exp_f32_e32 v147, v147
	s_nop 0
	v_add_f32_e32 v147, 1.0, v147
	v_rcp_f32_e32 v147, v147
	s_nop 0
	v_mul_f32_e32 v146, v147, v146
	v_and_b32_e32 v147, 0xffff0000, v173
	v_mul_f32_e32 v146, v148, v146
	v_mul_f32_e32 v148, 0xbfb8aa3b, v147
	v_exp_f32_e32 v148, v148
	s_nop 0
	v_add_f32_e32 v148, 1.0, v148
	v_rcp_f32_e32 v148, v148
	s_nop 0
	v_mul_f32_e32 v147, v148, v147
	v_lshlrev_b32_e32 v148, 16, v158
	v_mul_f32_e32 v147, v149, v147
	v_mul_f32_e32 v149, 0xbfb8aa3b, v148
	v_exp_f32_e32 v149, v149
	v_cvt_pk_bf16_f32 v153, v146, v147
	v_lshlrev_b64 v[146:147], 13, v[224:225]
	v_lshl_add_u64 v[146:147], s[44:45], 0, v[146:147]
	v_add_f32_e32 v149, 1.0, v149
	v_rcp_f32_e32 v149, v149
	v_lshl_add_u64 v[146:147], v[146:147], 0, v[216:217]
	global_store_dwordx4 v[146:147], v[150:153], off
	v_mul_f32_e32 v148, v149, v148
	v_mul_f32_e32 v138, v138, v148
	v_and_b32_e32 v148, 0xffff0000, v158
	v_mul_f32_e32 v149, 0xbfb8aa3b, v148
	v_exp_f32_e32 v149, v149
	s_nop 0
	v_add_f32_e32 v149, 1.0, v149
; __device__ __forceinline__ unsigned cvt_pk_bf16(float lo, float hi) { unsigned r; asm volatile("v_cvt_pk_bf16_f32 %0, %1, %2" : "=v"(r) : "v"(lo), "v"(hi)); return r; }
; __device__ __forceinline__ float bf_lo(unsigned w) { return __uint_as_float(w << 16); }
; __device__ __forceinline__ float bf_hi(unsigned w) { return __uint_as_float(w & 0xffff0000u); }
; __device__ __forceinline__ float fast_rcp(float x) { return __builtin_amdgcn_rcpf(x); }
; __device__ __forceinline__ float silu_f(float z) { return z * fast_rcp(1.0f + __builtin_amdgcn_exp2f(z * -1.44269504f)); }
;     __device__ __forceinline__ void operator()(const f32x4 (&acc)[2][2][4][2], const Unit& u, int wr, int wc, int fr, int fq, const Pre&) const {
;     ...
;             for (int g8 = 0; g8 < 8; ++g8) zv[g8] = *(const u32x4*)(Z + (size_t)(row0 + (g8 >> 2) * HALF + (g8 & 3) * 16) * DE2 + c);
; #pragma unroll
;             for (int ai = 0; ai < 2; ++ai)
; #pragma unroll
;                 for (int m = 0; m < 4; ++m) { const int r = row0 + ai * HALF + m * 16;
;                     const u32x4 zw = zv[ai * 4 + m];
;                     const f32x4 a0 = acc[ai][bj][m][0] * sc[bj][0], a1 = acc[ai][bj][m][1] * sc[bj][1];
;                     u32x4 w;
;                     w.x = cvt_pk_bf16(a0[0] * silu_f(bf_lo(zw.x)), a0[1] * silu_f(bf_hi(zw.x)));
;                     w.y = cvt_pk_bf16(a0[2] * silu_f(bf_lo(zw.y)), a0[3] * silu_f(bf_hi(zw.y)));
;                     w.z = cvt_pk_bf16(a1[0] * silu_f(bf_lo(zw.z)), a1[1] * silu_f(bf_hi(zw.z)));
;                     w.w = cvt_pk_bf16(a1[2] * silu_f(bf_lo(zw.w)), a1[3] * silu_f(bf_hi(zw.w)));
;                     *(u32x4*)(O + (size_t)r * DE + c) = w; } }
	v_rcp_f32_e32 v149, v149
	s_nop 0
	v_mul_f32_e32 v148, v149, v148
	v_mul_f32_e32 v139, v139, v148
	v_cvt_pk_bf16_f32 v138, v138, v139
	v_lshlrev_b32_e32 v139, 16, v159
	v_mul_f32_e32 v148, 0xbfb8aa3b, v139
	v_exp_f32_e32 v148, v148
	s_nop 0
	v_add_f32_e32 v148, 1.0, v148
	v_rcp_f32_e32 v148, v148
	s_nop 0
	v_mul_f32_e32 v139, v148, v139
	v_mul_f32_e32 v139, v140, v139
	v_and_b32_e32 v140, 0xffff0000, v159
	v_mul_f32_e32 v148, 0xbfb8aa3b, v140
	v_exp_f32_e32 v148, v148
	s_nop 0
	v_add_f32_e32 v148, 1.0, v148
	v_rcp_f32_e32 v148, v148
	s_nop 0
	v_mul_f32_e32 v140, v148, v140
	v_mul_f32_e32 v140, v141, v140
	v_cvt_pk_bf16_f32 v139, v139, v140
	v_lshlrev_b32_e32 v140, 16, v160
	v_mul_f32_e32 v141, 0xbfb8aa3b, v140
	v_exp_f32_e32 v141, v141
	s_nop 0
	v_add_f32_e32 v141, 1.0, v141
	v_rcp_f32_e32 v141, v141
	s_nop 0
	v_mul_f32_e32 v140, v141, v140
	v_mul_f32_e32 v134, v134, v140
	v_and_b32_e32 v140, 0xffff0000, v160
	v_mul_f32_e32 v141, 0xbfb8aa3b, v140
	v_exp_f32_e32 v141, v141
	s_nop 0
	v_add_f32_e32 v141, 1.0, v141
	v_rcp_f32_e32 v141, v141
	s_nop 0
	v_mul_f32_e32 v140, v141, v140
	v_mul_f32_e32 v135, v135, v140
	v_cvt_pk_bf16_f32 v140, v134, v135
	v_lshlrev_b32_e32 v134, 16, v161
	v_mul_f32_e32 v135, 0xbfb8aa3b, v134
	v_exp_f32_e32 v135, v135
	s_nop 0
	v_add_f32_e32 v135, 1.0, v135
	v_rcp_f32_e32 v135, v135
	s_nop 0
	v_mul_f32_e32 v134, v135, v134
	v_and_b32_e32 v135, 0xffff0000, v161
	v_mul_f32_e32 v134, v136, v134
	v_mul_f32_e32 v136, 0xbfb8aa3b, v135
	v_exp_f32_e32 v136, v136
	s_nop 0
	v_add_f32_e32 v136, 1.0, v136
	v_rcp_f32_e32 v136, v136
	s_nop 0
	v_mul_f32_e32 v135, v136, v135
	v_lshlrev_b32_e32 v136, 16, v154
	v_mul_f32_e32 v135, v137, v135
	v_mul_f32_e32 v137, 0xbfb8aa3b, v136
	v_exp_f32_e32 v137, v137
	v_cvt_pk_bf16_f32 v141, v134, v135
	v_lshlrev_b64 v[134:135], 13, v[222:223]
	v_lshl_add_u64 v[134:135], s[44:45], 0, v[134:135]
	v_add_f32_e32 v137, 1.0, v137
	v_rcp_f32_e32 v137, v137
	v_lshl_add_u64 v[134:135], v[134:135], 0, v[216:217]
	global_store_dwordx4 v[134:135], v[138:141], off
	v_mul_f32_e32 v136, v137, v136
	v_mul_f32_e32 v126, v126, v136
	v_and_b32_e32 v136, 0xffff0000, v154
	v_mul_f32_e32 v137, 0xbfb8aa3b, v136
	v_exp_f32_e32 v137, v137
	s_nop 0
	v_add_f32_e32 v137, 1.0, v137
	v_rcp_f32_e32 v137, v137
	s_nop 0
	v_mul_f32_e32 v136, v137, v136
	v_mul_f32_e32 v127, v127, v136
	v_cvt_pk_bf16_f32 v126, v126, v127
	v_lshlrev_b32_e32 v127, 16, v155
	v_mul_f32_e32 v136, 0xbfb8aa3b, v127
	v_exp_f32_e32 v136, v136
	s_nop 0
	v_add_f32_e32 v136, 1.0, v136
	v_rcp_f32_e32 v136, v136
	s_nop 0
	v_mul_f32_e32 v127, v136, v127
	v_mul_f32_e32 v127, v128, v127
	v_and_b32_e32 v128, 0xffff0000, v155
	v_mul_f32_e32 v136, 0xbfb8aa3b, v128
	v_exp_f32_e32 v136, v136
	s_nop 0
	v_add_f32_e32 v136, 1.0, v136
	v_rcp_f32_e32 v136, v136
	s_nop 0
	v_mul_f32_e32 v128, v136, v128
	v_mul_f32_e32 v128, v129, v128
	v_cvt_pk_bf16_f32 v127, v127, v128
	v_lshlrev_b32_e32 v128, 16, v156
	v_mul_f32_e32 v129, 0xbfb8aa3b, v128
	v_exp_f32_e32 v129, v129
	s_nop 0
	v_add_f32_e32 v129, 1.0, v129
	v_rcp_f32_e32 v129, v129
	s_nop 0
	v_mul_f32_e32 v128, v129, v128
	v_mul_f32_e32 v122, v122, v128
	v_and_b32_e32 v128, 0xffff0000, v156
	v_mul_f32_e32 v129, 0xbfb8aa3b, v128
	v_exp_f32_e32 v129, v129
	s_nop 0
	v_add_f32_e32 v129, 1.0, v129
	v_rcp_f32_e32 v129, v129
	s_nop 0
	v_mul_f32_e32 v128, v129, v128
	v_mul_f32_e32 v123, v123, v128
	v_cvt_pk_bf16_f32 v128, v122, v123
	v_lshlrev_b32_e32 v122, 16, v157
	v_mul_f32_e32 v123, 0xbfb8aa3b, v122
	v_exp_f32_e32 v123, v123
	s_nop 0
	v_add_f32_e32 v123, 1.0, v123
	v_rcp_f32_e32 v123, v123
	s_nop 0
	v_mul_f32_e32 v122, v123, v122
	v_and_b32_e32 v123, 0xffff0000, v157
	v_mul_f32_e32 v122, v124, v122
	v_mul_f32_e32 v124, 0xbfb8aa3b, v123
	v_exp_f32_e32 v124, v124
	s_nop 0
	v_add_f32_e32 v124, 1.0, v124
	v_rcp_f32_e32 v124, v124
	s_nop 0
	v_mul_f32_e32 v123, v124, v123
	v_lshlrev_b32_e32 v124, 16, v142
	v_mul_f32_e32 v123, v125, v123
	v_mul_f32_e32 v125, 0xbfb8aa3b, v124
	v_exp_f32_e32 v125, v125
	v_cvt_pk_bf16_f32 v129, v122, v123
	v_lshlrev_b64 v[122:123], 13, v[220:221]
	v_lshl_add_u64 v[122:123], s[44:45], 0, v[122:123]
	v_add_f32_e32 v125, 1.0, v125
	v_rcp_f32_e32 v125, v125
	v_lshl_add_u64 v[122:123], v[122:123], 0, v[216:217]
	global_store_dwordx4 v[122:123], v[126:129], off
	v_mul_f32_e32 v124, v125, v124
	v_mul_f32_e32 v114, v114, v124
	v_and_b32_e32 v124, 0xffff0000, v142
	v_mul_f32_e32 v125, 0xbfb8aa3b, v124
	v_exp_f32_e32 v125, v125
	s_nop 0
	v_add_f32_e32 v125, 1.0, v125
	v_rcp_f32_e32 v125, v125
	s_nop 0
	v_mul_f32_e32 v124, v125, v124
	v_mul_f32_e32 v115, v115, v124
	v_cvt_pk_bf16_f32 v114, v114, v115
	v_lshlrev_b32_e32 v115, 16, v143
	v_mul_f32_e32 v124, 0xbfb8aa3b, v115
	v_exp_f32_e32 v124, v124
	s_nop 0
	v_add_f32_e32 v124, 1.0, v124
	v_rcp_f32_e32 v124, v124
	s_nop 0
	v_mul_f32_e32 v115, v124, v115
	v_mul_f32_e32 v115, v116, v115
	v_and_b32_e32 v116, 0xffff0000, v143
	v_mul_f32_e32 v124, 0xbfb8aa3b, v116
	v_exp_f32_e32 v124, v124
	s_nop 0
	v_add_f32_e32 v124, 1.0, v124
	v_rcp_f32_e32 v124, v124
	s_nop 0
	v_mul_f32_e32 v116, v124, v116
	v_mul_f32_e32 v116, v117, v116
	v_cvt_pk_bf16_f32 v115, v115, v116
	v_lshlrev_b32_e32 v116, 16, v144
	v_mul_f32_e32 v117, 0xbfb8aa3b, v116
	v_exp_f32_e32 v117, v117
	s_nop 0
	v_add_f32_e32 v117, 1.0, v117
	v_rcp_f32_e32 v117, v117
	s_nop 0
	v_mul_f32_e32 v116, v117, v116
	v_mul_f32_e32 v110, v110, v116
	v_and_b32_e32 v116, 0xffff0000, v144
	v_mul_f32_e32 v117, 0xbfb8aa3b, v116
	v_exp_f32_e32 v117, v117
	s_nop 0
	v_add_f32_e32 v117, 1.0, v117
	v_rcp_f32_e32 v117, v117
	s_nop 0
	v_mul_f32_e32 v116, v117, v116
	v_mul_f32_e32 v111, v111, v116
	v_cvt_pk_bf16_f32 v116, v110, v111
; __device__ __forceinline__ unsigned cvt_pk_bf16(float lo, float hi) { unsigned r; asm volatile("v_cvt_pk_bf16_f32 %0, %1, %2" : "=v"(r) : "v"(lo), "v"(hi)); return r; }
; __device__ __forceinline__ float bf_lo(unsigned w) { return __uint_as_float(w << 16); }
; __device__ __forceinline__ float bf_hi(unsigned w) { return __uint_as_float(w & 0xffff0000u); }
; __device__ __forceinline__ float fast_rcp(float x) { return __builtin_amdgcn_rcpf(x); }
; __device__ __forceinline__ float silu_f(float z) { return z * fast_rcp(1.0f + __builtin_amdgcn_exp2f(z * -1.44269504f)); }
;     __device__ __forceinline__ void operator()(const f32x4 (&acc)[2][2][4][2], const Unit& u, int wr, int wc, int fr, int fq, const Pre&) const {
;     ...
;             for (int g8 = 0; g8 < 8; ++g8) zv[g8] = *(const u32x4*)(Z + (size_t)(row0 + (g8 >> 2) * HALF + (g8 & 3) * 16) * DE2 + c);
; #pragma unroll
;             for (int ai = 0; ai < 2; ++ai)
; #pragma unroll
;                 for (int m = 0; m < 4; ++m) { const int r = row0 + ai * HALF + m * 16;
;                     const u32x4 zw = zv[ai * 4 + m];
;                     const f32x4 a0 = acc[ai][bj][m][0] * sc[bj][0], a1 = acc[ai][bj][m][1] * sc[bj][1];
;                     u32x4 w;
;                     w.x = cvt_pk_bf16(a0[0] * silu_f(bf_lo(zw.x)), a0[1] * silu_f(bf_hi(zw.x)));
;                     w.y = cvt_pk_bf16(a0[2] * silu_f(bf_lo(zw.y)), a0[3] * silu_f(bf_hi(zw.y)));
;                     w.z = cvt_pk_bf16(a1[0] * silu_f(bf_lo(zw.z)), a1[1] * silu_f(bf_hi(zw.z)));
;                     w.w = cvt_pk_bf16(a1[2] * silu_f(bf_lo(zw.w)), a1[3] * silu_f(bf_hi(zw.w)));
;                     *(u32x4*)(O + (size_t)r * DE + c) = w; } }
	v_lshlrev_b32_e32 v110, 16, v145
	v_mul_f32_e32 v111, 0xbfb8aa3b, v110
	v_exp_f32_e32 v111, v111
	s_nop 0
	v_add_f32_e32 v111, 1.0, v111
	v_rcp_f32_e32 v111, v111
	s_nop 0
	v_mul_f32_e32 v110, v111, v110
	v_and_b32_e32 v111, 0xffff0000, v145
	v_mul_f32_e32 v110, v112, v110
	v_mul_f32_e32 v112, 0xbfb8aa3b, v111
	v_exp_f32_e32 v112, v112
	s_nop 0
	v_add_f32_e32 v112, 1.0, v112
	v_rcp_f32_e32 v112, v112
	s_nop 0
	v_mul_f32_e32 v111, v112, v111
	v_mul_f32_e32 v111, v113, v111
	v_cvt_pk_bf16_f32 v117, v110, v111
	v_lshlrev_b64 v[110:111], 13, v[218:219]
	v_lshl_add_u64 v[110:111], s[44:45], 0, v[110:111]
	v_lshl_add_u64 v[112:113], v[110:111], 0, v[216:217]
	v_lshlrev_b32_e32 v110, 16, v130
	v_mul_f32_e32 v111, 0xbfb8aa3b, v110
	v_exp_f32_e32 v111, v111
	global_store_dwordx4 v[112:113], v[114:117], off
	v_add_f32_e32 v111, 1.0, v111
	v_rcp_f32_e32 v111, v111
	s_nop 0
	v_mul_f32_e32 v110, v111, v110
	v_mul_f32_e32 v94, v94, v110
	v_and_b32_e32 v110, 0xffff0000, v130
	v_mul_f32_e32 v111, 0xbfb8aa3b, v110
	v_exp_f32_e32 v111, v111
	s_nop 0
	v_add_f32_e32 v111, 1.0, v111
	v_rcp_f32_e32 v111, v111
	s_nop 0
	v_mul_f32_e32 v110, v111, v110
	v_mul_f32_e32 v95, v95, v110
	v_cvt_pk_bf16_f32 v94, v94, v95
	v_lshlrev_b32_e32 v95, 16, v131
	v_mul_f32_e32 v110, 0xbfb8aa3b, v95
	v_exp_f32_e32 v110, v110
	s_nop 0
	v_add_f32_e32 v110, 1.0, v110
	v_rcp_f32_e32 v110, v110
	s_nop 0
	v_mul_f32_e32 v95, v110, v95
	v_mul_f32_e32 v95, v96, v95
	v_and_b32_e32 v96, 0xffff0000, v131
	v_mul_f32_e32 v110, 0xbfb8aa3b, v96
	v_exp_f32_e32 v110, v110
	s_nop 0
	v_add_f32_e32 v110, 1.0, v110
	v_rcp_f32_e32 v110, v110
	s_nop 0
	v_mul_f32_e32 v96, v110, v96
	v_mul_f32_e32 v96, v97, v96
	v_cvt_pk_bf16_f32 v95, v95, v96
	v_lshlrev_b32_e32 v96, 16, v132
	v_mul_f32_e32 v97, 0xbfb8aa3b, v96
	v_exp_f32_e32 v97, v97
	v_lshl_add_u64 v[110:111], v[166:167], 0, s[0:1]
	s_mov_b64 s[0:1], 0x140000
	v_lshl_add_u64 v[114:115], v[166:167], 0, s[0:1]
	v_add_f32_e32 v97, 1.0, v97
	v_rcp_f32_e32 v97, v97
	s_mov_b64 s[0:1], 0x160000
	v_mul_f32_e32 v96, v97, v96
	v_mul_f32_e32 v90, v90, v96
	v_and_b32_e32 v96, 0xffff0000, v132
	v_mul_f32_e32 v97, 0xbfb8aa3b, v96
	v_exp_f32_e32 v97, v97
	s_nop 0
	v_add_f32_e32 v97, 1.0, v97
	v_rcp_f32_e32 v97, v97
	s_nop 0
	v_mul_f32_e32 v96, v97, v96
	v_mul_f32_e32 v91, v91, v96
	v_cvt_pk_bf16_f32 v96, v90, v91
	v_lshlrev_b32_e32 v90, 16, v133
	v_mul_f32_e32 v91, 0xbfb8aa3b, v90
	v_exp_f32_e32 v91, v91
	s_nop 0
	v_add_f32_e32 v91, 1.0, v91
	v_rcp_f32_e32 v91, v91
	s_nop 0
	v_mul_f32_e32 v90, v91, v90
	v_and_b32_e32 v91, 0xffff0000, v133
	v_mul_f32_e32 v90, v92, v90
	v_mul_f32_e32 v92, 0xbfb8aa3b, v91
	v_exp_f32_e32 v92, v92
	s_nop 0
	v_add_f32_e32 v92, 1.0, v92
	v_rcp_f32_e32 v92, v92
	s_nop 0
	v_mul_f32_e32 v91, v92, v91
	v_mul_f32_e32 v91, v93, v91
	v_cvt_pk_bf16_f32 v97, v90, v91
	v_add_co_u32_e32 v90, vcc, s41, v166
	s_nop 1
	v_addc_co_u32_e32 v91, vcc, 0, v167, vcc
	global_store_dwordx4 v[90:91], v[94:97], off
	v_lshlrev_b32_e32 v90, 16, v118
	v_mul_f32_e32 v91, 0xbfb8aa3b, v90
	v_exp_f32_e32 v91, v91
	s_nop 0
	v_add_f32_e32 v91, 1.0, v91
	v_rcp_f32_e32 v91, v91
	s_nop 0
	v_mul_f32_e32 v90, v91, v90
	v_mul_f32_e32 v86, v86, v90
	v_and_b32_e32 v90, 0xffff0000, v118
	v_mul_f32_e32 v91, 0xbfb8aa3b, v90
	v_exp_f32_e32 v91, v91
	s_nop 0
	v_add_f32_e32 v91, 1.0, v91
	v_rcp_f32_e32 v91, v91
	s_nop 0
	v_mul_f32_e32 v90, v91, v90
	v_mul_f32_e32 v87, v87, v90
	v_cvt_pk_bf16_f32 v86, v86, v87
	v_lshlrev_b32_e32 v87, 16, v119
	v_mul_f32_e32 v90, 0xbfb8aa3b, v87
	v_exp_f32_e32 v90, v90
	s_nop 0
	v_add_f32_e32 v90, 1.0, v90
	v_rcp_f32_e32 v90, v90
	s_nop 0
	v_mul_f32_e32 v87, v90, v87
	v_mul_f32_e32 v87, v88, v87
	v_and_b32_e32 v88, 0xffff0000, v119
	v_mul_f32_e32 v90, 0xbfb8aa3b, v88
	v_exp_f32_e32 v90, v90
	s_nop 0
	v_add_f32_e32 v90, 1.0, v90
	v_rcp_f32_e32 v90, v90
	s_nop 0
	v_mul_f32_e32 v88, v90, v88
	v_mul_f32_e32 v88, v89, v88
	v_cvt_pk_bf16_f32 v87, v87, v88
	v_lshlrev_b32_e32 v88, 16, v120
	v_mul_f32_e32 v89, 0xbfb8aa3b, v88
	v_exp_f32_e32 v89, v89
	s_nop 0
	v_add_f32_e32 v89, 1.0, v89
	v_rcp_f32_e32 v89, v89
	s_nop 0
	v_mul_f32_e32 v88, v89, v88
	v_mul_f32_e32 v82, v82, v88
	v_and_b32_e32 v88, 0xffff0000, v120
	v_mul_f32_e32 v89, 0xbfb8aa3b, v88
	v_exp_f32_e32 v89, v89
	s_nop 0
	v_add_f32_e32 v89, 1.0, v89
	v_rcp_f32_e32 v89, v89
	s_nop 0
	v_mul_f32_e32 v88, v89, v88
	v_mul_f32_e32 v83, v83, v88
	v_cvt_pk_bf16_f32 v88, v82, v83
	v_lshlrev_b32_e32 v82, 16, v121
	v_mul_f32_e32 v83, 0xbfb8aa3b, v82
	v_exp_f32_e32 v83, v83
	s_nop 0
	v_add_f32_e32 v83, 1.0, v83
	v_rcp_f32_e32 v83, v83
	s_nop 0
	v_mul_f32_e32 v82, v83, v82
	v_and_b32_e32 v83, 0xffff0000, v121
	v_mul_f32_e32 v82, v84, v82
	v_mul_f32_e32 v84, 0xbfb8aa3b, v83
	v_exp_f32_e32 v84, v84
	s_nop 0
	v_add_f32_e32 v84, 1.0, v84
	v_rcp_f32_e32 v84, v84
	s_nop 0
	v_mul_f32_e32 v83, v84, v83
	v_mul_f32_e32 v83, v85, v83
	v_cvt_pk_bf16_f32 v89, v82, v83
	v_add_co_u32_e32 v82, vcc, s65, v166
	s_nop 1
	v_addc_co_u32_e32 v83, vcc, 0, v167, vcc
	global_store_dwordx4 v[82:83], v[86:89], off
	v_lshlrev_b32_e32 v82, 16, v106
	v_mul_f32_e32 v83, 0xbfb8aa3b, v82
	v_exp_f32_e32 v83, v83
	s_nop 0
	v_add_f32_e32 v83, 1.0, v83
	v_rcp_f32_e32 v83, v83
	s_nop 0
	v_mul_f32_e32 v82, v83, v82
	v_mul_f32_e32 v78, v78, v82
	v_and_b32_e32 v82, 0xffff0000, v106
	v_mul_f32_e32 v83, 0xbfb8aa3b, v82
	v_exp_f32_e32 v83, v83
	s_nop 0
	v_add_f32_e32 v83, 1.0, v83
	v_rcp_f32_e32 v83, v83
	s_nop 0
	v_mul_f32_e32 v82, v83, v82
	v_mul_f32_e32 v79, v79, v82
	v_cvt_pk_bf16_f32 v78, v78, v79
	v_lshlrev_b32_e32 v79, 16, v107
	v_mul_f32_e32 v82, 0xbfb8aa3b, v79
	v_exp_f32_e32 v82, v82
	s_nop 0
	v_add_f32_e32 v82, 1.0, v82
	v_rcp_f32_e32 v82, v82
; __device__ __forceinline__ unsigned cvt_pk_bf16(float lo, float hi) { unsigned r; asm volatile("v_cvt_pk_bf16_f32 %0, %1, %2" : "=v"(r) : "v"(lo), "v"(hi)); return r; }
; __device__ __forceinline__ float bf_lo(unsigned w) { return __uint_as_float(w << 16); }
; __device__ __forceinline__ float bf_hi(unsigned w) { return __uint_as_float(w & 0xffff0000u); }
; __device__ __forceinline__ float fast_rcp(float x) { return __builtin_amdgcn_rcpf(x); }
; __device__ __forceinline__ float silu_f(float z) { return z * fast_rcp(1.0f + __builtin_amdgcn_exp2f(z * -1.44269504f)); }
;     __device__ __forceinline__ void operator()(const f32x4 (&acc)[2][2][4][2], const Unit& u, int wr, int wc, int fr, int fq, const Pre&) const {
;     ...
;             for (int g8 = 0; g8 < 8; ++g8) zv[g8] = *(const u32x4*)(Z + (size_t)(row0 + (g8 >> 2) * HALF + (g8 & 3) * 16) * DE2 + c);
; #pragma unroll
;             for (int ai = 0; ai < 2; ++ai)
; #pragma unroll
;                 for (int m = 0; m < 4; ++m) { const int r = row0 + ai * HALF + m * 16;
;                     const u32x4 zw = zv[ai * 4 + m];
;                     const f32x4 a0 = acc[ai][bj][m][0] * sc[bj][0], a1 = acc[ai][bj][m][1] * sc[bj][1];
;                     u32x4 w;
;                     w.x = cvt_pk_bf16(a0[0] * silu_f(bf_lo(zw.x)), a0[1] * silu_f(bf_hi(zw.x)));
;                     w.y = cvt_pk_bf16(a0[2] * silu_f(bf_lo(zw.y)), a0[3] * silu_f(bf_hi(zw.y)));
;                     w.z = cvt_pk_bf16(a1[0] * silu_f(bf_lo(zw.z)), a1[1] * silu_f(bf_hi(zw.z)));
;                     w.w = cvt_pk_bf16(a1[2] * silu_f(bf_lo(zw.w)), a1[3] * silu_f(bf_hi(zw.w)));
;                     *(u32x4*)(O + (size_t)r * DE + c) = w; } }
	s_nop 0
	v_mul_f32_e32 v79, v82, v79
	v_mul_f32_e32 v79, v80, v79
	v_and_b32_e32 v80, 0xffff0000, v107
	v_mul_f32_e32 v82, 0xbfb8aa3b, v80
	v_exp_f32_e32 v82, v82
	v_lshl_add_u64 v[106:107], v[166:167], 0, s[0:1]
	s_mov_b64 s[0:1], s[54:55]
	v_add_f32_e32 v82, 1.0, v82
	v_rcp_f32_e32 v82, v82
	s_nop 0
	v_mul_f32_e32 v80, v82, v80
	v_mul_f32_e32 v80, v81, v80
	v_cvt_pk_bf16_f32 v79, v79, v80
	v_lshlrev_b32_e32 v80, 16, v108
	v_mul_f32_e32 v81, 0xbfb8aa3b, v80
	v_exp_f32_e32 v81, v81
	s_nop 0
	v_add_f32_e32 v81, 1.0, v81
	v_rcp_f32_e32 v81, v81
	s_nop 0
	v_mul_f32_e32 v80, v81, v80
	v_mul_f32_e32 v74, v74, v80
	v_and_b32_e32 v80, 0xffff0000, v108
	v_mul_f32_e32 v81, 0xbfb8aa3b, v80
	v_exp_f32_e32 v81, v81
	s_nop 0
	v_add_f32_e32 v81, 1.0, v81
	v_rcp_f32_e32 v81, v81
	s_nop 0
	v_mul_f32_e32 v80, v81, v80
	v_mul_f32_e32 v75, v75, v80
	v_cvt_pk_bf16_f32 v80, v74, v75
	v_lshlrev_b32_e32 v74, 16, v109
	v_mul_f32_e32 v75, 0xbfb8aa3b, v74
	v_exp_f32_e32 v75, v75
	s_nop 0
	v_add_f32_e32 v75, 1.0, v75
	v_rcp_f32_e32 v75, v75
	s_nop 0
	v_mul_f32_e32 v74, v75, v74
	v_and_b32_e32 v75, 0xffff0000, v109
	v_mul_f32_e32 v74, v76, v74
	v_mul_f32_e32 v76, 0xbfb8aa3b, v75
	v_exp_f32_e32 v76, v76
	s_nop 0
	v_add_f32_e32 v76, 1.0, v76
	v_rcp_f32_e32 v76, v76
	s_nop 0
	v_mul_f32_e32 v75, v76, v75
	v_mul_f32_e32 v75, v77, v75
	v_cvt_pk_bf16_f32 v81, v74, v75
	v_add_co_u32_e32 v74, vcc, s70, v166
	v_lshl_add_u64 v[76:77], s[46:47], 0, v[204:205]
	s_nop 0
	v_addc_co_u32_e32 v75, vcc, 0, v167, vcc
	global_store_dwordx4 v[74:75], v[78:81], off
	v_or_b32_e32 v74, 0x80, v200
	v_ashrrev_i32_e32 v75, 31, v74
	v_lshlrev_b64 v[74:75], 1, v[74:75]
	v_lshl_add_u64 v[76:77], v[76:77], 0, v[74:75]
	global_load_dwordx4 v[102:105], v[76:77], off
	v_lshl_add_u64 v[76:77], s[46:47], 0, v[198:199]
	v_lshl_add_u64 v[76:77], v[76:77], 0, v[74:75]
	global_load_dwordx4 v[98:101], v[76:77], off
	v_lshl_add_u64 v[76:77], s[46:47], 0, v[202:203]
	v_lshl_add_u64 v[76:77], v[76:77], 0, v[74:75]
	global_load_dwordx4 v[94:97], v[76:77], off
	v_lshl_add_u64 v[76:77], s[46:47], 0, v[206:207]
	v_lshl_add_u64 v[76:77], v[76:77], 0, v[74:75]
	global_load_dwordx4 v[90:93], v[76:77], off
	v_lshl_add_u64 v[76:77], s[46:47], 0, v[208:209]
	v_lshl_add_u64 v[76:77], v[76:77], 0, v[74:75]
	global_load_dwordx4 v[86:89], v[76:77], off
	v_lshl_add_u64 v[76:77], s[46:47], 0, v[210:211]
	v_lshl_add_u64 v[76:77], v[76:77], 0, v[74:75]
	global_load_dwordx4 v[82:85], v[76:77], off
	v_lshl_add_u64 v[76:77], s[46:47], 0, v[212:213]
	v_lshl_add_u64 v[76:77], v[76:77], 0, v[74:75]
	global_load_dwordx4 v[78:81], v[76:77], off
	v_lshl_add_u64 v[76:77], s[46:47], 0, v[214:215]
	v_lshl_add_u64 v[74:75], v[76:77], 0, v[74:75]
	global_load_dwordx4 v[74:77], v[74:75], off
	s_and_b64 vcc, exec, s[42:43]
	s_waitcnt vmcnt(0)
	v_lshlrev_b32_e32 v108, 16, v102
	v_mul_f32_e32 v109, 0xbfb8aa3b, v108
	v_exp_f32_e32 v109, v109
	v_and_b32_e32 v102, 0xffff0000, v102
	v_add_f32_e32 v109, 1.0, v109
	v_rcp_f32_e32 v109, v109
	s_nop 0
	v_mul_f32_e32 v108, v109, v108
	v_mul_f32_e32 v70, v70, v108
	v_mul_f32_e32 v108, 0xbfb8aa3b, v102
	v_exp_f32_e32 v108, v108
	s_nop 0
	v_add_f32_e32 v108, 1.0, v108
	v_rcp_f32_e32 v108, v108
	s_nop 0
	v_mul_f32_e32 v102, v108, v102
	v_mul_f32_e32 v71, v71, v102
	v_cvt_pk_bf16_f32 v70, v70, v71
	v_lshlrev_b32_e32 v71, 16, v103
	v_mul_f32_e32 v102, 0xbfb8aa3b, v71
	v_exp_f32_e32 v102, v102
	s_nop 0
	v_add_f32_e32 v102, 1.0, v102
	v_rcp_f32_e32 v102, v102
	s_nop 0
	v_mul_f32_e32 v71, v102, v71
	v_mul_f32_e32 v71, v72, v71
	v_and_b32_e32 v72, 0xffff0000, v103
	v_mul_f32_e32 v102, 0xbfb8aa3b, v72
	v_exp_f32_e32 v102, v102
	s_nop 0
	v_add_f32_e32 v102, 1.0, v102
	v_rcp_f32_e32 v102, v102
	s_nop 0
	v_mul_f32_e32 v72, v102, v72
	v_mul_f32_e32 v72, v73, v72
	v_cvt_pk_bf16_f32 v71, v71, v72
	v_lshlrev_b32_e32 v72, 16, v104
	v_mul_f32_e32 v73, 0xbfb8aa3b, v72
	v_exp_f32_e32 v73, v73
	s_nop 0
	v_add_f32_e32 v73, 1.0, v73
	v_rcp_f32_e32 v73, v73
	s_nop 0
	v_mul_f32_e32 v72, v73, v72
	v_mul_f32_e32 v66, v66, v72
	v_and_b32_e32 v72, 0xffff0000, v104
	v_mul_f32_e32 v73, 0xbfb8aa3b, v72
	v_exp_f32_e32 v73, v73
	s_nop 0
	v_add_f32_e32 v73, 1.0, v73
	v_rcp_f32_e32 v73, v73
	s_nop 0
	v_mul_f32_e32 v72, v73, v72
	v_mul_f32_e32 v67, v67, v72
	v_cvt_pk_bf16_f32 v72, v66, v67
	v_lshlrev_b32_e32 v66, 16, v105
	v_mul_f32_e32 v67, 0xbfb8aa3b, v66
	v_exp_f32_e32 v67, v67
	s_nop 0
	v_add_f32_e32 v67, 1.0, v67
	v_rcp_f32_e32 v67, v67
	s_nop 0
	v_mul_f32_e32 v66, v67, v66
	v_and_b32_e32 v67, 0xffff0000, v105
	v_mul_f32_e32 v66, v68, v66
	v_mul_f32_e32 v68, 0xbfb8aa3b, v67
	v_exp_f32_e32 v68, v68
	s_nop 0
	v_add_f32_e32 v68, 1.0, v68
	v_rcp_f32_e32 v68, v68
	s_nop 0
	v_mul_f32_e32 v67, v68, v67
	v_mul_f32_e32 v67, v69, v67
	v_cvt_pk_bf16_f32 v73, v66, v67
	v_lshlrev_b32_e32 v66, 16, v98
	v_mul_f32_e32 v67, 0xbfb8aa3b, v66
	v_exp_f32_e32 v67, v67
	global_store_dwordx4 v[166:167], v[70:73], off offset:256
	v_add_f32_e32 v67, 1.0, v67
	v_rcp_f32_e32 v67, v67
	s_nop 0
	v_mul_f32_e32 v66, v67, v66
	v_mul_f32_e32 v62, v62, v66
	v_and_b32_e32 v66, 0xffff0000, v98
	v_mul_f32_e32 v67, 0xbfb8aa3b, v66
	v_exp_f32_e32 v67, v67
	s_nop 0
	v_add_f32_e32 v67, 1.0, v67
	v_rcp_f32_e32 v67, v67
	s_nop 0
	v_mul_f32_e32 v66, v67, v66
	v_mul_f32_e32 v63, v63, v66
	v_cvt_pk_bf16_f32 v62, v62, v63
	v_lshlrev_b32_e32 v63, 16, v99
	v_mul_f32_e32 v66, 0xbfb8aa3b, v63
	v_exp_f32_e32 v66, v66
	s_nop 0
	v_add_f32_e32 v66, 1.0, v66
	v_rcp_f32_e32 v66, v66
	s_nop 0
	v_mul_f32_e32 v63, v66, v63
	v_mul_f32_e32 v63, v64, v63
	v_and_b32_e32 v64, 0xffff0000, v99
	v_mul_f32_e32 v66, 0xbfb8aa3b, v64
	v_exp_f32_e32 v66, v66
	s_nop 0
	v_add_f32_e32 v66, 1.0, v66
; __device__ __forceinline__ unsigned cvt_pk_bf16(float lo, float hi) { unsigned r; asm volatile("v_cvt_pk_bf16_f32 %0, %1, %2" : "=v"(r) : "v"(lo), "v"(hi)); return r; }
; __device__ __forceinline__ float bf_lo(unsigned w) { return __uint_as_float(w << 16); }
; __device__ __forceinline__ float bf_hi(unsigned w) { return __uint_as_float(w & 0xffff0000u); }
; __device__ __forceinline__ float fast_rcp(float x) { return __builtin_amdgcn_rcpf(x); }
; __device__ __forceinline__ float silu_f(float z) { return z * fast_rcp(1.0f + __builtin_amdgcn_exp2f(z * -1.44269504f)); }
;     __device__ __forceinline__ void operator()(const f32x4 (&acc)[2][2][4][2], const Unit& u, int wr, int wc, int fr, int fq, const Pre&) const {
;     ...
;             for (int g8 = 0; g8 < 8; ++g8) zv[g8] = *(const u32x4*)(Z + (size_t)(row0 + (g8 >> 2) * HALF + (g8 & 3) * 16) * DE2 + c);
; #pragma unroll
;             for (int ai = 0; ai < 2; ++ai)
; #pragma unroll
;                 for (int m = 0; m < 4; ++m) { const int r = row0 + ai * HALF + m * 16;
;                     const u32x4 zw = zv[ai * 4 + m];
;                     const f32x4 a0 = acc[ai][bj][m][0] * sc[bj][0], a1 = acc[ai][bj][m][1] * sc[bj][1];
;                     u32x4 w;
;                     w.x = cvt_pk_bf16(a0[0] * silu_f(bf_lo(zw.x)), a0[1] * silu_f(bf_hi(zw.x)));
;                     w.y = cvt_pk_bf16(a0[2] * silu_f(bf_lo(zw.y)), a0[3] * silu_f(bf_hi(zw.y)));
;                     w.z = cvt_pk_bf16(a1[0] * silu_f(bf_lo(zw.z)), a1[1] * silu_f(bf_hi(zw.z)));
;                     w.w = cvt_pk_bf16(a1[2] * silu_f(bf_lo(zw.w)), a1[3] * silu_f(bf_hi(zw.w)));
;                     *(u32x4*)(O + (size_t)r * DE + c) = w; } }
	v_rcp_f32_e32 v66, v66
	s_nop 0
	v_mul_f32_e32 v64, v66, v64
	v_mul_f32_e32 v64, v65, v64
	v_cvt_pk_bf16_f32 v63, v63, v64
	v_lshlrev_b32_e32 v64, 16, v100
	v_mul_f32_e32 v65, 0xbfb8aa3b, v64
	v_exp_f32_e32 v65, v65
	s_nop 0
	v_add_f32_e32 v65, 1.0, v65
	v_rcp_f32_e32 v65, v65
	s_nop 0
	v_mul_f32_e32 v64, v65, v64
	v_mul_f32_e32 v58, v58, v64
	v_and_b32_e32 v64, 0xffff0000, v100
	v_mul_f32_e32 v65, 0xbfb8aa3b, v64
	v_exp_f32_e32 v65, v65
	s_nop 0
	v_add_f32_e32 v65, 1.0, v65
	v_rcp_f32_e32 v65, v65
	s_nop 0
	v_mul_f32_e32 v64, v65, v64
	v_mul_f32_e32 v59, v59, v64
	v_cvt_pk_bf16_f32 v64, v58, v59
	v_lshlrev_b32_e32 v58, 16, v101
	v_mul_f32_e32 v59, 0xbfb8aa3b, v58
	v_exp_f32_e32 v59, v59
	s_nop 0
	v_add_f32_e32 v59, 1.0, v59
	v_rcp_f32_e32 v59, v59
	s_nop 0
	v_mul_f32_e32 v58, v59, v58
	v_and_b32_e32 v59, 0xffff0000, v101
	v_mul_f32_e32 v58, v60, v58
	v_mul_f32_e32 v60, 0xbfb8aa3b, v59
	v_exp_f32_e32 v60, v60
	s_nop 0
	v_add_f32_e32 v60, 1.0, v60
	v_rcp_f32_e32 v60, v60
	s_nop 0
	v_mul_f32_e32 v59, v60, v59
	v_mul_f32_e32 v59, v61, v59
	v_cvt_pk_bf16_f32 v65, v58, v59
	v_lshlrev_b32_e32 v58, 16, v94
	v_mul_f32_e32 v59, 0xbfb8aa3b, v58
	v_exp_f32_e32 v59, v59
	global_store_dwordx4 v[146:147], v[62:65], off offset:256
	v_add_f32_e32 v59, 1.0, v59
	v_rcp_f32_e32 v59, v59
	s_nop 0
	v_mul_f32_e32 v58, v59, v58
	v_mul_f32_e32 v54, v54, v58
	v_and_b32_e32 v58, 0xffff0000, v94
	v_mul_f32_e32 v59, 0xbfb8aa3b, v58
	v_exp_f32_e32 v59, v59
	s_nop 0
	v_add_f32_e32 v59, 1.0, v59
	v_rcp_f32_e32 v59, v59
	s_nop 0
	v_mul_f32_e32 v58, v59, v58
	v_mul_f32_e32 v55, v55, v58
	v_cvt_pk_bf16_f32 v54, v54, v55
	v_lshlrev_b32_e32 v55, 16, v95
	v_mul_f32_e32 v58, 0xbfb8aa3b, v55
	v_exp_f32_e32 v58, v58
	s_nop 0
	v_add_f32_e32 v58, 1.0, v58
	v_rcp_f32_e32 v58, v58
	s_nop 0
	v_mul_f32_e32 v55, v58, v55
	v_mul_f32_e32 v55, v56, v55
	v_and_b32_e32 v56, 0xffff0000, v95
	v_mul_f32_e32 v58, 0xbfb8aa3b, v56
	v_exp_f32_e32 v58, v58
	s_nop 0
	v_add_f32_e32 v58, 1.0, v58
	v_rcp_f32_e32 v58, v58
	s_nop 0
	v_mul_f32_e32 v56, v58, v56
	v_mul_f32_e32 v56, v57, v56
	v_cvt_pk_bf16_f32 v55, v55, v56
	v_lshlrev_b32_e32 v56, 16, v96
	v_mul_f32_e32 v57, 0xbfb8aa3b, v56
	v_exp_f32_e32 v57, v57
	s_nop 0
	v_add_f32_e32 v57, 1.0, v57
	v_rcp_f32_e32 v57, v57
	s_nop 0
	v_mul_f32_e32 v56, v57, v56
	v_mul_f32_e32 v50, v50, v56
	v_and_b32_e32 v56, 0xffff0000, v96
	v_mul_f32_e32 v57, 0xbfb8aa3b, v56
	v_exp_f32_e32 v57, v57
	s_nop 0
	v_add_f32_e32 v57, 1.0, v57
	v_rcp_f32_e32 v57, v57
	s_nop 0
	v_mul_f32_e32 v56, v57, v56
	v_mul_f32_e32 v51, v51, v56
	v_cvt_pk_bf16_f32 v56, v50, v51
	v_lshlrev_b32_e32 v50, 16, v97
	v_mul_f32_e32 v51, 0xbfb8aa3b, v50
	v_exp_f32_e32 v51, v51
	s_nop 0
	v_add_f32_e32 v51, 1.0, v51
	v_rcp_f32_e32 v51, v51
	s_nop 0
	v_mul_f32_e32 v50, v51, v50
	v_and_b32_e32 v51, 0xffff0000, v97
	v_mul_f32_e32 v50, v52, v50
	v_mul_f32_e32 v52, 0xbfb8aa3b, v51
	v_exp_f32_e32 v52, v52
	s_nop 0
	v_add_f32_e32 v52, 1.0, v52
	v_rcp_f32_e32 v52, v52
	s_nop 0
	v_mul_f32_e32 v51, v52, v51
	v_mul_f32_e32 v51, v53, v51
	v_cvt_pk_bf16_f32 v57, v50, v51
	v_lshlrev_b32_e32 v50, 16, v90
	v_mul_f32_e32 v51, 0xbfb8aa3b, v50
	v_exp_f32_e32 v51, v51
	global_store_dwordx4 v[134:135], v[54:57], off offset:256
	v_add_f32_e32 v51, 1.0, v51
	v_rcp_f32_e32 v51, v51
	s_nop 0
	v_mul_f32_e32 v50, v51, v50
	v_mul_f32_e32 v46, v46, v50
	v_and_b32_e32 v50, 0xffff0000, v90
	v_mul_f32_e32 v51, 0xbfb8aa3b, v50
	v_exp_f32_e32 v51, v51
	s_nop 0
	v_add_f32_e32 v51, 1.0, v51
	v_rcp_f32_e32 v51, v51
	s_nop 0
	v_mul_f32_e32 v50, v51, v50
	v_mul_f32_e32 v47, v47, v50
	v_cvt_pk_bf16_f32 v46, v46, v47
	v_lshlrev_b32_e32 v47, 16, v91
	v_mul_f32_e32 v50, 0xbfb8aa3b, v47
	v_exp_f32_e32 v50, v50
	s_nop 0
	v_add_f32_e32 v50, 1.0, v50
	v_rcp_f32_e32 v50, v50
	s_nop 0
	v_mul_f32_e32 v47, v50, v47
	v_mul_f32_e32 v47, v48, v47
	v_and_b32_e32 v48, 0xffff0000, v91
	v_mul_f32_e32 v50, 0xbfb8aa3b, v48
	v_exp_f32_e32 v50, v50
	s_nop 0
	v_add_f32_e32 v50, 1.0, v50
	v_rcp_f32_e32 v50, v50
	s_nop 0
	v_mul_f32_e32 v48, v50, v48
	v_mul_f32_e32 v48, v49, v48
	v_cvt_pk_bf16_f32 v47, v47, v48
	v_lshlrev_b32_e32 v48, 16, v92
	v_mul_f32_e32 v49, 0xbfb8aa3b, v48
	v_exp_f32_e32 v49, v49
	s_nop 0
	v_add_f32_e32 v49, 1.0, v49
	v_rcp_f32_e32 v49, v49
	s_nop 0
	v_mul_f32_e32 v48, v49, v48
	v_mul_f32_e32 v42, v42, v48
	v_and_b32_e32 v48, 0xffff0000, v92
	v_mul_f32_e32 v49, 0xbfb8aa3b, v48
	v_exp_f32_e32 v49, v49
	s_nop 0
	v_add_f32_e32 v49, 1.0, v49
	v_rcp_f32_e32 v49, v49
	s_nop 0
	v_mul_f32_e32 v48, v49, v48
	v_mul_f32_e32 v43, v43, v48
	v_cvt_pk_bf16_f32 v48, v42, v43
	v_lshlrev_b32_e32 v42, 16, v93
	v_mul_f32_e32 v43, 0xbfb8aa3b, v42
	v_exp_f32_e32 v43, v43
	s_nop 0
	v_add_f32_e32 v43, 1.0, v43
	v_rcp_f32_e32 v43, v43
	s_nop 0
	v_mul_f32_e32 v42, v43, v42
	v_and_b32_e32 v43, 0xffff0000, v93
	v_mul_f32_e32 v42, v44, v42
	v_mul_f32_e32 v44, 0xbfb8aa3b, v43
	v_exp_f32_e32 v44, v44
	s_nop 0
	v_add_f32_e32 v44, 1.0, v44
	v_rcp_f32_e32 v44, v44
	s_nop 0
	v_mul_f32_e32 v43, v44, v43
	v_mul_f32_e32 v43, v45, v43
	v_cvt_pk_bf16_f32 v49, v42, v43
	v_lshlrev_b32_e32 v42, 16, v86
	v_mul_f32_e32 v43, 0xbfb8aa3b, v42
	v_exp_f32_e32 v43, v43
	global_store_dwordx4 v[122:123], v[46:49], off offset:256
	v_add_f32_e32 v43, 1.0, v43
	v_rcp_f32_e32 v43, v43
	s_nop 0
	v_mul_f32_e32 v42, v43, v42
	v_mul_f32_e32 v30, v30, v42
	v_and_b32_e32 v42, 0xffff0000, v86
	v_mul_f32_e32 v43, 0xbfb8aa3b, v42
	v_exp_f32_e32 v43, v43
	s_nop 0
	v_add_f32_e32 v43, 1.0, v43
	v_rcp_f32_e32 v43, v43
	s_nop 0
	v_mul_f32_e32 v42, v43, v42
	v_mul_f32_e32 v31, v31, v42
	v_cvt_pk_bf16_f32 v30, v30, v31
	v_lshlrev_b32_e32 v31, 16, v87
	v_mul_f32_e32 v42, 0xbfb8aa3b, v31
	v_exp_f32_e32 v42, v42
; __device__ __forceinline__ unsigned cvt_pk_bf16(float lo, float hi) { unsigned r; asm volatile("v_cvt_pk_bf16_f32 %0, %1, %2" : "=v"(r) : "v"(lo), "v"(hi)); return r; }
; __device__ __forceinline__ float bf_lo(unsigned w) { return __uint_as_float(w << 16); }
; __device__ __forceinline__ float bf_hi(unsigned w) { return __uint_as_float(w & 0xffff0000u); }
; __device__ __forceinline__ float fast_rcp(float x) { return __builtin_amdgcn_rcpf(x); }
; __device__ __forceinline__ float silu_f(float z) { return z * fast_rcp(1.0f + __builtin_amdgcn_exp2f(z * -1.44269504f)); }
;     __device__ __forceinline__ void operator()(const f32x4 (&acc)[2][2][4][2], const Unit& u, int wr, int wc, int fr, int fq, const Pre&) const {
;     ...
;             for (int g8 = 0; g8 < 8; ++g8) zv[g8] = *(const u32x4*)(Z + (size_t)(row0 + (g8 >> 2) * HALF + (g8 & 3) * 16) * DE2 + c);
; #pragma unroll
;             for (int ai = 0; ai < 2; ++ai)
; #pragma unroll
;                 for (int m = 0; m < 4; ++m) { const int r = row0 + ai * HALF + m * 16;
;                     const u32x4 zw = zv[ai * 4 + m];
;                     const f32x4 a0 = acc[ai][bj][m][0] * sc[bj][0], a1 = acc[ai][bj][m][1] * sc[bj][1];
;                     u32x4 w;
;                     w.x = cvt_pk_bf16(a0[0] * silu_f(bf_lo(zw.x)), a0[1] * silu_f(bf_hi(zw.x)));
;                     w.y = cvt_pk_bf16(a0[2] * silu_f(bf_lo(zw.y)), a0[3] * silu_f(bf_hi(zw.y)));
;                     w.z = cvt_pk_bf16(a1[0] * silu_f(bf_lo(zw.z)), a1[1] * silu_f(bf_hi(zw.z)));
;                     w.w = cvt_pk_bf16(a1[2] * silu_f(bf_lo(zw.w)), a1[3] * silu_f(bf_hi(zw.w)));
;                     *(u32x4*)(O + (size_t)r * DE + c) = w; } }
	s_nop 0
	v_add_f32_e32 v42, 1.0, v42
	v_rcp_f32_e32 v42, v42
	s_nop 0
	v_mul_f32_e32 v31, v42, v31
	v_mul_f32_e32 v31, v32, v31
	v_and_b32_e32 v32, 0xffff0000, v87
	v_mul_f32_e32 v42, 0xbfb8aa3b, v32
	v_exp_f32_e32 v42, v42
	s_nop 0
	v_add_f32_e32 v42, 1.0, v42
	v_rcp_f32_e32 v42, v42
	s_nop 0
	v_mul_f32_e32 v32, v42, v32
	v_mul_f32_e32 v32, v33, v32
	v_cvt_pk_bf16_f32 v31, v31, v32
	v_lshlrev_b32_e32 v32, 16, v88
	v_mul_f32_e32 v33, 0xbfb8aa3b, v32
	v_exp_f32_e32 v33, v33
	s_nop 0
	v_add_f32_e32 v33, 1.0, v33
	v_rcp_f32_e32 v33, v33
	s_nop 0
	v_mul_f32_e32 v32, v33, v32
	v_mul_f32_e32 v26, v26, v32
	v_and_b32_e32 v32, 0xffff0000, v88
	v_mul_f32_e32 v33, 0xbfb8aa3b, v32
	v_exp_f32_e32 v33, v33
	s_nop 0
	v_add_f32_e32 v33, 1.0, v33
	v_rcp_f32_e32 v33, v33
	s_nop 0
	v_mul_f32_e32 v32, v33, v32
	v_mul_f32_e32 v27, v27, v32
	v_cvt_pk_bf16_f32 v32, v26, v27
	v_lshlrev_b32_e32 v26, 16, v89
	v_mul_f32_e32 v27, 0xbfb8aa3b, v26
	v_exp_f32_e32 v27, v27
	s_nop 0
	v_add_f32_e32 v27, 1.0, v27
	v_rcp_f32_e32 v27, v27
	s_nop 0
	v_mul_f32_e32 v26, v27, v26
	v_and_b32_e32 v27, 0xffff0000, v89
	v_mul_f32_e32 v26, v28, v26
	v_mul_f32_e32 v28, 0xbfb8aa3b, v27
	v_exp_f32_e32 v28, v28
	s_nop 0
	v_add_f32_e32 v28, 1.0, v28
	v_rcp_f32_e32 v28, v28
	s_nop 0
	v_mul_f32_e32 v27, v28, v27
	v_mul_f32_e32 v27, v29, v27
	v_cvt_pk_bf16_f32 v33, v26, v27
	v_lshlrev_b32_e32 v26, 16, v82
	v_mul_f32_e32 v27, 0xbfb8aa3b, v26
	v_exp_f32_e32 v27, v27
	global_store_dwordx4 v[112:113], v[30:33], off offset:256
	v_add_f32_e32 v27, 1.0, v27
	v_rcp_f32_e32 v27, v27
	s_nop 0
	v_mul_f32_e32 v26, v27, v26
	v_mul_f32_e32 v22, v22, v26
	v_and_b32_e32 v26, 0xffff0000, v82
	v_mul_f32_e32 v27, 0xbfb8aa3b, v26
	v_exp_f32_e32 v27, v27
	s_nop 0
	v_add_f32_e32 v27, 1.0, v27
	v_rcp_f32_e32 v27, v27
	s_nop 0
	v_mul_f32_e32 v26, v27, v26
	v_mul_f32_e32 v23, v23, v26
	v_cvt_pk_bf16_f32 v22, v22, v23
	v_lshlrev_b32_e32 v23, 16, v83
	v_mul_f32_e32 v26, 0xbfb8aa3b, v23
	v_exp_f32_e32 v26, v26
	s_nop 0
	v_add_f32_e32 v26, 1.0, v26
	v_rcp_f32_e32 v26, v26
	s_nop 0
	v_mul_f32_e32 v23, v26, v23
	v_mul_f32_e32 v23, v24, v23
	v_and_b32_e32 v24, 0xffff0000, v83
	v_mul_f32_e32 v26, 0xbfb8aa3b, v24
	v_exp_f32_e32 v26, v26
	s_nop 0
	v_add_f32_e32 v26, 1.0, v26
	v_rcp_f32_e32 v26, v26
	s_nop 0
	v_mul_f32_e32 v24, v26, v24
	v_mul_f32_e32 v24, v25, v24
	v_cvt_pk_bf16_f32 v23, v23, v24
	v_lshlrev_b32_e32 v24, 16, v84
	v_mul_f32_e32 v25, 0xbfb8aa3b, v24
	v_exp_f32_e32 v25, v25
	s_nop 0
	v_add_f32_e32 v25, 1.0, v25
	v_rcp_f32_e32 v25, v25
	s_nop 0
	v_mul_f32_e32 v24, v25, v24
	v_mul_f32_e32 v18, v18, v24
	v_and_b32_e32 v24, 0xffff0000, v84
	v_mul_f32_e32 v25, 0xbfb8aa3b, v24
	v_exp_f32_e32 v25, v25
	s_nop 0
	v_add_f32_e32 v25, 1.0, v25
	v_rcp_f32_e32 v25, v25
	s_nop 0
	v_mul_f32_e32 v24, v25, v24
	v_mul_f32_e32 v19, v19, v24
	v_cvt_pk_bf16_f32 v24, v18, v19
	v_lshlrev_b32_e32 v18, 16, v85
	v_mul_f32_e32 v19, 0xbfb8aa3b, v18
	v_exp_f32_e32 v19, v19
	s_nop 0
	v_add_f32_e32 v19, 1.0, v19
	v_rcp_f32_e32 v19, v19
	s_nop 0
	v_mul_f32_e32 v18, v19, v18
	v_and_b32_e32 v19, 0xffff0000, v85
	v_mul_f32_e32 v18, v20, v18
	v_mul_f32_e32 v20, 0xbfb8aa3b, v19
	v_exp_f32_e32 v20, v20
	s_nop 0
	v_add_f32_e32 v20, 1.0, v20
	v_rcp_f32_e32 v20, v20
	s_nop 0
	v_mul_f32_e32 v19, v20, v19
	v_mul_f32_e32 v19, v21, v19
	v_cvt_pk_bf16_f32 v25, v18, v19
	v_lshlrev_b32_e32 v18, 16, v78
	v_mul_f32_e32 v19, 0xbfb8aa3b, v18
	v_exp_f32_e32 v19, v19
	global_store_dwordx4 v[110:111], v[22:25], off offset:256
	v_add_f32_e32 v19, 1.0, v19
	v_rcp_f32_e32 v19, v19
	s_nop 0
	v_mul_f32_e32 v18, v19, v18
	v_mul_f32_e32 v14, v14, v18
	v_and_b32_e32 v18, 0xffff0000, v78
	v_mul_f32_e32 v19, 0xbfb8aa3b, v18
	v_exp_f32_e32 v19, v19
; __device__ __forceinline__ unsigned cvt_pk_bf16(float lo, float hi) { unsigned r; asm volatile("v_cvt_pk_bf16_f32 %0, %1, %2" : "=v"(r) : "v"(lo), "v"(hi)); return r; }
; __device__ __forceinline__ float bf_lo(unsigned w) { return __uint_as_float(w << 16); }
; __device__ __forceinline__ float bf_hi(unsigned w) { return __uint_as_float(w & 0xffff0000u); }
; __device__ __forceinline__ float silu_f(float z) { return z * fast_rcp(1.0f + __builtin_amdgcn_exp2f(z * -1.44269504f)); }
; #define PG8_WAIT_V(n) asm volatile("s_waitcnt vmcnt(" #n ")" ::: "memory")
; #define PG8_BAR __builtin_amdgcn_s_barrier()
; template <class Epi>
; __device__ __forceinline__ void gemm_phase(LAS unsigned char* lds, const Gemm g, const StaticOrder& S, const Epi& E) {
;     ...
;     PG8_WAIT_V(0);
;     if (wr == 0) PG8_BAR;
;     __device__ __forceinline__ void operator()(const f32x4 (&acc)[2][2][4][2], const Unit& u, int wr, int wc, int fr, int fq, const Pre&) const {
;     ...
;             for (int g8 = 0; g8 < 8; ++g8) zv[g8] = *(const u32x4*)(Z + (size_t)(row0 + (g8 >> 2) * HALF + (g8 & 3) * 16) * DE2 + c);
; #pragma unroll
;             for (int ai = 0; ai < 2; ++ai)
; #pragma unroll
;                 for (int m = 0; m < 4; ++m) { const int r = row0 + ai * HALF + m * 16;
;                     const u32x4 zw = zv[ai * 4 + m];
;                     const f32x4 a0 = acc[ai][bj][m][0] * sc[bj][0], a1 = acc[ai][bj][m][1] * sc[bj][1];
;                     u32x4 w;
;                     w.x = cvt_pk_bf16(a0[0] * silu_f(bf_lo(zw.x)), a0[1] * silu_f(bf_hi(zw.x)));
;                     w.y = cvt_pk_bf16(a0[2] * silu_f(bf_lo(zw.y)), a0[3] * silu_f(bf_hi(zw.y)));
;                     w.z = cvt_pk_bf16(a1[0] * silu_f(bf_lo(zw.z)), a1[1] * silu_f(bf_hi(zw.z)));
;                     w.w = cvt_pk_bf16(a1[2] * silu_f(bf_lo(zw.w)), a1[3] * silu_f(bf_hi(zw.w)));
;                     *(u32x4*)(O + (size_t)r * DE + c) = w; } }
	s_nop 0
	v_add_f32_e32 v19, 1.0, v19
	v_rcp_f32_e32 v19, v19
	s_nop 0
	v_mul_f32_e32 v18, v19, v18
	v_mul_f32_e32 v15, v15, v18
	v_cvt_pk_bf16_f32 v14, v14, v15
	v_lshlrev_b32_e32 v15, 16, v79
	v_mul_f32_e32 v18, 0xbfb8aa3b, v15
	v_exp_f32_e32 v18, v18
	s_nop 0
	v_add_f32_e32 v18, 1.0, v18
	v_rcp_f32_e32 v18, v18
	s_nop 0
	v_mul_f32_e32 v15, v18, v15
	v_mul_f32_e32 v15, v16, v15
	v_and_b32_e32 v16, 0xffff0000, v79
	v_mul_f32_e32 v18, 0xbfb8aa3b, v16
	v_exp_f32_e32 v18, v18
	s_nop 0
	v_add_f32_e32 v18, 1.0, v18
	v_rcp_f32_e32 v18, v18
	s_nop 0
	v_mul_f32_e32 v16, v18, v16
	v_mul_f32_e32 v16, v17, v16
	v_cvt_pk_bf16_f32 v15, v15, v16
	v_lshlrev_b32_e32 v16, 16, v80
	v_mul_f32_e32 v17, 0xbfb8aa3b, v16
	v_exp_f32_e32 v17, v17
	s_nop 0
	v_add_f32_e32 v17, 1.0, v17
	v_rcp_f32_e32 v17, v17
	s_nop 0
	v_mul_f32_e32 v16, v17, v16
	v_mul_f32_e32 v10, v10, v16
	v_and_b32_e32 v16, 0xffff0000, v80
	v_mul_f32_e32 v17, 0xbfb8aa3b, v16
	v_exp_f32_e32 v17, v17
	s_nop 0
	v_add_f32_e32 v17, 1.0, v17
	v_rcp_f32_e32 v17, v17
	s_nop 0
	v_mul_f32_e32 v16, v17, v16
	v_mul_f32_e32 v11, v11, v16
	v_cvt_pk_bf16_f32 v16, v10, v11
	v_lshlrev_b32_e32 v10, 16, v81
	v_mul_f32_e32 v11, 0xbfb8aa3b, v10
	v_exp_f32_e32 v11, v11
	s_nop 0
	v_add_f32_e32 v11, 1.0, v11
	v_rcp_f32_e32 v11, v11
	s_nop 0
	v_mul_f32_e32 v10, v11, v10
	v_and_b32_e32 v11, 0xffff0000, v81
	v_mul_f32_e32 v10, v12, v10
	v_mul_f32_e32 v12, 0xbfb8aa3b, v11
	v_exp_f32_e32 v12, v12
	s_nop 0
	v_add_f32_e32 v12, 1.0, v12
	v_rcp_f32_e32 v12, v12
	s_nop 0
	v_mul_f32_e32 v11, v12, v11
	v_mul_f32_e32 v11, v13, v11
	v_cvt_pk_bf16_f32 v17, v10, v11
	v_lshlrev_b32_e32 v10, 16, v74
	v_mul_f32_e32 v11, 0xbfb8aa3b, v10
	v_exp_f32_e32 v11, v11
	global_store_dwordx4 v[114:115], v[14:17], off offset:256
	v_add_f32_e32 v11, 1.0, v11
	v_rcp_f32_e32 v11, v11
	s_nop 0
	v_mul_f32_e32 v10, v11, v10
	v_mul_f32_e32 v6, v6, v10
	v_and_b32_e32 v10, 0xffff0000, v74
	v_mul_f32_e32 v11, 0xbfb8aa3b, v10
	v_exp_f32_e32 v11, v11
	s_nop 0
	v_add_f32_e32 v11, 1.0, v11
	v_rcp_f32_e32 v11, v11
	s_nop 0
	v_mul_f32_e32 v10, v11, v10
	v_mul_f32_e32 v7, v7, v10
	v_cvt_pk_bf16_f32 v6, v6, v7
	v_lshlrev_b32_e32 v7, 16, v75
	v_mul_f32_e32 v10, 0xbfb8aa3b, v7
	v_exp_f32_e32 v10, v10
	s_nop 0
	v_add_f32_e32 v10, 1.0, v10
	v_rcp_f32_e32 v10, v10
	s_nop 0
	v_mul_f32_e32 v7, v10, v7
	v_mul_f32_e32 v7, v8, v7
	v_and_b32_e32 v8, 0xffff0000, v75
	v_mul_f32_e32 v10, 0xbfb8aa3b, v8
	v_exp_f32_e32 v10, v10
	s_nop 0
	v_add_f32_e32 v10, 1.0, v10
	v_rcp_f32_e32 v10, v10
	s_nop 0
	v_mul_f32_e32 v8, v10, v8
	v_mul_f32_e32 v8, v9, v8
	v_cvt_pk_bf16_f32 v7, v7, v8
	v_lshlrev_b32_e32 v8, 16, v76
	v_mul_f32_e32 v9, 0xbfb8aa3b, v8
	v_exp_f32_e32 v9, v9
	s_nop 0
	v_add_f32_e32 v9, 1.0, v9
	v_rcp_f32_e32 v9, v9
	s_nop 0
	v_mul_f32_e32 v8, v9, v8
	v_mul_f32_e32 v2, v2, v8
	v_and_b32_e32 v8, 0xffff0000, v76
	v_mul_f32_e32 v9, 0xbfb8aa3b, v8
	v_exp_f32_e32 v9, v9
	s_nop 0
	v_add_f32_e32 v9, 1.0, v9
	v_rcp_f32_e32 v9, v9
	s_nop 0
	v_mul_f32_e32 v8, v9, v8
	v_mul_f32_e32 v3, v3, v8
	v_cvt_pk_bf16_f32 v8, v2, v3
	v_lshlrev_b32_e32 v2, 16, v77
	v_mul_f32_e32 v3, 0xbfb8aa3b, v2
	v_exp_f32_e32 v3, v3
	s_nop 0
	v_add_f32_e32 v3, 1.0, v3
	v_rcp_f32_e32 v3, v3
	s_nop 0
	v_mul_f32_e32 v2, v3, v2
	v_and_b32_e32 v3, 0xffff0000, v77
	v_mul_f32_e32 v2, v4, v2
	v_mul_f32_e32 v4, 0xbfb8aa3b, v3
	v_exp_f32_e32 v4, v4
	s_nop 0
	v_add_f32_e32 v4, 1.0, v4
	v_rcp_f32_e32 v4, v4
	s_nop 0
	v_mul_f32_e32 v3, v4, v3
	v_mul_f32_e32 v3, v5, v3
	v_cvt_pk_bf16_f32 v9, v2, v3
	global_store_dwordx4 v[106:107], v[6:9], off offset:256
	s_cbranch_vccz .LBB0_596
	s_waitcnt vmcnt(0)
	s_cmpk_gt_u32 s14, 0xff
	s_mov_b64 s[36:37], s[96:97]
	s_cbranch_scc1 .LBB0_607
	s_barrier

; #define PG8_STAGE(bufoff, gbase, voff) do { _Pragma("unroll") for (int _i = 0; _i < 2; ++_i) \
;         __builtin_amdgcn_global_load_lds((const unsigned*)((const char*)(gbase) + (voff)[_i]), (LAS unsigned*)(lds + (bufoff) + ldsw + _i * 8192), 16, 0, 0); } while (0)
; #define PG8_LDA(dst, b, h) do { _Pragma("unroll") for (int m = 0; m < 4; ++m) _Pragma("unroll") for (int k = 0; k < 2; ++k) dst[m][k] = *(const LAS bf16x8*)(lds + PG8_SA(b, h) + aoff + m * 2048 + k * 1024); } while (0)
; #define PG8_LDB(dst, b, h) do { _Pragma("unroll") for (int n = 0; n < 2; ++n) _Pragma("unroll") for (int k = 0; k < 2; ++k) dst[n][k] = *(const LAS bf16x8*)(lds + PG8_SB(b, h) + boff + n * 2048 + k * 1024); } while (0)
; #define PG8_MMA(ai, bj, At, Bt) do { __builtin_amdgcn_s_setprio(1); _Pragma("unroll") for (int m = 0; m < 4; ++m) _Pragma("unroll") for (int n = 0; n < 2; ++n) _Pragma("unroll") for (int k = 0; k < 2; ++k) \
;         acc[ai][bj][m][n] = __builtin_amdgcn_mfma_f32_16x16x32_bf16(Bt[n][k], At[m][k], acc[ai][bj][m][n], 0, 0, 0); __builtin_amdgcn_s_setprio(0); } while (0)
; #define PG8_WAIT_V(n) asm volatile("s_waitcnt vmcnt(" #n ")" ::: "memory")
; #define PG8_WAIT_L(n) asm volatile("s_waitcnt lgkmcnt(" #n ")" ::: "memory")
; #define PG8_BAR __builtin_amdgcn_s_barrier()
; template <class Epi>
; __device__ __forceinline__ void gemm_phase(LAS unsigned char* lds, const Gemm g, const StaticOrder& S, const Epi& E) {
;     ...
;             const bool last = (t == nt - 2);
;             const char* a1 = cA + (size_t)(t + 1) * kstepA;
;             const char* a2 = last ? nA : cA + (size_t)(t + 2) * kstepA; const char* b2 = last ? nB : cB + (size_t)(t + 2) * kstep;
;             const char* a3 = a2 + kstepA; const char* b3 = b2 + kstep;
;             PG8_LDB(B0, 0, 0); PG8_SCHED; PG8_LDA(At, 0, 0); PG8_STAGE(PG8_SA(1, 1), a1 + hstepA, voffA);
;             PG8_WAIT_L(8); PG8_BAR; PG8_WAIT_L(0); PG8_MMA(0, 0, At, B0); PG8_BAR; PG8_SCHED;
;             PG8_LDB(B1, 0, 1); PG8_STAGE(PG8_SB(0, 0), b2, voffB);
;             PG8_BAR; PG8_WAIT_L(0); PG8_MMA(0, 1, At, B1); PG8_BAR;
;             PG8_LDA(At, 0, 1); PG8_STAGE(PG8_SA(0, 0), a2, voffA);
;             PG8_BAR; PG8_WAIT_L(0); PG8_MMA(1, 0, At, B0); PG8_BAR; PG8_SCHED;
;             PG8_STAGE(PG8_SB(0, 1), b2 + hstepB, voffB);
;             PG8_WAIT_V(6); PG8_BAR; PG8_MMA(1, 1, At, B1); PG8_BAR;
.LBB0_796:
	s_add_u32 s4, s8, 0x103400
	s_addc_u32 s5, s9, 0
	s_cmp_eq_u32 s57, 60
	s_cselect_b32 s16, s38, s4
	s_cselect_b32 s17, s37, s5
	s_cselect_b32 s4, s49, s51
	s_cselect_b32 s5, s39, s56
	s_add_u32 s14, s16, 0x104400
	s_addc_u32 s15, s17, 0
	s_add_i32 s58, 0, 0x10000
	ds_read_b128 v[26:29], v250
	ds_read_b128 v[30:33], v250 offset:1024
	ds_read_b128 v[98:101], v250 offset:2048
	ds_read_b128 v[102:105], v250 offset:3072
	s_add_i32 m0, s22, 0xc000
	ds_read_b128 v[130:133], v247
	ds_read_b128 v[142:145], v247 offset:1024
	ds_read_b128 v[146:149], v247 offset:2048
	ds_read_b128 v[150:153], v247 offset:3072
	ds_read_b128 v[154:157], v247 offset:4096
	ds_read_b128 v[166:169], v247 offset:5120
	ds_read_b128 v[170:173], v247 offset:6144
	ds_read_b128 v[174:177], v247 offset:7168
	global_load_lds_dwordx4 v196, s[8:9]
	s_add_i32 m0, s22, 0xe000
	s_nop 0
	global_load_lds_dwordx4 v198, s[8:9]
	s_waitcnt lgkmcnt(8)
	s_barrier
	s_waitcnt lgkmcnt(0)
	v_mfma_f32_16x16x32_bf16 v[162:165], v[26:29], v[130:133], v[162:165]
	v_mfma_f32_16x16x32_bf16 v[158:161], v[98:101], v[130:133], v[158:161]
	v_mfma_f32_16x16x32_bf16 v[138:141], v[26:29], v[146:149], v[138:141]
	v_mfma_f32_16x16x32_bf16 v[134:137], v[98:101], v[146:149], v[134:137]
	v_mfma_f32_16x16x32_bf16 v[126:129], v[26:29], v[154:157], v[126:129]
	v_mfma_f32_16x16x32_bf16 v[122:125], v[98:101], v[154:157], v[122:125]
	v_mfma_f32_16x16x32_bf16 v[118:121], v[26:29], v[170:173], v[118:121]
	v_mfma_f32_16x16x32_bf16 v[114:117], v[98:101], v[170:173], v[114:117]
	v_mfma_f32_16x16x32_bf16 v[162:165], v[30:33], v[142:145], v[162:165]
	v_mfma_f32_16x16x32_bf16 v[158:161], v[102:105], v[142:145], v[158:161]
	v_mfma_f32_16x16x32_bf16 v[138:141], v[30:33], v[150:153], v[138:141]
	v_mfma_f32_16x16x32_bf16 v[134:137], v[102:105], v[150:153], v[134:137]
	v_mfma_f32_16x16x32_bf16 v[126:129], v[30:33], v[166:169], v[126:129]
	v_mfma_f32_16x16x32_bf16 v[122:125], v[102:105], v[166:169], v[122:125]
	v_mfma_f32_16x16x32_bf16 v[118:121], v[30:33], v[174:177], v[118:121]
	v_mfma_f32_16x16x32_bf16 v[114:117], v[102:105], v[174:177], v[114:117]
	s_barrier
	s_add_i32 s60, 0, 0x14000
	s_add_i32 s58, s58, s21
	s_add_u32 s100, s4, s6
	s_addc_u32 s101, s5, s7
	s_mov_b32 m0, s58
	ds_read_b128 v[184:187], v250 offset:16384
	ds_read_b128 v[200:203], v250 offset:17408
	ds_read_b128 v[204:207], v250 offset:18432
	ds_read_b128 v[208:211], v250 offset:19456
	global_load_lds_dwordx4 v0, s[4:5]
	s_add_i32 m0, s58, 0x2000
	s_nop 0
	global_load_lds_dwordx4 v188, s[4:5]
	s_barrier
	s_waitcnt lgkmcnt(0)
	v_mfma_f32_16x16x32_bf16 v[70:73], v[184:187], v[130:133], v[70:73]
	v_mfma_f32_16x16x32_bf16 v[66:69], v[204:207], v[130:133], v[66:69]
	v_mfma_f32_16x16x32_bf16 v[62:65], v[184:187], v[146:149], v[62:65]
	v_mfma_f32_16x16x32_bf16 v[58:61], v[204:207], v[146:149], v[58:61]
	v_mfma_f32_16x16x32_bf16 v[54:57], v[184:187], v[154:157], v[54:57]
	v_mfma_f32_16x16x32_bf16 v[50:53], v[204:207], v[154:157], v[50:53]
	v_mfma_f32_16x16x32_bf16 v[46:49], v[184:187], v[170:173], v[46:49]
	v_mfma_f32_16x16x32_bf16 v[42:45], v[204:207], v[170:173], v[42:45]
	v_mfma_f32_16x16x32_bf16 v[70:73], v[200:203], v[142:145], v[70:73]
	v_mfma_f32_16x16x32_bf16 v[66:69], v[208:211], v[142:145], v[66:69]
	v_mfma_f32_16x16x32_bf16 v[62:65], v[200:203], v[150:153], v[62:65]
	v_mfma_f32_16x16x32_bf16 v[58:61], v[208:211], v[150:153], v[58:61]
	v_mfma_f32_16x16x32_bf16 v[54:57], v[200:203], v[166:169], v[54:57]
	v_mfma_f32_16x16x32_bf16 v[50:53], v[208:211], v[166:169], v[50:53]
	v_mfma_f32_16x16x32_bf16 v[46:49], v[200:203], v[174:177], v[46:49]
	v_mfma_f32_16x16x32_bf16 v[42:45], v[208:211], v[174:177], v[42:45]
	s_barrier
	s_mov_b32 m0, s22
	ds_read_b128 v[130:133], v247 offset:16384
	ds_read_b128 v[142:145], v247 offset:17408
	ds_read_b128 v[146:149], v247 offset:18432
	ds_read_b128 v[150:153], v247 offset:19456
	ds_read_b128 v[154:157], v247 offset:20480
	ds_read_b128 v[166:169], v247 offset:21504
	ds_read_b128 v[170:173], v247 offset:22528
	ds_read_b128 v[174:177], v247 offset:23552
	global_load_lds_dwordx4 v192, s[16:17]
	s_mov_b32 m0, s23
	s_nop 0
	global_load_lds_dwordx4 v190, s[16:17]
	s_barrier
	s_waitcnt lgkmcnt(0)
	v_mfma_f32_16x16x32_bf16 v[110:113], v[26:29], v[130:133], v[110:113]
	v_mfma_f32_16x16x32_bf16 v[106:109], v[98:101], v[130:133], v[106:109]
	v_mfma_f32_16x16x32_bf16 v[94:97], v[26:29], v[146:149], v[94:97]
	v_mfma_f32_16x16x32_bf16 v[90:93], v[98:101], v[146:149], v[90:93]
	v_mfma_f32_16x16x32_bf16 v[86:89], v[26:29], v[154:157], v[86:89]
	v_mfma_f32_16x16x32_bf16 v[82:85], v[98:101], v[154:157], v[82:85]
	v_mfma_f32_16x16x32_bf16 v[26:29], v[26:29], v[170:173], v[78:81]
	v_mfma_f32_16x16x32_bf16 v[110:113], v[30:33], v[142:145], v[110:113]
	v_mfma_f32_16x16x32_bf16 v[106:109], v[102:105], v[142:145], v[106:109]
	v_mfma_f32_16x16x32_bf16 v[94:97], v[30:33], v[150:153], v[94:97]
	v_mfma_f32_16x16x32_bf16 v[90:93], v[102:105], v[150:153], v[90:93]
	v_mfma_f32_16x16x32_bf16 v[86:89], v[30:33], v[166:169], v[86:89]
	v_mfma_f32_16x16x32_bf16 v[82:85], v[102:105], v[166:169], v[82:85]
	v_mfma_f32_16x16x32_bf16 v[26:29], v[30:33], v[174:177], v[26:29]
	v_mfma_f32_16x16x32_bf16 v[30:33], v[98:101], v[170:173], v[74:77]
	v_mfma_f32_16x16x32_bf16 v[30:33], v[102:105], v[174:177], v[30:33]
	s_barrier
	s_add_u32 s58, s4, 0x100000
	s_addc_u32 s59, s5, 0
	s_add_i32 s60, s60, s21
	s_mov_b32 m0, s60
	s_nop 0
	global_load_lds_dwordx4 v0, s[58:59]
	s_add_i32 m0, s60, 0x2000
	s_nop 0
	global_load_lds_dwordx4 v188, s[58:59]
	s_waitcnt vmcnt(6)
	s_barrier
; #define PG8_STAGE(bufoff, gbase, voff) do { _Pragma("unroll") for (int _i = 0; _i < 2; ++_i) \
;         __builtin_amdgcn_global_load_lds((const unsigned*)((const char*)(gbase) + (voff)[_i]), (LAS unsigned*)(lds + (bufoff) + ldsw + _i * 8192), 16, 0, 0); } while (0)
; #define PG8_LDA(dst, b, h) do { _Pragma("unroll") for (int m = 0; m < 4; ++m) _Pragma("unroll") for (int k = 0; k < 2; ++k) dst[m][k] = *(const LAS bf16x8*)(lds + PG8_SA(b, h) + aoff + m * 2048 + k * 1024); } while (0)
; #define PG8_LDB(dst, b, h) do { _Pragma("unroll") for (int n = 0; n < 2; ++n) _Pragma("unroll") for (int k = 0; k < 2; ++k) dst[n][k] = *(const LAS bf16x8*)(lds + PG8_SB(b, h) + boff + n * 2048 + k * 1024); } while (0)
; #define PG8_MMA(ai, bj, At, Bt) do { __builtin_amdgcn_s_setprio(1); _Pragma("unroll") for (int m = 0; m < 4; ++m) _Pragma("unroll") for (int n = 0; n < 2; ++n) _Pragma("unroll") for (int k = 0; k < 2; ++k) \
;         acc[ai][bj][m][n] = __builtin_amdgcn_mfma_f32_16x16x32_bf16(Bt[n][k], At[m][k], acc[ai][bj][m][n], 0, 0, 0); __builtin_amdgcn_s_setprio(0); } while (0)
; #define PG8_WAIT_V(n) asm volatile("s_waitcnt vmcnt(" #n ")" ::: "memory")
; #define PG8_WAIT_L(n) asm volatile("s_waitcnt lgkmcnt(" #n ")" ::: "memory")
; #define PG8_BAR __builtin_amdgcn_s_barrier()
; #define PG8_SCHED __builtin_amdgcn_sched_barrier(0)
; template <class Epi>
; __device__ __forceinline__ void gemm_phase(LAS unsigned char* lds, const Gemm g, const StaticOrder& S, const Epi& E) {
;     ...
;             PG8_WAIT_V(6); PG8_BAR; PG8_MMA(1, 1, At, B1); PG8_BAR;
;             PG8_LDB(B0, 1, 0); PG8_SCHED; PG8_LDA(At, 1, 0); PG8_STAGE(PG8_SA(0, 1), a2 + hstepA, voffA);
;             PG8_WAIT_L(8); PG8_BAR; PG8_WAIT_L(0); PG8_MMA(0, 0, At, B0); PG8_BAR; PG8_SCHED;
;             PG8_LDB(B1, 1, 1); PG8_STAGE(PG8_SB(1, 0), b3, voffB);
;             PG8_BAR; PG8_WAIT_L(0); PG8_MMA(0, 1, At, B1); PG8_BAR;
;             PG8_LDA(At, 1, 1); PG8_STAGE(PG8_SA(1, 0), a3, voffA);
;             PG8_BAR; PG8_WAIT_L(0); PG8_MMA(1, 0, At, B0); PG8_BAR; PG8_SCHED;
;             PG8_STAGE(PG8_SB(1, 1), b3 + hstepB, voffB);
;             PG8_WAIT_V(6); PG8_BAR; PG8_MMA(1, 1, At, B1); PG8_BAR;
	v_mfma_f32_16x16x32_bf16 v[38:41], v[184:187], v[130:133], v[38:41]
	v_mfma_f32_16x16x32_bf16 v[34:37], v[204:207], v[130:133], v[34:37]
	v_mfma_f32_16x16x32_bf16 v[22:25], v[184:187], v[146:149], v[22:25]
	v_mfma_f32_16x16x32_bf16 v[18:21], v[204:207], v[146:149], v[18:21]
	v_mfma_f32_16x16x32_bf16 v[14:17], v[184:187], v[154:157], v[14:17]
	v_mfma_f32_16x16x32_bf16 v[10:13], v[204:207], v[154:157], v[10:13]
	v_mfma_f32_16x16x32_bf16 v[6:9], v[184:187], v[170:173], v[6:9]
	v_mfma_f32_16x16x32_bf16 v[2:5], v[204:207], v[170:173], v[2:5]
	v_mfma_f32_16x16x32_bf16 v[38:41], v[200:203], v[142:145], v[38:41]
	v_mfma_f32_16x16x32_bf16 v[34:37], v[208:211], v[142:145], v[34:37]
	v_mfma_f32_16x16x32_bf16 v[22:25], v[200:203], v[150:153], v[22:25]
	v_mfma_f32_16x16x32_bf16 v[18:21], v[208:211], v[150:153], v[18:21]
	v_mfma_f32_16x16x32_bf16 v[14:17], v[200:203], v[166:169], v[14:17]
	v_mfma_f32_16x16x32_bf16 v[10:13], v[208:211], v[166:169], v[10:13]
	v_mfma_f32_16x16x32_bf16 v[6:9], v[200:203], v[174:177], v[6:9]
	v_mfma_f32_16x16x32_bf16 v[2:5], v[208:211], v[174:177], v[2:5]
	s_barrier
	s_add_i32 s58, 0, 0x18000
	ds_read_b128 v[74:77], v250 offset:32768
	ds_read_b128 v[78:81], v250 offset:33792
	ds_read_b128 v[98:101], v250 offset:34816
	ds_read_b128 v[102:105], v250 offset:35840
	s_add_u32 s16, s16, 0x1000
	s_addc_u32 s17, s17, 0
	s_mov_b32 m0, s24
	ds_read_b128 v[130:133], v247 offset:32768
	ds_read_b128 v[142:145], v247 offset:33792
	ds_read_b128 v[146:149], v247 offset:34816
	ds_read_b128 v[150:153], v247 offset:35840
	ds_read_b128 v[154:157], v247 offset:36864
	ds_read_b128 v[166:169], v247 offset:37888
	ds_read_b128 v[170:173], v247 offset:38912
	ds_read_b128 v[174:177], v247 offset:39936
	global_load_lds_dwordx4 v192, s[16:17]
	s_mov_b32 m0, s25
	s_nop 0
	global_load_lds_dwordx4 v190, s[16:17]
	s_waitcnt lgkmcnt(8)
	s_barrier
	s_waitcnt lgkmcnt(0)
	v_mfma_f32_16x16x32_bf16 v[162:165], v[74:77], v[130:133], v[162:165]
	v_mfma_f32_16x16x32_bf16 v[158:161], v[98:101], v[130:133], v[158:161]
	v_mfma_f32_16x16x32_bf16 v[138:141], v[74:77], v[146:149], v[138:141]
	v_mfma_f32_16x16x32_bf16 v[134:137], v[98:101], v[146:149], v[134:137]
	v_mfma_f32_16x16x32_bf16 v[126:129], v[74:77], v[154:157], v[126:129]
	v_mfma_f32_16x16x32_bf16 v[122:125], v[98:101], v[154:157], v[122:125]
	v_mfma_f32_16x16x32_bf16 v[118:121], v[74:77], v[170:173], v[118:121]
	v_mfma_f32_16x16x32_bf16 v[114:117], v[98:101], v[170:173], v[114:117]
	v_mfma_f32_16x16x32_bf16 v[162:165], v[78:81], v[142:145], v[162:165]
	v_mfma_f32_16x16x32_bf16 v[158:161], v[102:105], v[142:145], v[158:161]
	v_mfma_f32_16x16x32_bf16 v[138:141], v[78:81], v[150:153], v[138:141]
	v_mfma_f32_16x16x32_bf16 v[134:137], v[102:105], v[150:153], v[134:137]
	v_mfma_f32_16x16x32_bf16 v[126:129], v[78:81], v[166:169], v[126:129]
	v_mfma_f32_16x16x32_bf16 v[122:125], v[102:105], v[166:169], v[122:125]
	v_mfma_f32_16x16x32_bf16 v[118:121], v[78:81], v[174:177], v[118:121]
	v_mfma_f32_16x16x32_bf16 v[114:117], v[102:105], v[174:177], v[114:117]
	s_barrier
	s_add_i32 s16, 0, 0x1c000
	s_add_i32 s17, s58, s21
	s_mov_b32 m0, s17
	ds_read_b128 v[184:187], v250 offset:49152
	ds_read_b128 v[200:203], v250 offset:50176
	ds_read_b128 v[204:207], v250 offset:51200
	ds_read_b128 v[208:211], v250 offset:52224
	global_load_lds_dwordx4 v0, s[100:101]
	s_add_i32 m0, s17, 0x2000
	s_nop 0
	global_load_lds_dwordx4 v188, s[100:101]
	s_barrier
	s_waitcnt lgkmcnt(0)
	v_mfma_f32_16x16x32_bf16 v[70:73], v[184:187], v[130:133], v[70:73]
	v_mfma_f32_16x16x32_bf16 v[66:69], v[204:207], v[130:133], v[66:69]
	v_mfma_f32_16x16x32_bf16 v[62:65], v[184:187], v[146:149], v[62:65]
	v_mfma_f32_16x16x32_bf16 v[58:61], v[204:207], v[146:149], v[58:61]
	v_mfma_f32_16x16x32_bf16 v[54:57], v[184:187], v[154:157], v[54:57]
	v_mfma_f32_16x16x32_bf16 v[50:53], v[204:207], v[154:157], v[50:53]
	v_mfma_f32_16x16x32_bf16 v[46:49], v[184:187], v[170:173], v[46:49]
	v_mfma_f32_16x16x32_bf16 v[42:45], v[204:207], v[170:173], v[42:45]
	v_mfma_f32_16x16x32_bf16 v[70:73], v[200:203], v[142:145], v[70:73]
	v_mfma_f32_16x16x32_bf16 v[66:69], v[208:211], v[142:145], v[66:69]
	v_mfma_f32_16x16x32_bf16 v[62:65], v[200:203], v[150:153], v[62:65]
	v_mfma_f32_16x16x32_bf16 v[58:61], v[208:211], v[150:153], v[58:61]
	v_mfma_f32_16x16x32_bf16 v[54:57], v[200:203], v[166:169], v[54:57]
	v_mfma_f32_16x16x32_bf16 v[50:53], v[208:211], v[166:169], v[50:53]
	v_mfma_f32_16x16x32_bf16 v[46:49], v[200:203], v[174:177], v[46:49]
	v_mfma_f32_16x16x32_bf16 v[42:45], v[208:211], v[174:177], v[42:45]
	s_barrier
	s_mov_b32 m0, s26
	ds_read_b128 v[130:133], v247 offset:49152
	ds_read_b128 v[142:145], v247 offset:50176
	ds_read_b128 v[146:149], v247 offset:51200
	ds_read_b128 v[150:153], v247 offset:52224
	ds_read_b128 v[154:157], v247 offset:53248
	ds_read_b128 v[166:169], v247 offset:54272
	ds_read_b128 v[170:173], v247 offset:55296
	ds_read_b128 v[174:177], v247 offset:56320
	global_load_lds_dwordx4 v192, s[14:15]
	s_mov_b32 m0, s27
	s_nop 0
	global_load_lds_dwordx4 v190, s[14:15]
	s_barrier
	s_waitcnt lgkmcnt(0)
	v_mfma_f32_16x16x32_bf16 v[110:113], v[74:77], v[130:133], v[110:113]
	v_mfma_f32_16x16x32_bf16 v[94:97], v[74:77], v[146:149], v[94:97]
	v_mfma_f32_16x16x32_bf16 v[86:89], v[74:77], v[154:157], v[86:89]
	v_mfma_f32_16x16x32_bf16 v[26:29], v[74:77], v[170:173], v[26:29]
	v_mfma_f32_16x16x32_bf16 v[110:113], v[78:81], v[142:145], v[110:113]
	v_mfma_f32_16x16x32_bf16 v[106:109], v[98:101], v[130:133], v[106:109]
	v_mfma_f32_16x16x32_bf16 v[94:97], v[78:81], v[150:153], v[94:97]
	v_mfma_f32_16x16x32_bf16 v[90:93], v[98:101], v[146:149], v[90:93]
	v_mfma_f32_16x16x32_bf16 v[86:89], v[78:81], v[166:169], v[86:89]
	v_mfma_f32_16x16x32_bf16 v[82:85], v[98:101], v[154:157], v[82:85]
	v_mfma_f32_16x16x32_bf16 v[78:81], v[78:81], v[174:177], v[26:29]
	v_mfma_f32_16x16x32_bf16 v[26:29], v[98:101], v[170:173], v[30:33]
	v_mfma_f32_16x16x32_bf16 v[106:109], v[102:105], v[142:145], v[106:109]
	v_mfma_f32_16x16x32_bf16 v[90:93], v[102:105], v[150:153], v[90:93]
	v_mfma_f32_16x16x32_bf16 v[82:85], v[102:105], v[166:169], v[82:85]
	v_mfma_f32_16x16x32_bf16 v[74:77], v[102:105], v[174:177], v[26:29]
	s_barrier
; __device__ __forceinline__ unsigned cvt_pk_bf16(float lo, float hi) { unsigned r; asm volatile("v_cvt_pk_bf16_f32 %0, %1, %2" : "=v"(r) : "v"(lo), "v"(hi)); return r; }
; __device__ __forceinline__ float bf_lo(unsigned w) { return __uint_as_float(w << 16); }
; __device__ __forceinline__ float bf_hi(unsigned w) { return __uint_as_float(w & 0xffff0000u); }
; template <class Epi>
; __device__ __forceinline__ void gemm_phase(LAS unsigned char* lds, const Gemm g, const StaticOrder& S, const Epi& E) {
;     ...
;             PG8_STAGE(PG8_SB(1, 1), b3 + hstepB, voffB);
;             PG8_WAIT_V(6); PG8_BAR; PG8_MMA(1, 1, At, B1); PG8_BAR;
;     __device__ __forceinline__ void operator()(const f32x4 (&acc)[2][2][4][2], const Unit& u, int wr, int wc, int fr, int fq, const Pre&) const {
;         const int row0 = u.pm * BM + wr * 64 + fr, col0 = u.pn * BM + wc * 32 + 8 * fq;
;         f32x4 bs[2][2];
; #pragma unroll
;         for (int bj = 0; bj < 2; ++bj) { bs[bj][0] = *(const f32x4*)(bias + col0 + bj * HALF); bs[bj][1] = *(const f32x4*)(bias + col0 + bj * HALF + 4); }
; #pragma unroll
;         for (int bj = 0; bj < 2; ++bj) { const int c = col0 + bj * HALF;
; #pragma unroll
;             for (int ai = 0; ai < 2; ++ai) { u32x4 zv[4], gv[4];
; #pragma unroll
;                 for (int m = 0; m < 4; ++m) { const int r = row0 + ai * HALF + m * 16; zv[m] = *(const u32x4*)(Z + (size_t)r * DE2 + c); gv[m] = *(const u32x4*)(Gm + (size_t)(c >> 4) * GSTR + r * 16 + (c & 15)); }
; #pragma unroll
;                 for (int m = 0; m < 4; ++m) { const int r = row0 + ai * HALF + m * 16;
;                     const u32x4 zw = zv[m], gw = gv[m];
;                     const f32x4 a0 = acc[ai][bj][m][0] + bs[bj][0], a1 = acc[ai][bj][m][1] + bs[bj][1];
;                     u32x4 w;
;                     w.x = cvt_pk_bf16(glu_gate_f(bf_lo(gw.x), a0[0], bf_lo(zw.x)), glu_gate_f(bf_hi(gw.x), a0[1], bf_hi(zw.x)));
;                     w.y = cvt_pk_bf16(glu_gate_f(bf_lo(gw.y), a0[2], bf_lo(zw.y)), glu_gate_f(bf_hi(gw.y), a0[3], bf_hi(zw.y)));
;                     w.z = cvt_pk_bf16(glu_gate_f(bf_lo(gw.z), a1[0], bf_lo(zw.z)), glu_gate_f(bf_hi(gw.z), a1[1], bf_hi(zw.z)));
;                     w.w = cvt_pk_bf16(glu_gate_f(bf_lo(gw.w), a1[2], bf_lo(zw.w)), glu_gate_f(bf_hi(gw.w), a1[3], bf_hi(zw.w)));
;                     *(u32x4*)(O + (size_t)r * DE + c) = w; } } }
	s_add_u32 s4, s4, 0x100080
	s_addc_u32 s5, s5, 0
	s_add_i32 s14, s16, s21
	s_mov_b32 m0, s14
	s_nop 0
	global_load_lds_dwordx4 v0, s[4:5]
	s_add_i32 m0, s14, 0x2000
	s_nop 0
	global_load_lds_dwordx4 v188, s[4:5]
	s_waitcnt vmcnt(6)
	s_barrier
	v_mfma_f32_16x16x32_bf16 v[26:29], v[184:187], v[130:133], v[38:41]
	v_mfma_f32_16x16x32_bf16 v[38:41], v[200:203], v[142:145], v[26:29]
	v_mfma_f32_16x16x32_bf16 v[26:29], v[204:207], v[130:133], v[34:37]
	v_mfma_f32_16x16x32_bf16 v[22:25], v[184:187], v[146:149], v[22:25]
	v_mfma_f32_16x16x32_bf16 v[18:21], v[204:207], v[146:149], v[18:21]
	v_mfma_f32_16x16x32_bf16 v[14:17], v[184:187], v[154:157], v[14:17]
	v_mfma_f32_16x16x32_bf16 v[10:13], v[204:207], v[154:157], v[10:13]
	v_mfma_f32_16x16x32_bf16 v[6:9], v[184:187], v[170:173], v[6:9]
	v_mfma_f32_16x16x32_bf16 v[2:5], v[204:207], v[170:173], v[2:5]
	v_mfma_f32_16x16x32_bf16 v[34:37], v[208:211], v[142:145], v[26:29]
	v_mfma_f32_16x16x32_bf16 v[22:25], v[200:203], v[150:153], v[22:25]
	v_mfma_f32_16x16x32_bf16 v[18:21], v[208:211], v[150:153], v[18:21]
	v_mfma_f32_16x16x32_bf16 v[14:17], v[200:203], v[166:169], v[14:17]
	v_mfma_f32_16x16x32_bf16 v[10:13], v[208:211], v[166:169], v[10:13]
	v_mfma_f32_16x16x32_bf16 v[6:9], v[200:203], v[174:177], v[6:9]
	v_mfma_f32_16x16x32_bf16 v[2:5], v[208:211], v[174:177], v[2:5]
	s_barrier
	s_add_i32 s57, s57, 2
	s_add_u32 s51, s51, 0x100
	s_addc_u32 s56, s56, 0
	s_add_u32 s8, s8, 0x208800
	s_addc_u32 s9, s9, 0
	s_cmp_gt_u32 s57, 61
	s_cbranch_scc0 .LBB0_796
	v_lshl_or_b32 v200, s36, 8, v246
	v_ashrrev_i32_e32 v201, 31, v200
	v_lshl_add_u32 v224, s35, 8, v244
	v_lshlrev_b64 v[204:205], 1, v[200:201]
	v_ashrrev_i32_e32 v225, 31, v224
	v_ashrrev_i32_e32 v130, 4, v200
	v_lshl_add_u64 v[222:223], s[46:47], 0, v[204:205]
	v_lshlrev_b64 v[202:203], 14, v[224:225]
	v_lshl_add_u64 v[30:31], v[200:201], 2, s[10:11]
	v_mad_i64_i32 v[220:221], s[4:5], v130, s94, v[194:195]
	v_lshl_add_u64 v[130:131], v[222:223], 0, v[202:203]
	global_load_dwordx4 v[98:101], v[30:31], off offset:16
	global_load_dwordx4 v[102:105], v[30:31], off
	global_load_dwordx4 v[26:29], v[30:31], off offset:528
	s_nop 0
	global_load_dwordx4 v[30:33], v[30:31], off offset:512
	v_or_b32_e32 v226, 48, v224
	global_load_dwordx4 v[170:173], v[130:131], off
	v_lshlrev_b32_e32 v142, 4, v226
	v_ashrrev_i32_e32 v143, 31, v142
	v_lshlrev_b64 v[218:219], 1, v[142:143]
	v_lshl_add_u64 v[142:143], v[220:221], 0, v[218:219]
	global_load_dwordx4 v[142:145], v[142:143], off
	v_lshlrev_b32_e32 v130, 4, v224
	v_ashrrev_i32_e32 v131, 31, v130
	v_lshlrev_b64 v[206:207], 1, v[130:131]
	v_lshl_add_u64 v[130:131], v[220:221], 0, v[206:207]
	global_load_dwordx4 v[174:177], v[130:131], off
	v_or_b32_e32 v230, 16, v224
	v_ashrrev_i32_e32 v231, 31, v230
	v_lshlrev_b64 v[210:211], 14, v[230:231]
	v_lshl_add_u64 v[130:131], v[222:223], 0, v[210:211]
	global_load_dwordx4 v[154:157], v[130:131], off
	v_lshlrev_b32_e32 v130, 4, v230
	v_ashrrev_i32_e32 v131, 31, v130
	v_or_b32_e32 v228, 32, v224
	v_lshlrev_b64 v[208:209], 1, v[130:131]
	v_ashrrev_i32_e32 v229, 31, v228
	v_lshl_add_u64 v[130:131], v[220:221], 0, v[208:209]
	v_lshlrev_b64 v[214:215], 14, v[228:229]
	global_load_dwordx4 v[166:169], v[130:131], off
	v_lshl_add_u64 v[130:131], v[222:223], 0, v[214:215]
	global_load_dwordx4 v[146:149], v[130:131], off
	v_lshlrev_b32_e32 v130, 4, v228
	v_ashrrev_i32_e32 v131, 31, v130
	v_lshlrev_b64 v[212:213], 1, v[130:131]
	v_ashrrev_i32_e32 v227, 31, v226
	v_lshl_add_u64 v[130:131], v[220:221], 0, v[212:213]
	v_lshlrev_b64 v[216:217], 14, v[226:227]
	global_load_dwordx4 v[150:153], v[130:131], off
	v_lshl_add_u64 v[130:131], v[222:223], 0, v[216:217]
	global_load_dwordx4 v[130:133], v[130:131], off
	s_and_b64 vcc, exec, s[40:41]
	s_mov_b32 s35, s50
	s_mov_b32 s36, s48
	s_mov_b64 s[8:9], s[54:55]
	s_mov_b64 s[14:15], s[52:53]
	s_waitcnt vmcnt(0)
	v_pk_add_f32 v[134:135], v[134:135], v[98:99]
	v_pk_add_f32 v[184:185], v[162:163], v[102:103]
	v_pk_add_f32 v[162:163], v[160:161], v[100:101]
	v_pk_add_f32 v[160:161], v[158:159], v[98:99]
	v_mul_f32_e32 v158, 0xbfb8aa3b, v184
	v_lshlrev_b32_e32 v186, 16, v170
	v_mul_f32_e32 v159, 0xbfb8aa3b, v186
	v_exp_f32_e32 v158, v158
	v_exp_f32_e32 v159, v159
	v_and_b32_e32 v170, 0xffff0000, v170
	v_pk_add_f32 v[164:165], v[164:165], v[104:105]
	v_mul_f32_e32 v160, 0xbfb8aa3b, v160
	v_pk_add_f32 v[158:159], v[158:159], 1.0 op_sel_hi:[1,0]
	v_mul_f32_e32 v164, 0xbfb8aa3b, v164
	v_mul_f32_e32 v158, v158, v159
	v_rcp_f32_e32 v158, v158
	v_lshlrev_b32_e32 v187, 16, v174
	v_mul_f32_e32 v184, v187, v186
	v_mul_f32_e32 v159, 0xbfb8aa3b, v170
	v_mul_f32_e32 v184, v184, v158
	v_mul_f32_e32 v158, 0xbfb8aa3b, v185
	v_exp_f32_e32 v158, v158
	v_exp_f32_e32 v159, v159
	v_and_b32_e32 v174, 0xffff0000, v174
	v_mul_f32_e32 v170, v174, v170
	v_mul_f32_e32 v162, 0xbfb8aa3b, v162
	v_pk_add_f32 v[158:159], v[158:159], 1.0 op_sel_hi:[1,0]
	v_pk_add_f32 v[138:139], v[138:139], v[102:103]
	v_mul_f32_e32 v158, v158, v159
	v_rcp_f32_e32 v158, v158
	v_lshlrev_b32_e32 v159, 16, v171
	v_and_b32_e32 v171, 0xffff0000, v171
	v_mul_f32_e32 v138, 0xbfb8aa3b, v138
	v_mul_f32_e32 v158, v170, v158
	v_cvt_pk_bf16_f32 v158, v184, v158
	v_exp_f32_e32 v184, v164
	v_mul_f32_e32 v164, 0xbfb8aa3b, v159
	v_exp_f32_e32 v185, v164
	v_lshlrev_b32_e32 v170, 16, v175
	v_mul_f32_e32 v159, v170, v159
	v_and_b32_e32 v170, 0xffff0000, v175
	v_pk_add_f32 v[184:185], v[184:185], 1.0 op_sel_hi:[1,0]
	v_mul_f32_e32 v170, v170, v171
	v_mul_f32_e32 v164, v184, v185
	v_rcp_f32_e32 v164, v164
	v_pk_add_f32 v[140:141], v[140:141], v[104:105]
	v_mul_f32_e32 v134, 0xbfb8aa3b, v134
	v_mul_f32_e32 v140, 0xbfb8aa3b, v140
; __device__ __forceinline__ unsigned cvt_pk_bf16(float lo, float hi) { unsigned r; asm volatile("v_cvt_pk_bf16_f32 %0, %1, %2" : "=v"(r) : "v"(lo), "v"(hi)); return r; }
; __device__ __forceinline__ float bf_lo(unsigned w) { return __uint_as_float(w << 16); }
; __device__ __forceinline__ float bf_hi(unsigned w) { return __uint_as_float(w & 0xffff0000u); }
;     __device__ __forceinline__ void operator()(const f32x4 (&acc)[2][2][4][2], const Unit& u, int wr, int wc, int fr, int fq, const Pre&) const {
;     ...
;         for (int bj = 0; bj < 2; ++bj) { const int c = col0 + bj * HALF;
; #pragma unroll
;             for (int ai = 0; ai < 2; ++ai) { u32x4 zv[4], gv[4];
; #pragma unroll
;                 for (int m = 0; m < 4; ++m) { const int r = row0 + ai * HALF + m * 16; zv[m] = *(const u32x4*)(Z + (size_t)r * DE2 + c); gv[m] = *(const u32x4*)(Gm + (size_t)(c >> 4) * GSTR + r * 16 + (c & 15)); }
; #pragma unroll
;                 for (int m = 0; m < 4; ++m) { const int r = row0 + ai * HALF + m * 16;
;                     const u32x4 zw = zv[m], gw = gv[m];
;                     const f32x4 a0 = acc[ai][bj][m][0] + bs[bj][0], a1 = acc[ai][bj][m][1] + bs[bj][1];
;                     u32x4 w;
;                     w.x = cvt_pk_bf16(glu_gate_f(bf_lo(gw.x), a0[0], bf_lo(zw.x)), glu_gate_f(bf_hi(gw.x), a0[1], bf_hi(zw.x)));
;                     w.y = cvt_pk_bf16(glu_gate_f(bf_lo(gw.y), a0[2], bf_lo(zw.y)), glu_gate_f(bf_hi(gw.y), a0[3], bf_hi(zw.y)));
;                     w.z = cvt_pk_bf16(glu_gate_f(bf_lo(gw.z), a1[0], bf_lo(zw.z)), glu_gate_f(bf_hi(gw.z), a1[1], bf_hi(zw.z)));
;                     w.w = cvt_pk_bf16(glu_gate_f(bf_lo(gw.w), a1[2], bf_lo(zw.w)), glu_gate_f(bf_hi(gw.w), a1[3], bf_hi(zw.w)));
;                     *(u32x4*)(O + (size_t)r * DE + c) = w; } } }
	v_mul_f32_e32 v159, v159, v164
	v_mul_f32_e32 v164, 0xbfb8aa3b, v165
	v_mul_f32_e32 v165, 0xbfb8aa3b, v171
	v_exp_f32_e32 v164, v164
	v_exp_f32_e32 v165, v165
	v_lshlrev_b32_e32 v171, 16, v176
	v_pk_add_f32 v[136:137], v[136:137], v[100:101]
	v_pk_add_f32 v[126:127], v[126:127], v[102:103]
	v_pk_add_f32 v[164:165], v[164:165], 1.0 op_sel_hi:[1,0]
	v_mul_f32_e32 v126, 0xbfb8aa3b, v126
	v_mul_f32_e32 v164, v164, v165
	v_rcp_f32_e32 v164, v164
	v_pk_add_f32 v[128:129], v[128:129], v[104:105]
	v_pk_add_f32 v[122:123], v[122:123], v[98:99]
	v_mul_f32_e32 v128, 0xbfb8aa3b, v128
	v_mul_f32_e32 v164, v170, v164
	v_lshlrev_b32_e32 v170, 16, v172
	v_cvt_pk_bf16_f32 v159, v159, v164
	v_exp_f32_e32 v164, v160
	v_mul_f32_e32 v160, 0xbfb8aa3b, v170
	v_exp_f32_e32 v165, v160
	v_mul_f32_e32 v160, v171, v170
	v_and_b32_e32 v170, 0xffff0000, v172
	v_mul_f32_e32 v122, 0xbfb8aa3b, v122
	v_pk_add_f32 v[164:165], v[164:165], 1.0 op_sel_hi:[1,0]
	v_pk_add_f32 v[124:125], v[124:125], v[100:101]
	v_mul_f32_e32 v164, v164, v165
	v_rcp_f32_e32 v164, v164
	v_and_b32_e32 v165, 0xffff0000, v176
	v_mul_f32_e32 v165, v165, v170
	v_pk_add_f32 v[118:119], v[118:119], v[102:103]
	v_mul_f32_e32 v164, v160, v164
	v_mul_f32_e32 v160, 0xbfb8aa3b, v161
	v_mul_f32_e32 v161, 0xbfb8aa3b, v170
	v_exp_f32_e32 v160, v160
	v_exp_f32_e32 v161, v161
	v_lshlrev_b32_e32 v170, 16, v177
	v_mul_f32_e32 v118, 0xbfb8aa3b, v118
	v_pk_add_f32 v[120:121], v[120:121], v[104:105]
	v_pk_add_f32 v[160:161], v[160:161], 1.0 op_sel_hi:[1,0]
	v_mul_f32_e32 v120, 0xbfb8aa3b, v120
	v_mul_f32_e32 v160, v160, v161
	v_rcp_f32_e32 v160, v160
	v_lshlrev_b32_e32 v161, 16, v173
	v_pk_add_f32 v[114:115], v[114:115], v[98:99]
	v_pk_add_f32 v[116:117], v[116:117], v[100:101]
	v_mul_f32_e32 v160, v165, v160
	v_cvt_pk_bf16_f32 v160, v164, v160
	v_exp_f32_e32 v164, v162
	v_mul_f32_e32 v162, 0xbfb8aa3b, v161
	v_exp_f32_e32 v165, v162
	v_mul_f32_e32 v161, v170, v161
	v_mul_f32_e32 v114, 0xbfb8aa3b, v114
	v_add_u32_e32 v176, 0x80, v224
	v_pk_add_f32 v[164:165], v[164:165], 1.0 op_sel_hi:[1,0]
	v_add_u32_e32 v170, 0xb0, v224
	v_mul_f32_e32 v162, v164, v165
	v_rcp_f32_e32 v162, v162
	v_and_b32_e32 v165, 0xffff0000, v173
	v_and_b32_e32 v164, 0xffff0000, v177
	v_mul_f32_e32 v164, v164, v165
	v_mul_f32_e32 v161, v161, v162
	v_mul_f32_e32 v162, 0xbfb8aa3b, v163
	v_mul_f32_e32 v163, 0xbfb8aa3b, v165
	v_exp_f32_e32 v162, v162
	v_exp_f32_e32 v163, v163
	v_ashrrev_i32_e32 v177, 31, v176
	v_pk_add_f32 v[110:111], v[110:111], v[102:103]
	v_add_u32_e32 v174, 0x90, v224
	v_pk_add_f32 v[162:163], v[162:163], 1.0 op_sel_hi:[1,0]
	v_mul_f32_e32 v110, 0xbfb8aa3b, v110
	v_mul_f32_e32 v162, v162, v163
	v_rcp_f32_e32 v162, v162
	v_exp_f32_e32 v184, v110
	v_ashrrev_i32_e32 v175, 31, v174
	v_add_u32_e32 v172, 0xa0, v224
	v_mul_f32_e32 v162, v164, v162
	v_cvt_pk_bf16_f32 v161, v161, v162
	v_lshlrev_b64 v[162:163], 13, v[224:225]
	v_lshl_add_u64 v[162:163], s[44:45], 0, v[162:163]
	v_lshl_add_u64 v[162:163], v[162:163], 0, v[204:205]
	global_store_dwordx4 v[162:163], v[158:161], off
	v_ashrrev_i32_e32 v173, 31, v172
	v_ashrrev_i32_e32 v171, 31, v170
	v_lshlrev_b32_e32 v160, 16, v154
	v_exp_f32_e32 v158, v138
	v_mul_f32_e32 v138, 0xbfb8aa3b, v160
	v_exp_f32_e32 v159, v138
	v_lshlrev_b32_e32 v161, 16, v166
	v_mul_f32_e32 v138, v161, v160
	v_and_b32_e32 v154, 0xffff0000, v154
	v_pk_add_f32 v[158:159], v[158:159], 1.0 op_sel_hi:[1,0]
	v_lshlrev_b64 v[160:161], 14, v[172:173]
	v_mul_f32_e32 v158, v158, v159
	v_rcp_f32_e32 v158, v158
	v_and_b32_e32 v159, 0xffff0000, v166
	v_pk_add_f32 v[112:113], v[112:113], v[104:105]
	v_pk_add_f32 v[106:107], v[106:107], v[98:99]
	v_mul_f32_e32 v158, v138, v158
	v_mul_f32_e32 v138, 0xbfb8aa3b, v139
	v_mul_f32_e32 v139, 0xbfb8aa3b, v154
	v_exp_f32_e32 v138, v138
	v_exp_f32_e32 v139, v139
	v_mul_f32_e32 v154, v159, v154
	v_mul_f32_e32 v112, 0xbfb8aa3b, v112
	v_mul_f32_e32 v106, 0xbfb8aa3b, v106
	v_pk_add_f32 v[138:139], v[138:139], 1.0 op_sel_hi:[1,0]
	v_pk_add_f32 v[108:109], v[108:109], v[100:101]
	v_mul_f32_e32 v138, v138, v139
	v_rcp_f32_e32 v138, v138
	v_lshlrev_b32_e32 v139, 16, v155
	v_and_b32_e32 v155, 0xffff0000, v155
	v_pk_add_f32 v[94:95], v[94:95], v[102:103]
	v_mul_f32_e32 v138, v154, v138
	v_cvt_pk_bf16_f32 v138, v158, v138
	v_exp_f32_e32 v158, v140
	v_mul_f32_e32 v140, 0xbfb8aa3b, v139
	v_exp_f32_e32 v159, v140
	v_lshlrev_b32_e32 v154, 16, v167
	v_mul_f32_e32 v139, v154, v139
	v_and_b32_e32 v154, 0xffff0000, v167
	v_pk_add_f32 v[158:159], v[158:159], 1.0 op_sel_hi:[1,0]
	v_mul_f32_e32 v154, v154, v155
	v_mul_f32_e32 v140, v158, v159
	v_rcp_f32_e32 v140, v140
	v_lshlrev_b64 v[166:167], 14, v[170:171]
	v_mul_f32_e32 v94, 0xbfb8aa3b, v94
	v_pk_add_f32 v[96:97], v[96:97], v[104:105]
	v_mul_f32_e32 v139, v139, v140
	v_mul_f32_e32 v140, 0xbfb8aa3b, v141
	v_mul_f32_e32 v141, 0xbfb8aa3b, v155
	v_exp_f32_e32 v140, v140
	v_exp_f32_e32 v141, v141
	v_lshlrev_b32_e32 v155, 16, v168
	v_mul_f32_e32 v96, 0xbfb8aa3b, v96
	v_pk_add_f32 v[90:91], v[90:91], v[98:99]
	v_pk_add_f32 v[140:141], v[140:141], 1.0 op_sel_hi:[1,0]
	v_mul_f32_e32 v90, 0xbfb8aa3b, v90
	v_mul_f32_e32 v140, v140, v141
	v_rcp_f32_e32 v140, v140
	v_pk_add_f32 v[92:93], v[92:93], v[100:101]
	v_pk_add_f32 v[86:87], v[86:87], v[102:103]
	v_pk_add_f32 v[88:89], v[88:89], v[104:105]
	v_mul_f32_e32 v140, v154, v140
	v_lshlrev_b32_e32 v154, 16, v156
	v_cvt_pk_bf16_f32 v139, v139, v140
	v_exp_f32_e32 v140, v134
	v_mul_f32_e32 v134, 0xbfb8aa3b, v154
	v_exp_f32_e32 v141, v134
	v_mul_f32_e32 v134, v155, v154
	v_and_b32_e32 v154, 0xffff0000, v156
	v_mul_f32_e32 v86, 0xbfb8aa3b, v86
	v_pk_add_f32 v[140:141], v[140:141], 1.0 op_sel_hi:[1,0]
	v_mul_f32_e32 v88, 0xbfb8aa3b, v88
; __device__ __forceinline__ unsigned cvt_pk_bf16(float lo, float hi) { unsigned r; asm volatile("v_cvt_pk_bf16_f32 %0, %1, %2" : "=v"(r) : "v"(lo), "v"(hi)); return r; }
; __device__ __forceinline__ float bf_lo(unsigned w) { return __uint_as_float(w << 16); }
; __device__ __forceinline__ float bf_hi(unsigned w) { return __uint_as_float(w & 0xffff0000u); }
;     __device__ __forceinline__ void operator()(const f32x4 (&acc)[2][2][4][2], const Unit& u, int wr, int wc, int fr, int fq, const Pre&) const {
;     ...
;         for (int bj = 0; bj < 2; ++bj) { const int c = col0 + bj * HALF;
; #pragma unroll
;             for (int ai = 0; ai < 2; ++ai) { u32x4 zv[4], gv[4];
; #pragma unroll
;                 for (int m = 0; m < 4; ++m) { const int r = row0 + ai * HALF + m * 16; zv[m] = *(const u32x4*)(Z + (size_t)r * DE2 + c); gv[m] = *(const u32x4*)(Gm + (size_t)(c >> 4) * GSTR + r * 16 + (c & 15)); }
; #pragma unroll
;                 for (int m = 0; m < 4; ++m) { const int r = row0 + ai * HALF + m * 16;
;                     const u32x4 zw = zv[m], gw = gv[m];
;                     const f32x4 a0 = acc[ai][bj][m][0] + bs[bj][0], a1 = acc[ai][bj][m][1] + bs[bj][1];
;                     u32x4 w;
;                     w.x = cvt_pk_bf16(glu_gate_f(bf_lo(gw.x), a0[0], bf_lo(zw.x)), glu_gate_f(bf_hi(gw.x), a0[1], bf_hi(zw.x)));
;                     w.y = cvt_pk_bf16(glu_gate_f(bf_lo(gw.y), a0[2], bf_lo(zw.y)), glu_gate_f(bf_hi(gw.y), a0[3], bf_hi(zw.y)));
;                     w.z = cvt_pk_bf16(glu_gate_f(bf_lo(gw.z), a1[0], bf_lo(zw.z)), glu_gate_f(bf_hi(gw.z), a1[1], bf_hi(zw.z)));
;                     w.w = cvt_pk_bf16(glu_gate_f(bf_lo(gw.w), a1[2], bf_lo(zw.w)), glu_gate_f(bf_hi(gw.w), a1[3], bf_hi(zw.w)));
;                     *(u32x4*)(O + (size_t)r * DE + c) = w; } } }
	v_mul_f32_e32 v140, v140, v141
	v_rcp_f32_e32 v140, v140
	v_and_b32_e32 v141, 0xffff0000, v168
	v_mul_f32_e32 v141, v141, v154
	v_pk_add_f32 v[82:83], v[82:83], v[98:99]
	v_mul_f32_e32 v140, v134, v140
	v_mul_f32_e32 v134, 0xbfb8aa3b, v135
	v_mul_f32_e32 v135, 0xbfb8aa3b, v154
	v_exp_f32_e32 v134, v134
	v_exp_f32_e32 v135, v135
	v_lshlrev_b32_e32 v154, 16, v169
	v_mul_f32_e32 v82, 0xbfb8aa3b, v82
	v_pk_add_f32 v[84:85], v[84:85], v[100:101]
	v_pk_add_f32 v[134:135], v[134:135], 1.0 op_sel_hi:[1,0]
	v_pk_add_f32 v[78:79], v[78:79], v[102:103]
	v_mul_f32_e32 v134, v134, v135
	v_rcp_f32_e32 v134, v134
	v_mul_f32_e32 v78, 0xbfb8aa3b, v78
	v_pk_add_f32 v[80:81], v[80:81], v[104:105]
	v_pk_add_f32 v[74:75], v[74:75], v[98:99]
	v_mul_f32_e32 v134, v141, v134
	v_lshlrev_b32_e32 v141, 16, v157
	v_cvt_pk_bf16_f32 v140, v140, v134
	v_mul_f32_e32 v134, 0xbfb8aa3b, v136
	v_mul_f32_e32 v135, 0xbfb8aa3b, v141
	v_exp_f32_e32 v134, v134
	v_exp_f32_e32 v135, v135
	v_mul_f32_e32 v136, v154, v141
	v_and_b32_e32 v154, 0xffff0000, v157
	v_and_b32_e32 v141, 0xffff0000, v169
	v_pk_add_f32 v[134:135], v[134:135], 1.0 op_sel_hi:[1,0]
	v_lshlrev_b64 v[156:157], 14, v[174:175]
	v_mul_f32_e32 v134, v134, v135
	v_rcp_f32_e32 v134, v134
	v_mul_f32_e32 v135, 0xbfb8aa3b, v154
	v_exp_f32_e32 v135, v135
	v_mul_f32_e32 v80, 0xbfb8aa3b, v80
	v_mul_f32_e32 v136, v136, v134
	v_mul_f32_e32 v134, 0xbfb8aa3b, v137
	v_exp_f32_e32 v134, v134
	v_mul_f32_e32 v137, v141, v154
	v_mul_f32_e32 v74, 0xbfb8aa3b, v74
	v_pk_add_f32 v[76:77], v[76:77], v[100:101]
	v_pk_add_f32 v[134:135], v[134:135], 1.0 op_sel_hi:[1,0]
	v_pk_add_f32 v[70:71], v[70:71], v[30:31]
	v_mul_f32_e32 v134, v134, v135
	v_rcp_f32_e32 v134, v134
	v_mul_f32_e32 v70, 0xbfb8aa3b, v70
	v_pk_add_f32 v[72:73], v[72:73], v[32:33]
	v_pk_add_f32 v[66:67], v[66:67], v[26:27]
	v_mul_f32_e32 v134, v137, v134
	v_cvt_pk_bf16_f32 v141, v136, v134
	v_lshlrev_b64 v[134:135], 13, v[230:231]
	v_lshl_add_u64 v[134:135], s[44:45], 0, v[134:135]
	v_lshlrev_b32_e32 v136, 16, v146
	v_lshl_add_u64 v[154:155], v[134:135], 0, v[204:205]
	v_exp_f32_e32 v134, v126
	v_mul_f32_e32 v126, 0xbfb8aa3b, v136
	v_exp_f32_e32 v135, v126
	v_lshlrev_b32_e32 v137, 16, v150
	v_mul_f32_e32 v126, v137, v136
	v_and_b32_e32 v136, 0xffff0000, v146
	v_pk_add_f32 v[134:135], v[134:135], 1.0 op_sel_hi:[1,0]
	global_store_dwordx4 v[154:155], v[138:141], off
	v_mul_f32_e32 v134, v134, v135
	v_rcp_f32_e32 v134, v134
	v_and_b32_e32 v135, 0xffff0000, v150
	v_mul_f32_e32 v135, v135, v136
	v_mul_f32_e32 v72, 0xbfb8aa3b, v72
	v_mul_f32_e32 v134, v126, v134
	v_mul_f32_e32 v126, 0xbfb8aa3b, v127
	v_mul_f32_e32 v127, 0xbfb8aa3b, v136
	v_exp_f32_e32 v126, v126
	v_exp_f32_e32 v127, v127
	v_lshlrev_b32_e32 v136, 16, v151
	v_mul_f32_e32 v66, 0xbfb8aa3b, v66
	v_pk_add_f32 v[68:69], v[68:69], v[28:29]
	v_pk_add_f32 v[126:127], v[126:127], 1.0 op_sel_hi:[1,0]
	v_pk_add_f32 v[62:63], v[62:63], v[30:31]
	v_mul_f32_e32 v126, v126, v127
	v_rcp_f32_e32 v126, v126
	v_lshlrev_b32_e32 v127, 16, v147
	v_mul_f32_e32 v62, 0xbfb8aa3b, v62
	v_pk_add_f32 v[64:65], v[64:65], v[32:33]
	v_mul_f32_e32 v126, v135, v126
	v_cvt_pk_bf16_f32 v126, v134, v126
	v_exp_f32_e32 v134, v128
	v_mul_f32_e32 v128, 0xbfb8aa3b, v127
	v_exp_f32_e32 v135, v128
	v_mul_f32_e32 v127, v136, v127
	v_mul_f32_e32 v64, 0xbfb8aa3b, v64
	v_pk_add_f32 v[58:59], v[58:59], v[26:27]
	v_pk_add_f32 v[134:135], v[134:135], 1.0 op_sel_hi:[1,0]
	v_mul_f32_e32 v58, 0xbfb8aa3b, v58
	v_mul_f32_e32 v128, v134, v135
	v_rcp_f32_e32 v128, v128
	v_and_b32_e32 v135, 0xffff0000, v147
	v_and_b32_e32 v134, 0xffff0000, v151
	v_mul_f32_e32 v134, v134, v135
	v_mul_f32_e32 v127, v127, v128
	v_mul_f32_e32 v128, 0xbfb8aa3b, v129
	v_mul_f32_e32 v129, 0xbfb8aa3b, v135
	v_exp_f32_e32 v128, v128
	v_exp_f32_e32 v129, v129
	v_lshlrev_b32_e32 v135, 16, v152
	v_lshlrev_b64 v[150:151], 14, v[176:177]
	v_pk_add_f32 v[60:61], v[60:61], v[28:29]
	v_pk_add_f32 v[128:129], v[128:129], 1.0 op_sel_hi:[1,0]
	v_pk_add_f32 v[54:55], v[54:55], v[30:31]
	v_mul_f32_e32 v128, v128, v129
	v_rcp_f32_e32 v128, v128
	v_mul_f32_e32 v54, 0xbfb8aa3b, v54
	v_pk_add_f32 v[56:57], v[56:57], v[32:33]
	v_pk_add_f32 v[50:51], v[50:51], v[26:27]
	v_mul_f32_e32 v128, v134, v128
	v_lshlrev_b32_e32 v134, 16, v148
	v_cvt_pk_bf16_f32 v127, v127, v128
	v_exp_f32_e32 v128, v122
	v_mul_f32_e32 v122, 0xbfb8aa3b, v134
	v_exp_f32_e32 v129, v122
	v_mul_f32_e32 v122, v135, v134
	v_and_b32_e32 v134, 0xffff0000, v148
	v_mul_f32_e32 v56, 0xbfb8aa3b, v56
	v_pk_add_f32 v[128:129], v[128:129], 1.0 op_sel_hi:[1,0]
	v_mul_f32_e32 v50, 0xbfb8aa3b, v50
	v_mul_f32_e32 v128, v128, v129
	v_rcp_f32_e32 v128, v128
	v_and_b32_e32 v129, 0xffff0000, v152
	v_mul_f32_e32 v129, v129, v134
	v_pk_add_f32 v[52:53], v[52:53], v[28:29]
	v_mul_f32_e32 v128, v122, v128
	v_mul_f32_e32 v122, 0xbfb8aa3b, v123
	v_mul_f32_e32 v123, 0xbfb8aa3b, v134
	v_exp_f32_e32 v122, v122
	v_exp_f32_e32 v123, v123
	v_lshlrev_b32_e32 v134, 16, v153
	v_pk_add_f32 v[46:47], v[46:47], v[30:31]
	v_pk_add_f32 v[48:49], v[48:49], v[32:33]
	v_pk_add_f32 v[122:123], v[122:123], 1.0 op_sel_hi:[1,0]
	v_mul_f32_e32 v46, 0xbfb8aa3b, v46
	v_mul_f32_e32 v122, v122, v123
	v_rcp_f32_e32 v122, v122
	v_mul_f32_e32 v48, 0xbfb8aa3b, v48
	v_pk_add_f32 v[42:43], v[42:43], v[26:27]
	v_pk_add_f32 v[44:45], v[44:45], v[28:29]
	v_mul_f32_e32 v122, v129, v122
	v_lshlrev_b32_e32 v129, 16, v149
	v_cvt_pk_bf16_f32 v128, v128, v122
	v_mul_f32_e32 v122, 0xbfb8aa3b, v124
	v_mul_f32_e32 v123, 0xbfb8aa3b, v129
	v_exp_f32_e32 v122, v122
	v_exp_f32_e32 v123, v123
	v_mul_f32_e32 v124, v134, v129
	v_and_b32_e32 v134, 0xffff0000, v149
	v_and_b32_e32 v129, 0xffff0000, v153
; __device__ __forceinline__ unsigned cvt_pk_bf16(float lo, float hi) { unsigned r; asm volatile("v_cvt_pk_bf16_f32 %0, %1, %2" : "=v"(r) : "v"(lo), "v"(hi)); return r; }
; __device__ __forceinline__ float bf_lo(unsigned w) { return __uint_as_float(w << 16); }
; __device__ __forceinline__ float bf_hi(unsigned w) { return __uint_as_float(w & 0xffff0000u); }
;     __device__ __forceinline__ void operator()(const f32x4 (&acc)[2][2][4][2], const Unit& u, int wr, int wc, int fr, int fq, const Pre&) const {
;     ...
;         for (int bj = 0; bj < 2; ++bj) { const int c = col0 + bj * HALF;
; #pragma unroll
;             for (int ai = 0; ai < 2; ++ai) { u32x4 zv[4], gv[4];
; #pragma unroll
;                 for (int m = 0; m < 4; ++m) { const int r = row0 + ai * HALF + m * 16; zv[m] = *(const u32x4*)(Z + (size_t)r * DE2 + c); gv[m] = *(const u32x4*)(Gm + (size_t)(c >> 4) * GSTR + r * 16 + (c & 15)); }
; #pragma unroll
;                 for (int m = 0; m < 4; ++m) { const int r = row0 + ai * HALF + m * 16;
;                     const u32x4 zw = zv[m], gw = gv[m];
;                     const f32x4 a0 = acc[ai][bj][m][0] + bs[bj][0], a1 = acc[ai][bj][m][1] + bs[bj][1];
;                     u32x4 w;
;                     w.x = cvt_pk_bf16(glu_gate_f(bf_lo(gw.x), a0[0], bf_lo(zw.x)), glu_gate_f(bf_hi(gw.x), a0[1], bf_hi(zw.x)));
;                     w.y = cvt_pk_bf16(glu_gate_f(bf_lo(gw.y), a0[2], bf_lo(zw.y)), glu_gate_f(bf_hi(gw.y), a0[3], bf_hi(zw.y)));
;                     w.z = cvt_pk_bf16(glu_gate_f(bf_lo(gw.z), a1[0], bf_lo(zw.z)), glu_gate_f(bf_hi(gw.z), a1[1], bf_hi(zw.z)));
;                     w.w = cvt_pk_bf16(glu_gate_f(bf_lo(gw.w), a1[2], bf_lo(zw.w)), glu_gate_f(bf_hi(gw.w), a1[3], bf_hi(zw.w)));
;                     *(u32x4*)(O + (size_t)r * DE + c) = w; } } }
	v_pk_add_f32 v[122:123], v[122:123], 1.0 op_sel_hi:[1,0]
	v_mul_f32_e32 v42, 0xbfb8aa3b, v42
	v_mul_f32_e32 v122, v122, v123
	v_rcp_f32_e32 v122, v122
	v_mul_f32_e32 v123, 0xbfb8aa3b, v134
	v_exp_f32_e32 v123, v123
	v_pk_add_f32 v[38:39], v[38:39], v[30:31]
	v_mul_f32_e32 v124, v124, v122
	v_mul_f32_e32 v122, 0xbfb8aa3b, v125
	v_exp_f32_e32 v122, v122
	v_mul_f32_e32 v125, v129, v134
	v_mul_f32_e32 v38, 0xbfb8aa3b, v38
	v_pk_add_f32 v[40:41], v[40:41], v[32:33]
	v_pk_add_f32 v[122:123], v[122:123], 1.0 op_sel_hi:[1,0]
	v_mul_f32_e32 v40, 0xbfb8aa3b, v40
	v_mul_f32_e32 v122, v122, v123
	v_rcp_f32_e32 v122, v122
	v_pk_add_f32 v[34:35], v[34:35], v[26:27]
	v_pk_add_f32 v[36:37], v[36:37], v[28:29]
	v_mul_f32_e32 v34, 0xbfb8aa3b, v34
	v_mul_f32_e32 v122, v125, v122
	v_cvt_pk_bf16_f32 v129, v124, v122
	v_lshlrev_b64 v[122:123], 13, v[228:229]
	v_lshl_add_u64 v[122:123], s[44:45], 0, v[122:123]
	v_lshlrev_b32_e32 v124, 16, v130
	v_lshl_add_u64 v[146:147], v[122:123], 0, v[204:205]
	v_exp_f32_e32 v122, v118
	v_mul_f32_e32 v118, 0xbfb8aa3b, v124
	v_exp_f32_e32 v123, v118
	v_lshlrev_b32_e32 v125, 16, v142
	v_mul_f32_e32 v118, v125, v124
	v_and_b32_e32 v124, 0xffff0000, v130
	v_pk_add_f32 v[122:123], v[122:123], 1.0 op_sel_hi:[1,0]
	global_store_dwordx4 v[146:147], v[126:129], off
	v_mul_f32_e32 v122, v122, v123
	v_rcp_f32_e32 v122, v122
	v_and_b32_e32 v123, 0xffff0000, v142
	v_mul_f32_e32 v123, v123, v124
	v_pk_add_f32 v[22:23], v[22:23], v[30:31]
	v_mul_f32_e32 v122, v118, v122
	v_mul_f32_e32 v118, 0xbfb8aa3b, v119
	v_mul_f32_e32 v119, 0xbfb8aa3b, v124
	v_exp_f32_e32 v118, v118
	v_exp_f32_e32 v119, v119
	v_lshlrev_b32_e32 v124, 16, v143
	v_mul_f32_e32 v22, 0xbfb8aa3b, v22
	v_pk_add_f32 v[24:25], v[24:25], v[32:33]
	v_pk_add_f32 v[118:119], v[118:119], 1.0 op_sel_hi:[1,0]
	v_mul_f32_e32 v24, 0xbfb8aa3b, v24
	v_mul_f32_e32 v118, v118, v119
	v_rcp_f32_e32 v118, v118
	v_lshlrev_b32_e32 v119, 16, v131
	v_pk_add_f32 v[18:19], v[18:19], v[26:27]
	v_pk_add_f32 v[20:21], v[20:21], v[28:29]
	v_mul_f32_e32 v118, v123, v118
	v_cvt_pk_bf16_f32 v118, v122, v118
	v_exp_f32_e32 v122, v120
	v_mul_f32_e32 v120, 0xbfb8aa3b, v119
	v_exp_f32_e32 v123, v120
	v_mul_f32_e32 v119, v124, v119
	v_mul_f32_e32 v18, 0xbfb8aa3b, v18
	v_pk_add_f32 v[14:15], v[14:15], v[30:31]
	v_pk_add_f32 v[122:123], v[122:123], 1.0 op_sel_hi:[1,0]
	v_mul_f32_e32 v14, 0xbfb8aa3b, v14
	v_mul_f32_e32 v120, v122, v123
	v_rcp_f32_e32 v120, v120
	v_and_b32_e32 v123, 0xffff0000, v131
	v_and_b32_e32 v122, 0xffff0000, v143
	v_mul_f32_e32 v122, v122, v123
	v_mul_f32_e32 v119, v119, v120
	v_mul_f32_e32 v120, 0xbfb8aa3b, v121
	v_mul_f32_e32 v121, 0xbfb8aa3b, v123
	v_exp_f32_e32 v120, v120
	v_exp_f32_e32 v121, v121
	v_lshlrev_b32_e32 v123, 16, v144
	v_pk_add_f32 v[16:17], v[16:17], v[32:33]
	v_pk_add_f32 v[10:11], v[10:11], v[26:27]
	v_pk_add_f32 v[120:121], v[120:121], 1.0 op_sel_hi:[1,0]
	v_mul_f32_e32 v16, 0xbfb8aa3b, v16
	v_mul_f32_e32 v120, v120, v121
	v_rcp_f32_e32 v120, v120
	v_mul_f32_e32 v10, 0xbfb8aa3b, v10
	v_pk_add_f32 v[12:13], v[12:13], v[28:29]
	v_pk_add_f32 v[6:7], v[6:7], v[30:31]
	v_mul_f32_e32 v120, v122, v120
	v_lshlrev_b32_e32 v122, 16, v132
	v_cvt_pk_bf16_f32 v119, v119, v120
	v_exp_f32_e32 v120, v114
	v_mul_f32_e32 v114, 0xbfb8aa3b, v122
	v_exp_f32_e32 v121, v114
	v_mul_f32_e32 v114, v123, v122
	v_and_b32_e32 v122, 0xffff0000, v132
	v_mul_f32_e32 v6, 0xbfb8aa3b, v6
	v_pk_add_f32 v[120:121], v[120:121], 1.0 op_sel_hi:[1,0]
	v_pk_add_f32 v[8:9], v[8:9], v[32:33]
	v_mul_f32_e32 v120, v120, v121
	v_rcp_f32_e32 v120, v120
	v_and_b32_e32 v121, 0xffff0000, v144
	v_mul_f32_e32 v121, v121, v122
	v_mul_f32_e32 v8, 0xbfb8aa3b, v8
	v_mul_f32_e32 v120, v114, v120
	v_mul_f32_e32 v114, 0xbfb8aa3b, v115
	v_mul_f32_e32 v115, 0xbfb8aa3b, v122
	v_exp_f32_e32 v114, v114
	v_exp_f32_e32 v115, v115
	v_lshlrev_b32_e32 v122, 16, v145
	v_pk_add_f32 v[2:3], v[2:3], v[26:27]
	v_pk_add_f32 v[4:5], v[4:5], v[28:29]
	v_pk_add_f32 v[114:115], v[114:115], 1.0 op_sel_hi:[1,0]
	v_mul_f32_e32 v2, 0xbfb8aa3b, v2
	v_mul_f32_e32 v114, v114, v115
	v_rcp_f32_e32 v114, v114
	s_nop 0
	v_mul_f32_e32 v114, v121, v114
	v_lshlrev_b32_e32 v121, 16, v133
	v_cvt_pk_bf16_f32 v120, v120, v114
	v_mul_f32_e32 v114, 0xbfb8aa3b, v116
	v_mul_f32_e32 v115, 0xbfb8aa3b, v121
	v_exp_f32_e32 v114, v114
	v_exp_f32_e32 v115, v115
	v_mul_f32_e32 v116, v122, v121
	v_and_b32_e32 v122, 0xffff0000, v133
	v_and_b32_e32 v121, 0xffff0000, v145
	v_pk_add_f32 v[114:115], v[114:115], 1.0 op_sel_hi:[1,0]
	s_nop 0
	v_mul_f32_e32 v114, v114, v115
	v_rcp_f32_e32 v114, v114
	v_mul_f32_e32 v115, 0xbfb8aa3b, v122
	v_exp_f32_e32 v115, v115
	v_mul_f32_e32 v116, v116, v114
	v_mul_f32_e32 v114, 0xbfb8aa3b, v117
	v_exp_f32_e32 v114, v114
	v_mul_f32_e32 v117, v121, v122
	v_pk_add_f32 v[114:115], v[114:115], 1.0 op_sel_hi:[1,0]
	s_nop 0
	v_mul_f32_e32 v114, v114, v115
	v_rcp_f32_e32 v114, v114
	s_nop 0
	v_mul_f32_e32 v114, v117, v114
	v_cvt_pk_bf16_f32 v121, v116, v114
	v_lshlrev_b64 v[114:115], 13, v[226:227]
	v_lshl_add_u64 v[114:115], s[44:45], 0, v[114:115]
	v_lshl_add_u64 v[148:149], v[114:115], 0, v[204:205]
	global_store_dwordx4 v[148:149], v[118:121], off
	v_lshl_add_u64 v[114:115], v[222:223], 0, v[150:151]
	global_load_dwordx4 v[138:141], v[114:115], off
	v_lshlrev_b32_e32 v118, 4, v170
	v_ashrrev_i32_e32 v119, 31, v118
	v_lshlrev_b64 v[168:169], 1, v[118:119]
	v_lshl_add_u64 v[118:119], v[220:221], 0, v[168:169]
	global_load_dwordx4 v[118:121], v[118:119], off
	v_lshlrev_b32_e32 v114, 4, v176
	v_ashrrev_i32_e32 v115, 31, v114
	v_lshlrev_b64 v[152:153], 1, v[114:115]
	v_lshl_add_u64 v[114:115], v[220:221], 0, v[152:153]
	global_load_dwordx4 v[142:145], v[114:115], off
	v_lshl_add_u64 v[114:115], v[222:223], 0, v[156:157]
	global_load_dwordx4 v[130:133], v[114:115], off
	v_lshlrev_b32_e32 v114, 4, v174
	v_ashrrev_i32_e32 v115, 31, v114
	v_lshlrev_b64 v[158:159], 1, v[114:115]
	v_lshl_add_u64 v[114:115], v[220:221], 0, v[158:159]
	global_load_dwordx4 v[134:137], v[114:115], off
	v_lshl_add_u64 v[114:115], v[222:223], 0, v[160:161]
	global_load_dwordx4 v[122:125], v[114:115], off
	v_lshlrev_b32_e32 v114, 4, v172
	v_ashrrev_i32_e32 v115, 31, v114
	v_lshlrev_b64 v[164:165], 1, v[114:115]
	v_lshl_add_u64 v[114:115], v[220:221], 0, v[164:165]
	global_load_dwordx4 v[126:129], v[114:115], off
	v_lshl_add_u64 v[114:115], v[222:223], 0, v[166:167]
	global_load_dwordx4 v[114:117], v[114:115], off
	s_waitcnt vmcnt(0)
; __device__ __forceinline__ unsigned cvt_pk_bf16(float lo, float hi) { unsigned r; asm volatile("v_cvt_pk_bf16_f32 %0, %1, %2" : "=v"(r) : "v"(lo), "v"(hi)); return r; }
; __device__ __forceinline__ float bf_lo(unsigned w) { return __uint_as_float(w << 16); }
; __device__ __forceinline__ float bf_hi(unsigned w) { return __uint_as_float(w & 0xffff0000u); }
;     __device__ __forceinline__ void operator()(const f32x4 (&acc)[2][2][4][2], const Unit& u, int wr, int wc, int fr, int fq, const Pre&) const {
;     ...
;         for (int bj = 0; bj < 2; ++bj) { const int c = col0 + bj * HALF;
; #pragma unroll
;             for (int ai = 0; ai < 2; ++ai) { u32x4 zv[4], gv[4];
; #pragma unroll
;                 for (int m = 0; m < 4; ++m) { const int r = row0 + ai * HALF + m * 16; zv[m] = *(const u32x4*)(Z + (size_t)r * DE2 + c); gv[m] = *(const u32x4*)(Gm + (size_t)(c >> 4) * GSTR + r * 16 + (c & 15)); }
; #pragma unroll
;                 for (int m = 0; m < 4; ++m) { const int r = row0 + ai * HALF + m * 16;
;                     const u32x4 zw = zv[m], gw = gv[m];
;                     const f32x4 a0 = acc[ai][bj][m][0] + bs[bj][0], a1 = acc[ai][bj][m][1] + bs[bj][1];
;                     u32x4 w;
;                     w.x = cvt_pk_bf16(glu_gate_f(bf_lo(gw.x), a0[0], bf_lo(zw.x)), glu_gate_f(bf_hi(gw.x), a0[1], bf_hi(zw.x)));
;                     w.y = cvt_pk_bf16(glu_gate_f(bf_lo(gw.y), a0[2], bf_lo(zw.y)), glu_gate_f(bf_hi(gw.y), a0[3], bf_hi(zw.y)));
;                     w.z = cvt_pk_bf16(glu_gate_f(bf_lo(gw.z), a1[0], bf_lo(zw.z)), glu_gate_f(bf_hi(gw.z), a1[1], bf_hi(zw.z)));
;                     w.w = cvt_pk_bf16(glu_gate_f(bf_lo(gw.w), a1[2], bf_lo(zw.w)), glu_gate_f(bf_hi(gw.w), a1[3], bf_hi(zw.w)));
;                     *(u32x4*)(O + (size_t)r * DE + c) = w; } } }
	v_lshlrev_b32_e32 v186, 16, v138
	v_mul_f32_e32 v110, 0xbfb8aa3b, v186
	v_exp_f32_e32 v185, v110
	v_and_b32_e32 v138, 0xffff0000, v138
	v_pk_add_f32 v[184:185], v[184:185], 1.0 op_sel_hi:[1,0]
	s_nop 0
	v_mul_f32_e32 v184, v184, v185
	v_rcp_f32_e32 v184, v184
	v_lshlrev_b32_e32 v187, 16, v142
	v_mul_f32_e32 v110, v187, v186
	v_mul_f32_e32 v184, v110, v184
	v_mul_f32_e32 v110, 0xbfb8aa3b, v111
	v_mul_f32_e32 v111, 0xbfb8aa3b, v138
	v_exp_f32_e32 v110, v110
	v_exp_f32_e32 v111, v111
	v_and_b32_e32 v142, 0xffff0000, v142
	v_mul_f32_e32 v138, v142, v138
	v_pk_add_f32 v[110:111], v[110:111], 1.0 op_sel_hi:[1,0]
	s_nop 0
	v_mul_f32_e32 v110, v110, v111
	v_rcp_f32_e32 v110, v110
	v_lshlrev_b32_e32 v111, 16, v139
	v_and_b32_e32 v139, 0xffff0000, v139
	v_mul_f32_e32 v110, v138, v110
	v_cvt_pk_bf16_f32 v110, v184, v110
	v_exp_f32_e32 v184, v112
	v_mul_f32_e32 v112, 0xbfb8aa3b, v111
	v_exp_f32_e32 v185, v112
	v_lshlrev_b32_e32 v138, 16, v143
	v_mul_f32_e32 v111, v138, v111
	v_and_b32_e32 v138, 0xffff0000, v143
	v_pk_add_f32 v[184:185], v[184:185], 1.0 op_sel_hi:[1,0]
	v_mul_f32_e32 v138, v138, v139
	v_mul_f32_e32 v112, v184, v185
	v_rcp_f32_e32 v112, v112
	s_nop 0
	v_mul_f32_e32 v111, v111, v112
	v_mul_f32_e32 v112, 0xbfb8aa3b, v113
	v_mul_f32_e32 v113, 0xbfb8aa3b, v139
	v_exp_f32_e32 v112, v112
	v_exp_f32_e32 v113, v113
	v_lshlrev_b32_e32 v139, 16, v144
	v_pk_add_f32 v[112:113], v[112:113], 1.0 op_sel_hi:[1,0]
	s_nop 0
	v_mul_f32_e32 v112, v112, v113
	v_rcp_f32_e32 v112, v112
	s_nop 0
	v_mul_f32_e32 v112, v138, v112
	v_lshlrev_b32_e32 v138, 16, v140
	v_cvt_pk_bf16_f32 v111, v111, v112
	v_exp_f32_e32 v112, v106
	v_mul_f32_e32 v106, 0xbfb8aa3b, v138
	v_exp_f32_e32 v113, v106
	v_mul_f32_e32 v106, v139, v138
	v_and_b32_e32 v138, 0xffff0000, v140
	v_pk_add_f32 v[112:113], v[112:113], 1.0 op_sel_hi:[1,0]
	s_nop 0
	v_mul_f32_e32 v112, v112, v113
	v_rcp_f32_e32 v112, v112
	v_and_b32_e32 v113, 0xffff0000, v144
	v_mul_f32_e32 v113, v113, v138
	v_mul_f32_e32 v112, v106, v112
	v_mul_f32_e32 v106, 0xbfb8aa3b, v107
	v_mul_f32_e32 v107, 0xbfb8aa3b, v138
	v_exp_f32_e32 v106, v106
	v_exp_f32_e32 v107, v107
	v_lshlrev_b32_e32 v138, 16, v145
	v_pk_add_f32 v[106:107], v[106:107], 1.0 op_sel_hi:[1,0]
	s_nop 0
	v_mul_f32_e32 v106, v106, v107
	v_rcp_f32_e32 v106, v106
	s_nop 0
	v_mul_f32_e32 v106, v113, v106
	v_lshlrev_b32_e32 v113, 16, v141
	v_cvt_pk_bf16_f32 v112, v112, v106
	v_mul_f32_e32 v106, 0xbfb8aa3b, v108
	v_mul_f32_e32 v107, 0xbfb8aa3b, v113
	v_exp_f32_e32 v106, v106
	v_exp_f32_e32 v107, v107
	v_mul_f32_e32 v108, v138, v113
	v_and_b32_e32 v138, 0xffff0000, v141
	v_and_b32_e32 v113, 0xffff0000, v145
	v_pk_add_f32 v[106:107], v[106:107], 1.0 op_sel_hi:[1,0]
	s_nop 0
	v_mul_f32_e32 v106, v106, v107
	v_rcp_f32_e32 v106, v106
	v_mul_f32_e32 v107, 0xbfb8aa3b, v138
	v_exp_f32_e32 v107, v107
	v_mul_f32_e32 v108, v108, v106
	v_mul_f32_e32 v106, 0xbfb8aa3b, v109
	v_exp_f32_e32 v106, v106
	v_mul_f32_e32 v109, v113, v138
	v_pk_add_f32 v[106:107], v[106:107], 1.0 op_sel_hi:[1,0]
	s_nop 0
	v_mul_f32_e32 v106, v106, v107
	v_rcp_f32_e32 v106, v106
	s_nop 0
	v_mul_f32_e32 v106, v109, v106
	v_cvt_pk_bf16_f32 v113, v108, v106
	v_lshlrev_b64 v[106:107], 13, v[176:177]
	v_lshl_add_u64 v[106:107], s[44:45], 0, v[106:107]
	v_lshl_add_u64 v[106:107], v[106:107], 0, v[204:205]
	global_store_dwordx4 v[106:107], v[110:113], off
	v_exp_f32_e32 v108, v94
	s_nop 0
	v_lshlrev_b32_e32 v110, 16, v130
	v_mul_f32_e32 v94, 0xbfb8aa3b, v110
	v_exp_f32_e32 v109, v94
	v_lshlrev_b32_e32 v111, 16, v134
	v_mul_f32_e32 v94, v111, v110
	v_and_b32_e32 v110, 0xffff0000, v130
	v_pk_add_f32 v[108:109], v[108:109], 1.0 op_sel_hi:[1,0]
	s_nop 0
	v_mul_f32_e32 v108, v108, v109
	v_rcp_f32_e32 v108, v108
	v_and_b32_e32 v109, 0xffff0000, v134
	v_mul_f32_e32 v109, v109, v110
	v_mul_f32_e32 v108, v94, v108
	v_mul_f32_e32 v94, 0xbfb8aa3b, v95
	v_mul_f32_e32 v95, 0xbfb8aa3b, v110
	v_exp_f32_e32 v94, v94
	v_exp_f32_e32 v95, v95
	v_lshlrev_b32_e32 v110, 16, v135
	v_pk_add_f32 v[94:95], v[94:95], 1.0 op_sel_hi:[1,0]
	s_nop 0
	v_mul_f32_e32 v94, v94, v95
	v_rcp_f32_e32 v94, v94
	v_lshlrev_b32_e32 v95, 16, v131
	v_mul_f32_e32 v94, v109, v94
	v_cvt_pk_bf16_f32 v94, v108, v94
	v_exp_f32_e32 v108, v96
	v_mul_f32_e32 v96, 0xbfb8aa3b, v95
	v_exp_f32_e32 v109, v96
	v_mul_f32_e32 v95, v110, v95
	v_pk_add_f32 v[108:109], v[108:109], 1.0 op_sel_hi:[1,0]
	s_nop 0
	v_mul_f32_e32 v96, v108, v109
	v_rcp_f32_e32 v96, v96
	v_and_b32_e32 v109, 0xffff0000, v131
	v_and_b32_e32 v108, 0xffff0000, v135
	v_mul_f32_e32 v108, v108, v109
	v_mul_f32_e32 v95, v95, v96
	v_mul_f32_e32 v96, 0xbfb8aa3b, v97
	v_mul_f32_e32 v97, 0xbfb8aa3b, v109
	v_exp_f32_e32 v96, v96
	v_exp_f32_e32 v97, v97
	v_lshlrev_b32_e32 v109, 16, v136
	v_pk_add_f32 v[96:97], v[96:97], 1.0 op_sel_hi:[1,0]
	s_nop 0
	v_mul_f32_e32 v96, v96, v97
	v_rcp_f32_e32 v96, v96
	s_nop 0
	v_mul_f32_e32 v96, v108, v96
	v_lshlrev_b32_e32 v108, 16, v132
	v_cvt_pk_bf16_f32 v95, v95, v96
	v_exp_f32_e32 v96, v90
	v_mul_f32_e32 v90, 0xbfb8aa3b, v108
	v_exp_f32_e32 v97, v90
	v_mul_f32_e32 v90, v109, v108
	v_and_b32_e32 v108, 0xffff0000, v132
	v_pk_add_f32 v[96:97], v[96:97], 1.0 op_sel_hi:[1,0]
	s_nop 0
	v_mul_f32_e32 v96, v96, v97
	v_rcp_f32_e32 v96, v96
	v_and_b32_e32 v97, 0xffff0000, v136
	v_mul_f32_e32 v97, v97, v108
	v_mul_f32_e32 v96, v90, v96
	v_mul_f32_e32 v90, 0xbfb8aa3b, v91
	v_mul_f32_e32 v91, 0xbfb8aa3b, v108
	v_exp_f32_e32 v90, v90
	v_exp_f32_e32 v91, v91
	v_lshlrev_b32_e32 v108, 16, v137
	v_pk_add_f32 v[90:91], v[90:91], 1.0 op_sel_hi:[1,0]
	s_nop 0
	v_mul_f32_e32 v90, v90, v91
	v_rcp_f32_e32 v90, v90
	s_nop 0
	v_mul_f32_e32 v90, v97, v90
	v_lshlrev_b32_e32 v97, 16, v133
; __device__ __forceinline__ unsigned cvt_pk_bf16(float lo, float hi) { unsigned r; asm volatile("v_cvt_pk_bf16_f32 %0, %1, %2" : "=v"(r) : "v"(lo), "v"(hi)); return r; }
; __device__ __forceinline__ float bf_lo(unsigned w) { return __uint_as_float(w << 16); }
; __device__ __forceinline__ float bf_hi(unsigned w) { return __uint_as_float(w & 0xffff0000u); }
;     __device__ __forceinline__ void operator()(const f32x4 (&acc)[2][2][4][2], const Unit& u, int wr, int wc, int fr, int fq, const Pre&) const {
;     ...
;         for (int bj = 0; bj < 2; ++bj) { const int c = col0 + bj * HALF;
; #pragma unroll
;             for (int ai = 0; ai < 2; ++ai) { u32x4 zv[4], gv[4];
; #pragma unroll
;                 for (int m = 0; m < 4; ++m) { const int r = row0 + ai * HALF + m * 16; zv[m] = *(const u32x4*)(Z + (size_t)r * DE2 + c); gv[m] = *(const u32x4*)(Gm + (size_t)(c >> 4) * GSTR + r * 16 + (c & 15)); }
; #pragma unroll
;                 for (int m = 0; m < 4; ++m) { const int r = row0 + ai * HALF + m * 16;
;                     const u32x4 zw = zv[m], gw = gv[m];
;                     const f32x4 a0 = acc[ai][bj][m][0] + bs[bj][0], a1 = acc[ai][bj][m][1] + bs[bj][1];
;                     u32x4 w;
;                     w.x = cvt_pk_bf16(glu_gate_f(bf_lo(gw.x), a0[0], bf_lo(zw.x)), glu_gate_f(bf_hi(gw.x), a0[1], bf_hi(zw.x)));
;                     w.y = cvt_pk_bf16(glu_gate_f(bf_lo(gw.y), a0[2], bf_lo(zw.y)), glu_gate_f(bf_hi(gw.y), a0[3], bf_hi(zw.y)));
;                     w.z = cvt_pk_bf16(glu_gate_f(bf_lo(gw.z), a1[0], bf_lo(zw.z)), glu_gate_f(bf_hi(gw.z), a1[1], bf_hi(zw.z)));
;                     w.w = cvt_pk_bf16(glu_gate_f(bf_lo(gw.w), a1[2], bf_lo(zw.w)), glu_gate_f(bf_hi(gw.w), a1[3], bf_hi(zw.w)));
;                     *(u32x4*)(O + (size_t)r * DE + c) = w; } } }
	v_cvt_pk_bf16_f32 v96, v96, v90
	v_mul_f32_e32 v90, 0xbfb8aa3b, v92
	v_mul_f32_e32 v91, 0xbfb8aa3b, v97
	v_exp_f32_e32 v90, v90
	v_exp_f32_e32 v91, v91
	v_mul_f32_e32 v92, v108, v97
	v_and_b32_e32 v108, 0xffff0000, v133
	v_and_b32_e32 v97, 0xffff0000, v137
	v_pk_add_f32 v[90:91], v[90:91], 1.0 op_sel_hi:[1,0]
	s_nop 0
	v_mul_f32_e32 v90, v90, v91
	v_rcp_f32_e32 v90, v90
	v_mul_f32_e32 v91, 0xbfb8aa3b, v108
	v_exp_f32_e32 v91, v91
	v_mul_f32_e32 v92, v92, v90
	v_mul_f32_e32 v90, 0xbfb8aa3b, v93
	v_exp_f32_e32 v90, v90
	v_mul_f32_e32 v93, v97, v108
	v_pk_add_f32 v[90:91], v[90:91], 1.0 op_sel_hi:[1,0]
	s_nop 0
	v_mul_f32_e32 v90, v90, v91
	v_rcp_f32_e32 v90, v90
	s_nop 0
	v_mul_f32_e32 v90, v93, v90
	v_cvt_pk_bf16_f32 v97, v92, v90
	v_lshlrev_b64 v[90:91], 13, v[174:175]
	v_lshl_add_u64 v[90:91], s[44:45], 0, v[90:91]
	v_lshlrev_b32_e32 v92, 16, v122
	v_lshl_add_u64 v[108:109], v[90:91], 0, v[204:205]
	v_exp_f32_e32 v90, v86
	v_mul_f32_e32 v86, 0xbfb8aa3b, v92
	v_exp_f32_e32 v91, v86
	v_lshlrev_b32_e32 v93, 16, v126
	v_mul_f32_e32 v86, v93, v92
	v_and_b32_e32 v92, 0xffff0000, v122
	v_pk_add_f32 v[90:91], v[90:91], 1.0 op_sel_hi:[1,0]
	global_store_dwordx4 v[108:109], v[94:97], off
	v_mul_f32_e32 v90, v90, v91
	v_rcp_f32_e32 v90, v90
	v_and_b32_e32 v91, 0xffff0000, v126
	v_mul_f32_e32 v91, v91, v92
	v_mul_f32_e32 v90, v86, v90
	v_mul_f32_e32 v86, 0xbfb8aa3b, v87
	v_mul_f32_e32 v87, 0xbfb8aa3b, v92
	v_exp_f32_e32 v86, v86
	v_exp_f32_e32 v87, v87
	v_lshlrev_b32_e32 v92, 16, v127
	v_pk_add_f32 v[86:87], v[86:87], 1.0 op_sel_hi:[1,0]
	s_nop 0
	v_mul_f32_e32 v86, v86, v87
	v_rcp_f32_e32 v86, v86
	v_lshlrev_b32_e32 v87, 16, v123
	v_mul_f32_e32 v86, v91, v86
	v_cvt_pk_bf16_f32 v86, v90, v86
	v_exp_f32_e32 v90, v88
	v_mul_f32_e32 v88, 0xbfb8aa3b, v87
	v_exp_f32_e32 v91, v88
	v_mul_f32_e32 v87, v92, v87
	v_pk_add_f32 v[90:91], v[90:91], 1.0 op_sel_hi:[1,0]
	s_nop 0
	v_mul_f32_e32 v88, v90, v91
	v_rcp_f32_e32 v88, v88
	v_and_b32_e32 v91, 0xffff0000, v123
	v_and_b32_e32 v90, 0xffff0000, v127
	v_mul_f32_e32 v90, v90, v91
	v_mul_f32_e32 v87, v87, v88
	v_mul_f32_e32 v88, 0xbfb8aa3b, v89
	v_mul_f32_e32 v89, 0xbfb8aa3b, v91
	v_exp_f32_e32 v88, v88
	v_exp_f32_e32 v89, v89
	v_lshlrev_b32_e32 v91, 16, v128
	v_pk_add_f32 v[88:89], v[88:89], 1.0 op_sel_hi:[1,0]
	s_nop 0
	v_mul_f32_e32 v88, v88, v89
	v_rcp_f32_e32 v88, v88
	s_nop 0
	v_mul_f32_e32 v88, v90, v88
	v_lshlrev_b32_e32 v90, 16, v124
	v_cvt_pk_bf16_f32 v87, v87, v88
	v_exp_f32_e32 v88, v82
	v_mul_f32_e32 v82, 0xbfb8aa3b, v90
	v_exp_f32_e32 v89, v82
	v_mul_f32_e32 v82, v91, v90
	v_and_b32_e32 v90, 0xffff0000, v124
	v_pk_add_f32 v[88:89], v[88:89], 1.0 op_sel_hi:[1,0]
	s_nop 0
	v_mul_f32_e32 v88, v88, v89
	v_rcp_f32_e32 v88, v88
	v_and_b32_e32 v89, 0xffff0000, v128
	v_mul_f32_e32 v89, v89, v90
	v_mul_f32_e32 v88, v82, v88
	v_mul_f32_e32 v82, 0xbfb8aa3b, v83
	v_mul_f32_e32 v83, 0xbfb8aa3b, v90
	v_exp_f32_e32 v82, v82
	v_exp_f32_e32 v83, v83
	v_lshlrev_b32_e32 v90, 16, v129
	v_pk_add_f32 v[82:83], v[82:83], 1.0 op_sel_hi:[1,0]
	s_nop 0
	v_mul_f32_e32 v82, v82, v83
	v_rcp_f32_e32 v82, v82
	s_nop 0
	v_mul_f32_e32 v82, v89, v82
	v_lshlrev_b32_e32 v89, 16, v125
	v_cvt_pk_bf16_f32 v88, v88, v82
	v_mul_f32_e32 v82, 0xbfb8aa3b, v84
	v_mul_f32_e32 v83, 0xbfb8aa3b, v89
	v_exp_f32_e32 v82, v82
	v_exp_f32_e32 v83, v83
	v_mul_f32_e32 v84, v90, v89
	v_and_b32_e32 v90, 0xffff0000, v125
	v_and_b32_e32 v89, 0xffff0000, v129
	v_pk_add_f32 v[82:83], v[82:83], 1.0 op_sel_hi:[1,0]
	s_nop 0
	v_mul_f32_e32 v82, v82, v83
	v_rcp_f32_e32 v82, v82
	v_mul_f32_e32 v83, 0xbfb8aa3b, v90
	v_exp_f32_e32 v83, v83
	v_mul_f32_e32 v84, v84, v82
	v_mul_f32_e32 v82, 0xbfb8aa3b, v85
	v_exp_f32_e32 v82, v82
	v_mul_f32_e32 v85, v89, v90
	v_pk_add_f32 v[82:83], v[82:83], 1.0 op_sel_hi:[1,0]
	s_nop 0
	v_mul_f32_e32 v82, v82, v83
	v_rcp_f32_e32 v82, v82
	s_nop 0
	v_mul_f32_e32 v82, v85, v82
	v_cvt_pk_bf16_f32 v89, v84, v82
	v_lshlrev_b64 v[82:83], 13, v[172:173]
	v_lshl_add_u64 v[82:83], s[44:45], 0, v[82:83]
	v_lshlrev_b32_e32 v84, 16, v114
	v_lshl_add_u64 v[110:111], v[82:83], 0, v[204:205]
	v_exp_f32_e32 v82, v78
	v_mul_f32_e32 v78, 0xbfb8aa3b, v84
	v_exp_f32_e32 v83, v78
	v_lshlrev_b32_e32 v85, 16, v118
	v_mul_f32_e32 v78, v85, v84
	v_and_b32_e32 v84, 0xffff0000, v114
	v_pk_add_f32 v[82:83], v[82:83], 1.0 op_sel_hi:[1,0]
	global_store_dwordx4 v[110:111], v[86:89], off
	v_mul_f32_e32 v82, v82, v83
	v_rcp_f32_e32 v82, v82
	v_and_b32_e32 v83, 0xffff0000, v118
	v_mul_f32_e32 v83, v83, v84
	v_exp_f32_e32 v118, v70
	v_mul_f32_e32 v82, v78, v82
	v_mul_f32_e32 v78, 0xbfb8aa3b, v79
	v_mul_f32_e32 v79, 0xbfb8aa3b, v84
	v_exp_f32_e32 v78, v78
	v_exp_f32_e32 v79, v79
	v_lshlrev_b32_e32 v84, 16, v119
	v_pk_add_f32 v[78:79], v[78:79], 1.0 op_sel_hi:[1,0]
	s_nop 0
	v_mul_f32_e32 v78, v78, v79
	v_rcp_f32_e32 v78, v78
	v_lshlrev_b32_e32 v79, 16, v115
	v_mul_f32_e32 v78, v83, v78
	v_cvt_pk_bf16_f32 v78, v82, v78
	v_exp_f32_e32 v82, v80
	v_mul_f32_e32 v80, 0xbfb8aa3b, v79
	v_exp_f32_e32 v83, v80
	v_mul_f32_e32 v79, v84, v79
	v_pk_add_f32 v[82:83], v[82:83], 1.0 op_sel_hi:[1,0]
	s_nop 0
	v_mul_f32_e32 v80, v82, v83
	v_rcp_f32_e32 v80, v80
	v_and_b32_e32 v83, 0xffff0000, v115
	v_and_b32_e32 v82, 0xffff0000, v119
	v_mul_f32_e32 v82, v82, v83
	v_mul_f32_e32 v79, v79, v80
	v_mul_f32_e32 v80, 0xbfb8aa3b, v81
	v_mul_f32_e32 v81, 0xbfb8aa3b, v83
	v_exp_f32_e32 v80, v80
	v_exp_f32_e32 v81, v81
	v_lshlrev_b32_e32 v83, 16, v120
	v_pk_add_f32 v[80:81], v[80:81], 1.0 op_sel_hi:[1,0]
	s_nop 0
	v_mul_f32_e32 v80, v80, v81
	v_rcp_f32_e32 v80, v80
	s_nop 0
	v_mul_f32_e32 v80, v82, v80
	v_lshlrev_b32_e32 v82, 16, v116
	v_cvt_pk_bf16_f32 v79, v79, v80
	v_exp_f32_e32 v80, v74
; __device__ __forceinline__ unsigned cvt_pk_bf16(float lo, float hi) { unsigned r; asm volatile("v_cvt_pk_bf16_f32 %0, %1, %2" : "=v"(r) : "v"(lo), "v"(hi)); return r; }
; __device__ __forceinline__ float bf_lo(unsigned w) { return __uint_as_float(w << 16); }
; __device__ __forceinline__ float bf_hi(unsigned w) { return __uint_as_float(w & 0xffff0000u); }
;     __device__ __forceinline__ void operator()(const f32x4 (&acc)[2][2][4][2], const Unit& u, int wr, int wc, int fr, int fq, const Pre&) const {
;     ...
;         for (int bj = 0; bj < 2; ++bj) { const int c = col0 + bj * HALF;
; #pragma unroll
;             for (int ai = 0; ai < 2; ++ai) { u32x4 zv[4], gv[4];
; #pragma unroll
;                 for (int m = 0; m < 4; ++m) { const int r = row0 + ai * HALF + m * 16; zv[m] = *(const u32x4*)(Z + (size_t)r * DE2 + c); gv[m] = *(const u32x4*)(Gm + (size_t)(c >> 4) * GSTR + r * 16 + (c & 15)); }
; #pragma unroll
;                 for (int m = 0; m < 4; ++m) { const int r = row0 + ai * HALF + m * 16;
;                     const u32x4 zw = zv[m], gw = gv[m];
;                     const f32x4 a0 = acc[ai][bj][m][0] + bs[bj][0], a1 = acc[ai][bj][m][1] + bs[bj][1];
;                     u32x4 w;
;                     w.x = cvt_pk_bf16(glu_gate_f(bf_lo(gw.x), a0[0], bf_lo(zw.x)), glu_gate_f(bf_hi(gw.x), a0[1], bf_hi(zw.x)));
;                     w.y = cvt_pk_bf16(glu_gate_f(bf_lo(gw.y), a0[2], bf_lo(zw.y)), glu_gate_f(bf_hi(gw.y), a0[3], bf_hi(zw.y)));
;                     w.z = cvt_pk_bf16(glu_gate_f(bf_lo(gw.z), a1[0], bf_lo(zw.z)), glu_gate_f(bf_hi(gw.z), a1[1], bf_hi(zw.z)));
;                     w.w = cvt_pk_bf16(glu_gate_f(bf_lo(gw.w), a1[2], bf_lo(zw.w)), glu_gate_f(bf_hi(gw.w), a1[3], bf_hi(zw.w)));
;                     *(u32x4*)(O + (size_t)r * DE + c) = w; } } }
	v_mul_f32_e32 v74, 0xbfb8aa3b, v82
	v_exp_f32_e32 v81, v74
	v_mul_f32_e32 v74, v83, v82
	v_and_b32_e32 v82, 0xffff0000, v116
	v_pk_add_f32 v[80:81], v[80:81], 1.0 op_sel_hi:[1,0]
	s_nop 0
	v_mul_f32_e32 v80, v80, v81
	v_rcp_f32_e32 v80, v80
	v_and_b32_e32 v81, 0xffff0000, v120
	v_mul_f32_e32 v81, v81, v82
	v_mul_f32_e32 v80, v74, v80
	v_mul_f32_e32 v74, 0xbfb8aa3b, v75
	v_mul_f32_e32 v75, 0xbfb8aa3b, v82
	v_exp_f32_e32 v74, v74
	v_exp_f32_e32 v75, v75
	v_lshlrev_b32_e32 v82, 16, v121
	v_pk_add_f32 v[74:75], v[74:75], 1.0 op_sel_hi:[1,0]
	s_nop 0
	v_mul_f32_e32 v74, v74, v75
	v_rcp_f32_e32 v74, v74
	s_nop 0
	v_mul_f32_e32 v74, v81, v74
	v_lshlrev_b32_e32 v81, 16, v117
	v_cvt_pk_bf16_f32 v80, v80, v74
	v_mul_f32_e32 v74, 0xbfb8aa3b, v76
	v_mul_f32_e32 v75, 0xbfb8aa3b, v81
	v_exp_f32_e32 v74, v74
	v_exp_f32_e32 v75, v75
	v_mul_f32_e32 v76, v82, v81
	v_and_b32_e32 v82, 0xffff0000, v117
	v_and_b32_e32 v81, 0xffff0000, v121
	v_pk_add_f32 v[74:75], v[74:75], 1.0 op_sel_hi:[1,0]
	s_nop 0
	v_mul_f32_e32 v74, v74, v75
	v_rcp_f32_e32 v74, v74
	v_mul_f32_e32 v75, 0xbfb8aa3b, v82
	v_exp_f32_e32 v75, v75
	v_mul_f32_e32 v76, v76, v74
	v_mul_f32_e32 v74, 0xbfb8aa3b, v77
	v_exp_f32_e32 v74, v74
	v_mul_f32_e32 v77, v81, v82
	v_pk_add_f32 v[74:75], v[74:75], 1.0 op_sel_hi:[1,0]
	s_nop 0
	v_mul_f32_e32 v74, v74, v75
	v_rcp_f32_e32 v74, v74
	s_nop 0
	v_mul_f32_e32 v74, v77, v74
	v_cvt_pk_bf16_f32 v81, v76, v74
	v_lshlrev_b64 v[74:75], 13, v[170:171]
	v_lshl_add_u64 v[74:75], s[44:45], 0, v[74:75]
	v_lshl_add_u64 v[112:113], v[74:75], 0, v[204:205]
	v_or_b32_e32 v74, 0x80, v200
	v_ashrrev_i32_e32 v75, 31, v74
	v_ashrrev_i32_e32 v76, 4, v74
	v_mad_i64_i32 v[114:115], s[4:5], v76, s94, v[194:195]
	v_lshl_add_u64 v[76:77], s[46:47], 0, v[202:203]
	v_lshlrev_b64 v[116:117], 1, v[74:75]
	v_lshl_add_u64 v[74:75], v[76:77], 0, v[116:117]
	global_load_dwordx4 v[98:101], v[74:75], off
	s_nop 0
	global_store_dwordx4 v[112:113], v[78:81], off
	s_nop 1
	v_lshl_add_u64 v[78:79], v[114:115], 0, v[218:219]
	global_load_dwordx4 v[78:81], v[78:79], off
	v_lshl_add_u64 v[74:75], v[114:115], 0, v[206:207]
	global_load_dwordx4 v[102:105], v[74:75], off
	v_lshl_add_u64 v[74:75], s[46:47], 0, v[210:211]
	v_lshl_add_u64 v[74:75], v[74:75], 0, v[116:117]
	global_load_dwordx4 v[90:93], v[74:75], off
	v_lshl_add_u64 v[74:75], v[114:115], 0, v[208:209]
	global_load_dwordx4 v[94:97], v[74:75], off
	v_lshl_add_u64 v[74:75], s[46:47], 0, v[214:215]
	v_lshl_add_u64 v[74:75], v[74:75], 0, v[116:117]
	global_load_dwordx4 v[82:85], v[74:75], off
	v_lshl_add_u64 v[74:75], v[114:115], 0, v[212:213]
	global_load_dwordx4 v[86:89], v[74:75], off
	v_lshl_add_u64 v[74:75], s[46:47], 0, v[216:217]
	v_lshl_add_u64 v[74:75], v[74:75], 0, v[116:117]
	global_load_dwordx4 v[74:77], v[74:75], off
	s_waitcnt vmcnt(0)
	v_lshlrev_b32_e32 v120, 16, v98
	v_mul_f32_e32 v70, 0xbfb8aa3b, v120
	v_exp_f32_e32 v119, v70
	v_and_b32_e32 v98, 0xffff0000, v98
	v_pk_add_f32 v[118:119], v[118:119], 1.0 op_sel_hi:[1,0]
	s_nop 0
	v_mul_f32_e32 v118, v118, v119
	v_rcp_f32_e32 v118, v118
	v_lshlrev_b32_e32 v121, 16, v102
	v_mul_f32_e32 v70, v121, v120
	v_and_b32_e32 v102, 0xffff0000, v102
	v_mul_f32_e32 v118, v70, v118
	v_mul_f32_e32 v70, 0xbfb8aa3b, v71
	v_mul_f32_e32 v71, 0xbfb8aa3b, v98
	v_exp_f32_e32 v70, v70
	v_exp_f32_e32 v71, v71
	v_mul_f32_e32 v98, v102, v98
	v_pk_add_f32 v[70:71], v[70:71], 1.0 op_sel_hi:[1,0]
	s_nop 0
	v_mul_f32_e32 v70, v70, v71
	v_rcp_f32_e32 v70, v70
	v_lshlrev_b32_e32 v71, 16, v99
	v_and_b32_e32 v99, 0xffff0000, v99
	v_mul_f32_e32 v70, v98, v70
	v_cvt_pk_bf16_f32 v70, v118, v70
	v_exp_f32_e32 v118, v72
	v_mul_f32_e32 v72, 0xbfb8aa3b, v71
	v_exp_f32_e32 v119, v72
	v_lshlrev_b32_e32 v98, 16, v103
	v_mul_f32_e32 v71, v98, v71
	v_and_b32_e32 v98, 0xffff0000, v103
	v_pk_add_f32 v[118:119], v[118:119], 1.0 op_sel_hi:[1,0]
	v_mul_f32_e32 v98, v98, v99
	v_mul_f32_e32 v72, v118, v119
	v_rcp_f32_e32 v72, v72
	s_nop 0
	v_mul_f32_e32 v71, v71, v72
	v_mul_f32_e32 v72, 0xbfb8aa3b, v73
	v_mul_f32_e32 v73, 0xbfb8aa3b, v99
	v_exp_f32_e32 v72, v72
	v_exp_f32_e32 v73, v73
	v_lshlrev_b32_e32 v99, 16, v104
	v_pk_add_f32 v[72:73], v[72:73], 1.0 op_sel_hi:[1,0]
	s_nop 0
	v_mul_f32_e32 v72, v72, v73
	v_rcp_f32_e32 v72, v72
	s_nop 0
	v_mul_f32_e32 v72, v98, v72
	v_lshlrev_b32_e32 v98, 16, v100
	v_cvt_pk_bf16_f32 v71, v71, v72
	v_exp_f32_e32 v72, v66
	v_mul_f32_e32 v66, 0xbfb8aa3b, v98
	v_exp_f32_e32 v73, v66
	v_mul_f32_e32 v66, v99, v98
	v_and_b32_e32 v98, 0xffff0000, v100
	v_pk_add_f32 v[72:73], v[72:73], 1.0 op_sel_hi:[1,0]
	s_nop 0
	v_mul_f32_e32 v72, v72, v73
	v_rcp_f32_e32 v72, v72
	v_and_b32_e32 v73, 0xffff0000, v104
	v_mul_f32_e32 v73, v73, v98
	v_mul_f32_e32 v72, v66, v72
	v_mul_f32_e32 v66, 0xbfb8aa3b, v67
	v_mul_f32_e32 v67, 0xbfb8aa3b, v98
	v_exp_f32_e32 v66, v66
	v_exp_f32_e32 v67, v67
	v_lshlrev_b32_e32 v98, 16, v105
	v_pk_add_f32 v[66:67], v[66:67], 1.0 op_sel_hi:[1,0]
	s_nop 0
	v_mul_f32_e32 v66, v66, v67
	v_rcp_f32_e32 v66, v66
	s_nop 0
	v_mul_f32_e32 v66, v73, v66
	v_lshlrev_b32_e32 v73, 16, v101
	v_cvt_pk_bf16_f32 v72, v72, v66
	v_mul_f32_e32 v66, 0xbfb8aa3b, v68
	v_mul_f32_e32 v67, 0xbfb8aa3b, v73
	v_exp_f32_e32 v66, v66
	v_exp_f32_e32 v67, v67
	v_mul_f32_e32 v68, v98, v73
	v_and_b32_e32 v98, 0xffff0000, v101
	v_and_b32_e32 v73, 0xffff0000, v105
	v_pk_add_f32 v[66:67], v[66:67], 1.0 op_sel_hi:[1,0]
	s_nop 0
	v_mul_f32_e32 v66, v66, v67
	v_rcp_f32_e32 v66, v66
	v_mul_f32_e32 v67, 0xbfb8aa3b, v98
	v_exp_f32_e32 v67, v67
	v_mul_f32_e32 v68, v68, v66
	v_mul_f32_e32 v66, 0xbfb8aa3b, v69
	v_exp_f32_e32 v66, v66
	v_mul_f32_e32 v69, v73, v98
	v_pk_add_f32 v[66:67], v[66:67], 1.0 op_sel_hi:[1,0]
	s_nop 0
; __device__ __forceinline__ unsigned cvt_pk_bf16(float lo, float hi) { unsigned r; asm volatile("v_cvt_pk_bf16_f32 %0, %1, %2" : "=v"(r) : "v"(lo), "v"(hi)); return r; }
; __device__ __forceinline__ float bf_lo(unsigned w) { return __uint_as_float(w << 16); }
; __device__ __forceinline__ float bf_hi(unsigned w) { return __uint_as_float(w & 0xffff0000u); }
;     __device__ __forceinline__ void operator()(const f32x4 (&acc)[2][2][4][2], const Unit& u, int wr, int wc, int fr, int fq, const Pre&) const {
;     ...
;         for (int bj = 0; bj < 2; ++bj) { const int c = col0 + bj * HALF;
; #pragma unroll
;             for (int ai = 0; ai < 2; ++ai) { u32x4 zv[4], gv[4];
; #pragma unroll
;                 for (int m = 0; m < 4; ++m) { const int r = row0 + ai * HALF + m * 16; zv[m] = *(const u32x4*)(Z + (size_t)r * DE2 + c); gv[m] = *(const u32x4*)(Gm + (size_t)(c >> 4) * GSTR + r * 16 + (c & 15)); }
; #pragma unroll
;                 for (int m = 0; m < 4; ++m) { const int r = row0 + ai * HALF + m * 16;
;                     const u32x4 zw = zv[m], gw = gv[m];
;                     const f32x4 a0 = acc[ai][bj][m][0] + bs[bj][0], a1 = acc[ai][bj][m][1] + bs[bj][1];
;                     u32x4 w;
;                     w.x = cvt_pk_bf16(glu_gate_f(bf_lo(gw.x), a0[0], bf_lo(zw.x)), glu_gate_f(bf_hi(gw.x), a0[1], bf_hi(zw.x)));
;                     w.y = cvt_pk_bf16(glu_gate_f(bf_lo(gw.y), a0[2], bf_lo(zw.y)), glu_gate_f(bf_hi(gw.y), a0[3], bf_hi(zw.y)));
;                     w.z = cvt_pk_bf16(glu_gate_f(bf_lo(gw.z), a1[0], bf_lo(zw.z)), glu_gate_f(bf_hi(gw.z), a1[1], bf_hi(zw.z)));
;                     w.w = cvt_pk_bf16(glu_gate_f(bf_lo(gw.w), a1[2], bf_lo(zw.w)), glu_gate_f(bf_hi(gw.w), a1[3], bf_hi(zw.w)));
;                     *(u32x4*)(O + (size_t)r * DE + c) = w; } } }
	v_mul_f32_e32 v66, v66, v67
	v_rcp_f32_e32 v66, v66
	s_nop 0
	v_mul_f32_e32 v66, v69, v66
	v_cvt_pk_bf16_f32 v73, v68, v66
	v_lshlrev_b32_e32 v68, 16, v90
	v_exp_f32_e32 v66, v62
	v_mul_f32_e32 v62, 0xbfb8aa3b, v68
	v_exp_f32_e32 v67, v62
	v_lshlrev_b32_e32 v69, 16, v94
	v_mul_f32_e32 v62, v69, v68
	v_and_b32_e32 v68, 0xffff0000, v90
	v_pk_add_f32 v[66:67], v[66:67], 1.0 op_sel_hi:[1,0]
	global_store_dwordx4 v[162:163], v[70:73], off offset:256
	v_mul_f32_e32 v66, v66, v67
	v_rcp_f32_e32 v66, v66
	v_and_b32_e32 v67, 0xffff0000, v94
	v_mul_f32_e32 v67, v67, v68
	v_mul_f32_e32 v66, v62, v66
	v_mul_f32_e32 v62, 0xbfb8aa3b, v63
	v_mul_f32_e32 v63, 0xbfb8aa3b, v68
	v_exp_f32_e32 v62, v62
	v_exp_f32_e32 v63, v63
	v_lshlrev_b32_e32 v68, 16, v95
	v_pk_add_f32 v[62:63], v[62:63], 1.0 op_sel_hi:[1,0]
	s_nop 0
	v_mul_f32_e32 v62, v62, v63
	v_rcp_f32_e32 v62, v62
	v_lshlrev_b32_e32 v63, 16, v91
	v_mul_f32_e32 v62, v67, v62
	v_cvt_pk_bf16_f32 v62, v66, v62
	v_exp_f32_e32 v66, v64
	v_mul_f32_e32 v64, 0xbfb8aa3b, v63
	v_exp_f32_e32 v67, v64
	v_mul_f32_e32 v63, v68, v63
	v_pk_add_f32 v[66:67], v[66:67], 1.0 op_sel_hi:[1,0]
	s_nop 0
	v_mul_f32_e32 v64, v66, v67
	v_rcp_f32_e32 v64, v64
	v_and_b32_e32 v67, 0xffff0000, v91
	v_and_b32_e32 v66, 0xffff0000, v95
	v_mul_f32_e32 v66, v66, v67
	v_mul_f32_e32 v63, v63, v64
	v_mul_f32_e32 v64, 0xbfb8aa3b, v65
	v_mul_f32_e32 v65, 0xbfb8aa3b, v67
	v_exp_f32_e32 v64, v64
	v_exp_f32_e32 v65, v65
	v_lshlrev_b32_e32 v67, 16, v96
	v_pk_add_f32 v[64:65], v[64:65], 1.0 op_sel_hi:[1,0]
	s_nop 0
	v_mul_f32_e32 v64, v64, v65
	v_rcp_f32_e32 v64, v64
	s_nop 0
	v_mul_f32_e32 v64, v66, v64
	v_lshlrev_b32_e32 v66, 16, v92
	v_cvt_pk_bf16_f32 v63, v63, v64
	v_exp_f32_e32 v64, v58
	v_mul_f32_e32 v58, 0xbfb8aa3b, v66
	v_exp_f32_e32 v65, v58
	v_mul_f32_e32 v58, v67, v66
	v_and_b32_e32 v66, 0xffff0000, v92
	v_pk_add_f32 v[64:65], v[64:65], 1.0 op_sel_hi:[1,0]
	s_nop 0
	v_mul_f32_e32 v64, v64, v65
	v_rcp_f32_e32 v64, v64
	v_and_b32_e32 v65, 0xffff0000, v96
	v_mul_f32_e32 v65, v65, v66
	v_mul_f32_e32 v64, v58, v64
	v_mul_f32_e32 v58, 0xbfb8aa3b, v59
	v_mul_f32_e32 v59, 0xbfb8aa3b, v66
	v_exp_f32_e32 v58, v58
	v_exp_f32_e32 v59, v59
	v_lshlrev_b32_e32 v66, 16, v97
	v_pk_add_f32 v[58:59], v[58:59], 1.0 op_sel_hi:[1,0]
	s_nop 0
	v_mul_f32_e32 v58, v58, v59
	v_rcp_f32_e32 v58, v58
	s_nop 0
	v_mul_f32_e32 v58, v65, v58
	v_lshlrev_b32_e32 v65, 16, v93
	v_cvt_pk_bf16_f32 v64, v64, v58
	v_mul_f32_e32 v58, 0xbfb8aa3b, v60
	v_mul_f32_e32 v59, 0xbfb8aa3b, v65
	v_exp_f32_e32 v58, v58
	v_exp_f32_e32 v59, v59
	v_mul_f32_e32 v60, v66, v65
	v_and_b32_e32 v66, 0xffff0000, v93
	v_and_b32_e32 v65, 0xffff0000, v97
	v_pk_add_f32 v[58:59], v[58:59], 1.0 op_sel_hi:[1,0]
	s_nop 0
	v_mul_f32_e32 v58, v58, v59
	v_rcp_f32_e32 v58, v58
	v_mul_f32_e32 v59, 0xbfb8aa3b, v66
	v_exp_f32_e32 v59, v59
	v_mul_f32_e32 v60, v60, v58
	v_mul_f32_e32 v58, 0xbfb8aa3b, v61
	v_exp_f32_e32 v58, v58
	v_mul_f32_e32 v61, v65, v66
	v_pk_add_f32 v[58:59], v[58:59], 1.0 op_sel_hi:[1,0]
	s_nop 0
	v_mul_f32_e32 v58, v58, v59
	v_rcp_f32_e32 v58, v58
	s_nop 0
	v_mul_f32_e32 v58, v61, v58
	v_cvt_pk_bf16_f32 v65, v60, v58
	v_lshlrev_b32_e32 v60, 16, v82
	v_exp_f32_e32 v58, v54
	v_mul_f32_e32 v54, 0xbfb8aa3b, v60
	v_exp_f32_e32 v59, v54
	v_lshlrev_b32_e32 v61, 16, v86
	v_mul_f32_e32 v54, v61, v60
	v_and_b32_e32 v60, 0xffff0000, v82
	v_pk_add_f32 v[58:59], v[58:59], 1.0 op_sel_hi:[1,0]
	global_store_dwordx4 v[154:155], v[62:65], off offset:256
	v_mul_f32_e32 v58, v58, v59
	v_rcp_f32_e32 v58, v58
	v_and_b32_e32 v59, 0xffff0000, v86
	v_mul_f32_e32 v59, v59, v60
	v_mul_f32_e32 v58, v54, v58
	v_mul_f32_e32 v54, 0xbfb8aa3b, v55
	v_mul_f32_e32 v55, 0xbfb8aa3b, v60
	v_exp_f32_e32 v54, v54
	v_exp_f32_e32 v55, v55
	v_lshlrev_b32_e32 v60, 16, v87
	v_pk_add_f32 v[54:55], v[54:55], 1.0 op_sel_hi:[1,0]
	s_nop 0
	v_mul_f32_e32 v54, v54, v55
	v_rcp_f32_e32 v54, v54
	v_lshlrev_b32_e32 v55, 16, v83
	v_mul_f32_e32 v54, v59, v54
	v_cvt_pk_bf16_f32 v54, v58, v54
	v_exp_f32_e32 v58, v56
	v_mul_f32_e32 v56, 0xbfb8aa3b, v55
	v_exp_f32_e32 v59, v56
	v_mul_f32_e32 v55, v60, v55
	v_pk_add_f32 v[58:59], v[58:59], 1.0 op_sel_hi:[1,0]
	s_nop 0
	v_mul_f32_e32 v56, v58, v59
	v_rcp_f32_e32 v56, v56
	v_and_b32_e32 v59, 0xffff0000, v83
	v_and_b32_e32 v58, 0xffff0000, v87
	v_mul_f32_e32 v58, v58, v59
	v_mul_f32_e32 v55, v55, v56
	v_mul_f32_e32 v56, 0xbfb8aa3b, v57
	v_mul_f32_e32 v57, 0xbfb8aa3b, v59
	v_exp_f32_e32 v56, v56
	v_exp_f32_e32 v57, v57
	v_lshlrev_b32_e32 v59, 16, v88
	v_pk_add_f32 v[56:57], v[56:57], 1.0 op_sel_hi:[1,0]
	s_nop 0
	v_mul_f32_e32 v56, v56, v57
	v_rcp_f32_e32 v56, v56
	s_nop 0
	v_mul_f32_e32 v56, v58, v56
	v_lshlrev_b32_e32 v58, 16, v84
	v_cvt_pk_bf16_f32 v55, v55, v56
	v_exp_f32_e32 v56, v50
	v_mul_f32_e32 v50, 0xbfb8aa3b, v58
	v_exp_f32_e32 v57, v50
	v_mul_f32_e32 v50, v59, v58
	v_and_b32_e32 v58, 0xffff0000, v84
	v_pk_add_f32 v[56:57], v[56:57], 1.0 op_sel_hi:[1,0]
	s_nop 0
	v_mul_f32_e32 v56, v56, v57
	v_rcp_f32_e32 v56, v56
	v_and_b32_e32 v57, 0xffff0000, v88
	v_mul_f32_e32 v57, v57, v58
	v_mul_f32_e32 v56, v50, v56
	v_mul_f32_e32 v50, 0xbfb8aa3b, v51
	v_mul_f32_e32 v51, 0xbfb8aa3b, v58
	v_exp_f32_e32 v50, v50
	v_exp_f32_e32 v51, v51
	v_lshlrev_b32_e32 v58, 16, v89
	v_pk_add_f32 v[50:51], v[50:51], 1.0 op_sel_hi:[1,0]
	s_nop 0
	v_mul_f32_e32 v50, v50, v51
	v_rcp_f32_e32 v50, v50
	s_nop 0
	v_mul_f32_e32 v50, v57, v50
	v_lshlrev_b32_e32 v57, 16, v85
	v_cvt_pk_bf16_f32 v56, v56, v50
	v_mul_f32_e32 v50, 0xbfb8aa3b, v52
	v_mul_f32_e32 v51, 0xbfb8aa3b, v57
	v_exp_f32_e32 v50, v50
	v_exp_f32_e32 v51, v51
	v_mul_f32_e32 v52, v58, v57
	v_and_b32_e32 v58, 0xffff0000, v85
	v_and_b32_e32 v57, 0xffff0000, v89
; __device__ __forceinline__ unsigned cvt_pk_bf16(float lo, float hi) { unsigned r; asm volatile("v_cvt_pk_bf16_f32 %0, %1, %2" : "=v"(r) : "v"(lo), "v"(hi)); return r; }
; __device__ __forceinline__ float bf_lo(unsigned w) { return __uint_as_float(w << 16); }
; __device__ __forceinline__ float bf_hi(unsigned w) { return __uint_as_float(w & 0xffff0000u); }
;     __device__ __forceinline__ void operator()(const f32x4 (&acc)[2][2][4][2], const Unit& u, int wr, int wc, int fr, int fq, const Pre&) const {
;     ...
;         for (int bj = 0; bj < 2; ++bj) { const int c = col0 + bj * HALF;
; #pragma unroll
;             for (int ai = 0; ai < 2; ++ai) { u32x4 zv[4], gv[4];
; #pragma unroll
;                 for (int m = 0; m < 4; ++m) { const int r = row0 + ai * HALF + m * 16; zv[m] = *(const u32x4*)(Z + (size_t)r * DE2 + c); gv[m] = *(const u32x4*)(Gm + (size_t)(c >> 4) * GSTR + r * 16 + (c & 15)); }
; #pragma unroll
;                 for (int m = 0; m < 4; ++m) { const int r = row0 + ai * HALF + m * 16;
;                     const u32x4 zw = zv[m], gw = gv[m];
;                     const f32x4 a0 = acc[ai][bj][m][0] + bs[bj][0], a1 = acc[ai][bj][m][1] + bs[bj][1];
;                     u32x4 w;
;                     w.x = cvt_pk_bf16(glu_gate_f(bf_lo(gw.x), a0[0], bf_lo(zw.x)), glu_gate_f(bf_hi(gw.x), a0[1], bf_hi(zw.x)));
;                     w.y = cvt_pk_bf16(glu_gate_f(bf_lo(gw.y), a0[2], bf_lo(zw.y)), glu_gate_f(bf_hi(gw.y), a0[3], bf_hi(zw.y)));
;                     w.z = cvt_pk_bf16(glu_gate_f(bf_lo(gw.z), a1[0], bf_lo(zw.z)), glu_gate_f(bf_hi(gw.z), a1[1], bf_hi(zw.z)));
;                     w.w = cvt_pk_bf16(glu_gate_f(bf_lo(gw.w), a1[2], bf_lo(zw.w)), glu_gate_f(bf_hi(gw.w), a1[3], bf_hi(zw.w)));
;                     *(u32x4*)(O + (size_t)r * DE + c) = w; } } }
	v_pk_add_f32 v[50:51], v[50:51], 1.0 op_sel_hi:[1,0]
	s_nop 0
	v_mul_f32_e32 v50, v50, v51
	v_rcp_f32_e32 v50, v50
	v_mul_f32_e32 v51, 0xbfb8aa3b, v58
	v_exp_f32_e32 v51, v51
	v_mul_f32_e32 v52, v52, v50
	v_mul_f32_e32 v50, 0xbfb8aa3b, v53
	v_exp_f32_e32 v50, v50
	v_mul_f32_e32 v53, v57, v58
	v_pk_add_f32 v[50:51], v[50:51], 1.0 op_sel_hi:[1,0]
	s_nop 0
	v_mul_f32_e32 v50, v50, v51
	v_rcp_f32_e32 v50, v50
	s_nop 0
	v_mul_f32_e32 v50, v53, v50
	v_cvt_pk_bf16_f32 v57, v52, v50
	v_lshlrev_b32_e32 v52, 16, v74
	v_exp_f32_e32 v50, v46
	v_mul_f32_e32 v46, 0xbfb8aa3b, v52
	v_exp_f32_e32 v51, v46
	v_lshlrev_b32_e32 v53, 16, v78
	v_mul_f32_e32 v46, v53, v52
	v_and_b32_e32 v52, 0xffff0000, v74
	v_pk_add_f32 v[50:51], v[50:51], 1.0 op_sel_hi:[1,0]
	global_store_dwordx4 v[146:147], v[54:57], off offset:256
	v_mul_f32_e32 v50, v50, v51
	v_rcp_f32_e32 v50, v50
	v_and_b32_e32 v51, 0xffff0000, v78
	v_mul_f32_e32 v51, v51, v52
	v_exp_f32_e32 v74, v38
	v_mul_f32_e32 v50, v46, v50
	v_mul_f32_e32 v46, 0xbfb8aa3b, v47
	v_mul_f32_e32 v47, 0xbfb8aa3b, v52
	v_exp_f32_e32 v46, v46
	v_exp_f32_e32 v47, v47
	v_lshlrev_b32_e32 v52, 16, v79
	v_pk_add_f32 v[46:47], v[46:47], 1.0 op_sel_hi:[1,0]
	s_nop 0
	v_mul_f32_e32 v46, v46, v47
	v_rcp_f32_e32 v46, v46
	v_lshlrev_b32_e32 v47, 16, v75
	v_mul_f32_e32 v46, v51, v46
	v_cvt_pk_bf16_f32 v46, v50, v46
	v_exp_f32_e32 v50, v48
	v_mul_f32_e32 v48, 0xbfb8aa3b, v47
	v_exp_f32_e32 v51, v48
	v_mul_f32_e32 v47, v52, v47
	v_pk_add_f32 v[50:51], v[50:51], 1.0 op_sel_hi:[1,0]
	s_nop 0
	v_mul_f32_e32 v48, v50, v51
	v_rcp_f32_e32 v48, v48
	v_and_b32_e32 v51, 0xffff0000, v75
	v_and_b32_e32 v50, 0xffff0000, v79
	v_mul_f32_e32 v50, v50, v51
	v_mul_f32_e32 v47, v47, v48
	v_mul_f32_e32 v48, 0xbfb8aa3b, v49
	v_mul_f32_e32 v49, 0xbfb8aa3b, v51
	v_exp_f32_e32 v48, v48
	v_exp_f32_e32 v49, v49
	v_lshlrev_b32_e32 v51, 16, v80
	v_pk_add_f32 v[48:49], v[48:49], 1.0 op_sel_hi:[1,0]
	s_nop 0
	v_mul_f32_e32 v48, v48, v49
	v_rcp_f32_e32 v48, v48
	s_nop 0
	v_mul_f32_e32 v48, v50, v48
	v_lshlrev_b32_e32 v50, 16, v76
	v_cvt_pk_bf16_f32 v47, v47, v48
	v_exp_f32_e32 v48, v42
	v_mul_f32_e32 v42, 0xbfb8aa3b, v50
	v_exp_f32_e32 v49, v42
	v_mul_f32_e32 v42, v51, v50
	v_and_b32_e32 v50, 0xffff0000, v76
	v_pk_add_f32 v[48:49], v[48:49], 1.0 op_sel_hi:[1,0]
	s_nop 0
	v_mul_f32_e32 v48, v48, v49
	v_rcp_f32_e32 v48, v48
	v_and_b32_e32 v49, 0xffff0000, v80
	v_mul_f32_e32 v49, v49, v50
	v_mul_f32_e32 v48, v42, v48
	v_mul_f32_e32 v42, 0xbfb8aa3b, v43
	v_mul_f32_e32 v43, 0xbfb8aa3b, v50
	v_exp_f32_e32 v42, v42
	v_exp_f32_e32 v43, v43
	v_lshlrev_b32_e32 v50, 16, v81
	v_pk_add_f32 v[42:43], v[42:43], 1.0 op_sel_hi:[1,0]
	s_nop 0
	v_mul_f32_e32 v42, v42, v43
	v_rcp_f32_e32 v42, v42
	s_nop 0
	v_mul_f32_e32 v42, v49, v42
	v_lshlrev_b32_e32 v49, 16, v77
	v_cvt_pk_bf16_f32 v48, v48, v42
	v_mul_f32_e32 v42, 0xbfb8aa3b, v44
	v_mul_f32_e32 v43, 0xbfb8aa3b, v49
	v_exp_f32_e32 v42, v42
	v_exp_f32_e32 v43, v43
	v_mul_f32_e32 v44, v50, v49
	v_and_b32_e32 v50, 0xffff0000, v77
	v_and_b32_e32 v49, 0xffff0000, v81
	v_pk_add_f32 v[42:43], v[42:43], 1.0 op_sel_hi:[1,0]
	s_nop 0
	v_mul_f32_e32 v42, v42, v43
	v_rcp_f32_e32 v42, v42
	v_mul_f32_e32 v43, 0xbfb8aa3b, v50
	v_exp_f32_e32 v43, v43
	v_mul_f32_e32 v44, v44, v42
	v_mul_f32_e32 v42, 0xbfb8aa3b, v45
	v_exp_f32_e32 v42, v42
	v_mul_f32_e32 v45, v49, v50
	v_pk_add_f32 v[42:43], v[42:43], 1.0 op_sel_hi:[1,0]
	s_nop 0
	v_mul_f32_e32 v42, v42, v43
	v_rcp_f32_e32 v42, v42
	s_nop 0
	v_mul_f32_e32 v42, v45, v42
	v_cvt_pk_bf16_f32 v49, v44, v42
	v_lshl_add_u64 v[42:43], s[46:47], 0, v[150:151]
	global_store_dwordx4 v[148:149], v[46:49], off offset:256
	v_lshl_add_u64 v[42:43], v[42:43], 0, v[116:117]
	global_load_dwordx4 v[66:69], v[42:43], off
	v_lshl_add_u64 v[46:47], v[114:115], 0, v[168:169]
	global_load_dwordx4 v[46:49], v[46:47], off
	v_lshl_add_u64 v[42:43], v[114:115], 0, v[152:153]
	global_load_dwordx4 v[70:73], v[42:43], off
	v_lshl_add_u64 v[42:43], s[46:47], 0, v[156:157]
	v_lshl_add_u64 v[42:43], v[42:43], 0, v[116:117]
	global_load_dwordx4 v[58:61], v[42:43], off
	v_lshl_add_u64 v[42:43], v[114:115], 0, v[158:159]
	global_load_dwordx4 v[62:65], v[42:43], off
	v_lshl_add_u64 v[42:43], s[46:47], 0, v[160:161]
	v_lshl_add_u64 v[42:43], v[42:43], 0, v[116:117]
	global_load_dwordx4 v[50:53], v[42:43], off
	v_lshl_add_u64 v[42:43], v[114:115], 0, v[164:165]
	global_load_dwordx4 v[54:57], v[42:43], off
	v_lshl_add_u64 v[42:43], s[46:47], 0, v[166:167]
	v_lshl_add_u64 v[42:43], v[42:43], 0, v[116:117]
	global_load_dwordx4 v[42:45], v[42:43], off
	s_waitcnt vmcnt(0)
; __device__ __forceinline__ unsigned cvt_pk_bf16(float lo, float hi) { unsigned r; asm volatile("v_cvt_pk_bf16_f32 %0, %1, %2" : "=v"(r) : "v"(lo), "v"(hi)); return r; }
; __device__ __forceinline__ float bf_lo(unsigned w) { return __uint_as_float(w << 16); }
; __device__ __forceinline__ float bf_hi(unsigned w) { return __uint_as_float(w & 0xffff0000u); }
;     __device__ __forceinline__ void operator()(const f32x4 (&acc)[2][2][4][2], const Unit& u, int wr, int wc, int fr, int fq, const Pre&) const {
;     ...
;         for (int bj = 0; bj < 2; ++bj) { const int c = col0 + bj * HALF;
; #pragma unroll
;             for (int ai = 0; ai < 2; ++ai) { u32x4 zv[4], gv[4];
; #pragma unroll
;                 for (int m = 0; m < 4; ++m) { const int r = row0 + ai * HALF + m * 16; zv[m] = *(const u32x4*)(Z + (size_t)r * DE2 + c); gv[m] = *(const u32x4*)(Gm + (size_t)(c >> 4) * GSTR + r * 16 + (c & 15)); }
; #pragma unroll
;                 for (int m = 0; m < 4; ++m) { const int r = row0 + ai * HALF + m * 16;
;                     const u32x4 zw = zv[m], gw = gv[m];
;                     const f32x4 a0 = acc[ai][bj][m][0] + bs[bj][0], a1 = acc[ai][bj][m][1] + bs[bj][1];
;                     u32x4 w;
;                     w.x = cvt_pk_bf16(glu_gate_f(bf_lo(gw.x), a0[0], bf_lo(zw.x)), glu_gate_f(bf_hi(gw.x), a0[1], bf_hi(zw.x)));
;                     w.y = cvt_pk_bf16(glu_gate_f(bf_lo(gw.y), a0[2], bf_lo(zw.y)), glu_gate_f(bf_hi(gw.y), a0[3], bf_hi(zw.y)));
;                     w.z = cvt_pk_bf16(glu_gate_f(bf_lo(gw.z), a1[0], bf_lo(zw.z)), glu_gate_f(bf_hi(gw.z), a1[1], bf_hi(zw.z)));
;                     w.w = cvt_pk_bf16(glu_gate_f(bf_lo(gw.w), a1[2], bf_lo(zw.w)), glu_gate_f(bf_hi(gw.w), a1[3], bf_hi(zw.w)));
;                     *(u32x4*)(O + (size_t)r * DE + c) = w; } } }
	v_lshlrev_b32_e32 v76, 16, v66
	v_mul_f32_e32 v38, 0xbfb8aa3b, v76
	v_exp_f32_e32 v75, v38
	v_and_b32_e32 v66, 0xffff0000, v66
	v_lshlrev_b32_e32 v77, 16, v70
	v_mul_f32_e32 v38, v77, v76
	v_pk_add_f32 v[74:75], v[74:75], 1.0 op_sel_hi:[1,0]
	v_and_b32_e32 v70, 0xffff0000, v70
	v_mul_f32_e32 v74, v74, v75
	v_rcp_f32_e32 v74, v74
	s_nop 0
	v_mul_f32_e32 v74, v38, v74
	v_mul_f32_e32 v38, 0xbfb8aa3b, v39
	v_mul_f32_e32 v39, 0xbfb8aa3b, v66
	v_exp_f32_e32 v38, v38
	v_exp_f32_e32 v39, v39
	v_mul_f32_e32 v66, v70, v66
	v_pk_add_f32 v[38:39], v[38:39], 1.0 op_sel_hi:[1,0]
	s_nop 0
	v_mul_f32_e32 v38, v38, v39
	v_rcp_f32_e32 v38, v38
	v_lshlrev_b32_e32 v39, 16, v67
	v_and_b32_e32 v67, 0xffff0000, v67
	v_mul_f32_e32 v38, v66, v38
	v_cvt_pk_bf16_f32 v38, v74, v38
	v_exp_f32_e32 v74, v40
	v_mul_f32_e32 v40, 0xbfb8aa3b, v39
	v_exp_f32_e32 v75, v40
	v_lshlrev_b32_e32 v66, 16, v71
	v_mul_f32_e32 v39, v66, v39
	v_and_b32_e32 v66, 0xffff0000, v71
	v_pk_add_f32 v[74:75], v[74:75], 1.0 op_sel_hi:[1,0]
	v_mul_f32_e32 v66, v66, v67
	v_mul_f32_e32 v40, v74, v75
	v_rcp_f32_e32 v40, v40
	s_nop 0
	v_mul_f32_e32 v39, v39, v40
	v_mul_f32_e32 v40, 0xbfb8aa3b, v41
	v_mul_f32_e32 v41, 0xbfb8aa3b, v67
	v_exp_f32_e32 v40, v40
	v_exp_f32_e32 v41, v41
	v_lshlrev_b32_e32 v67, 16, v72
	v_pk_add_f32 v[40:41], v[40:41], 1.0 op_sel_hi:[1,0]
	s_nop 0
	v_mul_f32_e32 v40, v40, v41
	v_rcp_f32_e32 v40, v40
	s_nop 0
	v_mul_f32_e32 v40, v66, v40
	v_lshlrev_b32_e32 v66, 16, v68
	v_cvt_pk_bf16_f32 v39, v39, v40
	v_exp_f32_e32 v40, v34
	v_mul_f32_e32 v34, 0xbfb8aa3b, v66
	v_exp_f32_e32 v41, v34
	v_mul_f32_e32 v34, v67, v66
	v_and_b32_e32 v66, 0xffff0000, v68
	v_pk_add_f32 v[40:41], v[40:41], 1.0 op_sel_hi:[1,0]
	s_nop 0
	v_mul_f32_e32 v40, v40, v41
	v_rcp_f32_e32 v40, v40
	v_and_b32_e32 v41, 0xffff0000, v72
	v_mul_f32_e32 v41, v41, v66
	v_mul_f32_e32 v40, v34, v40
	v_mul_f32_e32 v34, 0xbfb8aa3b, v35
	v_mul_f32_e32 v35, 0xbfb8aa3b, v66
	v_exp_f32_e32 v34, v34
	v_exp_f32_e32 v35, v35
	v_lshlrev_b32_e32 v66, 16, v73
	v_pk_add_f32 v[34:35], v[34:35], 1.0 op_sel_hi:[1,0]
	s_nop 0
	v_mul_f32_e32 v34, v34, v35
	v_rcp_f32_e32 v34, v34
	s_nop 0
	v_mul_f32_e32 v34, v41, v34
	v_lshlrev_b32_e32 v41, 16, v69
	v_cvt_pk_bf16_f32 v40, v40, v34
	v_mul_f32_e32 v34, 0xbfb8aa3b, v36
	v_mul_f32_e32 v35, 0xbfb8aa3b, v41
	v_exp_f32_e32 v34, v34
	v_exp_f32_e32 v35, v35
	v_mul_f32_e32 v36, v66, v41
	v_and_b32_e32 v66, 0xffff0000, v69
	v_and_b32_e32 v41, 0xffff0000, v73
	v_pk_add_f32 v[34:35], v[34:35], 1.0 op_sel_hi:[1,0]
	s_nop 0
	v_mul_f32_e32 v34, v34, v35
	v_rcp_f32_e32 v34, v34
	v_mul_f32_e32 v35, 0xbfb8aa3b, v66
	v_exp_f32_e32 v35, v35
	v_mul_f32_e32 v36, v36, v34
	v_mul_f32_e32 v34, 0xbfb8aa3b, v37
	v_exp_f32_e32 v34, v34
	v_mul_f32_e32 v37, v41, v66
	v_pk_add_f32 v[34:35], v[34:35], 1.0 op_sel_hi:[1,0]
	s_nop 0
	v_mul_f32_e32 v34, v34, v35
	v_rcp_f32_e32 v34, v34
	s_nop 0
	v_mul_f32_e32 v34, v37, v34
	v_cvt_pk_bf16_f32 v41, v36, v34
	v_lshlrev_b32_e32 v36, 16, v58
	v_exp_f32_e32 v34, v22
	v_mul_f32_e32 v22, 0xbfb8aa3b, v36
	v_exp_f32_e32 v35, v22
	v_lshlrev_b32_e32 v37, 16, v62
	v_mul_f32_e32 v22, v37, v36
	v_and_b32_e32 v36, 0xffff0000, v58
	v_pk_add_f32 v[34:35], v[34:35], 1.0 op_sel_hi:[1,0]
	global_store_dwordx4 v[106:107], v[38:41], off offset:256
	v_mul_f32_e32 v34, v34, v35
	v_rcp_f32_e32 v34, v34
	v_and_b32_e32 v35, 0xffff0000, v62
	v_mul_f32_e32 v35, v35, v36
	v_mul_f32_e32 v34, v22, v34
	v_mul_f32_e32 v22, 0xbfb8aa3b, v23
	v_mul_f32_e32 v23, 0xbfb8aa3b, v36
	v_exp_f32_e32 v22, v22
	v_exp_f32_e32 v23, v23
	v_lshlrev_b32_e32 v36, 16, v63
	v_pk_add_f32 v[22:23], v[22:23], 1.0 op_sel_hi:[1,0]
	s_nop 0
	v_mul_f32_e32 v22, v22, v23
	v_rcp_f32_e32 v22, v22
	v_lshlrev_b32_e32 v23, 16, v59
	v_mul_f32_e32 v22, v35, v22
	v_cvt_pk_bf16_f32 v22, v34, v22
	v_exp_f32_e32 v34, v24
	v_mul_f32_e32 v24, 0xbfb8aa3b, v23
	v_exp_f32_e32 v35, v24
	v_mul_f32_e32 v23, v36, v23
	v_pk_add_f32 v[34:35], v[34:35], 1.0 op_sel_hi:[1,0]
	s_nop 0
	v_mul_f32_e32 v24, v34, v35
	v_rcp_f32_e32 v24, v24
	v_and_b32_e32 v35, 0xffff0000, v59
	v_and_b32_e32 v34, 0xffff0000, v63
	v_mul_f32_e32 v34, v34, v35
	v_mul_f32_e32 v23, v23, v24
	v_mul_f32_e32 v24, 0xbfb8aa3b, v25
	v_mul_f32_e32 v25, 0xbfb8aa3b, v35
	v_exp_f32_e32 v24, v24
	v_exp_f32_e32 v25, v25
	v_lshlrev_b32_e32 v35, 16, v64
	v_pk_add_f32 v[24:25], v[24:25], 1.0 op_sel_hi:[1,0]
	s_nop 0
	v_mul_f32_e32 v24, v24, v25
	v_rcp_f32_e32 v24, v24
	s_nop 0
	v_mul_f32_e32 v24, v34, v24
	v_lshlrev_b32_e32 v34, 16, v60
	v_cvt_pk_bf16_f32 v23, v23, v24
	v_exp_f32_e32 v24, v18
	v_mul_f32_e32 v18, 0xbfb8aa3b, v34
	v_exp_f32_e32 v25, v18
	v_mul_f32_e32 v18, v35, v34
	v_and_b32_e32 v34, 0xffff0000, v60
	v_pk_add_f32 v[24:25], v[24:25], 1.0 op_sel_hi:[1,0]
	s_nop 0
	v_mul_f32_e32 v24, v24, v25
	v_rcp_f32_e32 v24, v24
	v_and_b32_e32 v25, 0xffff0000, v64
	v_mul_f32_e32 v25, v25, v34
	v_mul_f32_e32 v24, v18, v24
	v_mul_f32_e32 v18, 0xbfb8aa3b, v19
	v_mul_f32_e32 v19, 0xbfb8aa3b, v34
	v_exp_f32_e32 v18, v18
	v_exp_f32_e32 v19, v19
	v_lshlrev_b32_e32 v34, 16, v65
	v_pk_add_f32 v[18:19], v[18:19], 1.0 op_sel_hi:[1,0]
	s_nop 0
	v_mul_f32_e32 v18, v18, v19
	v_rcp_f32_e32 v18, v18
	s_nop 0
	v_mul_f32_e32 v18, v25, v18
	v_lshlrev_b32_e32 v25, 16, v61
	v_cvt_pk_bf16_f32 v24, v24, v18
	v_mul_f32_e32 v18, 0xbfb8aa3b, v20
	v_mul_f32_e32 v19, 0xbfb8aa3b, v25
	v_exp_f32_e32 v18, v18
	v_exp_f32_e32 v19, v19
	v_mul_f32_e32 v20, v34, v25
	v_and_b32_e32 v34, 0xffff0000, v61
	v_and_b32_e32 v25, 0xffff0000, v65
	v_pk_add_f32 v[18:19], v[18:19], 1.0 op_sel_hi:[1,0]
	s_nop 0
	v_mul_f32_e32 v18, v18, v19
	v_rcp_f32_e32 v18, v18
	v_mul_f32_e32 v19, 0xbfb8aa3b, v34
	v_exp_f32_e32 v19, v19
	v_mul_f32_e32 v20, v20, v18
; __device__ __forceinline__ unsigned cvt_pk_bf16(float lo, float hi) { unsigned r; asm volatile("v_cvt_pk_bf16_f32 %0, %1, %2" : "=v"(r) : "v"(lo), "v"(hi)); return r; }
; __device__ __forceinline__ float bf_lo(unsigned w) { return __uint_as_float(w << 16); }
; __device__ __forceinline__ float bf_hi(unsigned w) { return __uint_as_float(w & 0xffff0000u); }
; #define PG8_WAIT_V(n) asm volatile("s_waitcnt vmcnt(" #n ")" ::: "memory")
; #define PG8_BAR __builtin_amdgcn_s_barrier()
; template <class Epi>
; __device__ __forceinline__ void gemm_phase(LAS unsigned char* lds, const Gemm g, const StaticOrder& S, const Epi& E) {
;     ...
;         if (!has_next) break;
; #pragma unroll
;         for (int a = 0; a < 2; ++a)
; #pragma unroll
;             for (int b = 0; b < 2; ++b)
; #pragma unroll
;                 for (int m = 0; m < 4; ++m)
; #pragma unroll
;                     for (int n = 0; n < 2; ++n) acc[a][b][m][n] = (f32x4){0.f, 0.f, 0.f, 0.f};
;         cur = nxt; cA = nA; cB = nB; ++ui;
;         pre = E.pre(cur, wr, fr);
;     }
;     PG8_WAIT_V(0);
;     if (wr == 0) PG8_BAR;
;     PG8_BAR;
;     __device__ __forceinline__ void operator()(const f32x4 (&acc)[2][2][4][2], const Unit& u, int wr, int wc, int fr, int fq, const Pre&) const {
;     ...
;                 for (int m = 0; m < 4; ++m) { const int r = row0 + ai * HALF + m * 16;
;                     const u32x4 zw = zv[m], gw = gv[m];
;                     const f32x4 a0 = acc[ai][bj][m][0] + bs[bj][0], a1 = acc[ai][bj][m][1] + bs[bj][1];
;                     u32x4 w;
;                     w.x = cvt_pk_bf16(glu_gate_f(bf_lo(gw.x), a0[0], bf_lo(zw.x)), glu_gate_f(bf_hi(gw.x), a0[1], bf_hi(zw.x)));
;                     w.y = cvt_pk_bf16(glu_gate_f(bf_lo(gw.y), a0[2], bf_lo(zw.y)), glu_gate_f(bf_hi(gw.y), a0[3], bf_hi(zw.y)));
;                     w.z = cvt_pk_bf16(glu_gate_f(bf_lo(gw.z), a1[0], bf_lo(zw.z)), glu_gate_f(bf_hi(gw.z), a1[1], bf_hi(zw.z)));
;                     w.w = cvt_pk_bf16(glu_gate_f(bf_lo(gw.w), a1[2], bf_lo(zw.w)), glu_gate_f(bf_hi(gw.w), a1[3], bf_hi(zw.w)));
;                     *(u32x4*)(O + (size_t)r * DE + c) = w; } } }
	v_mul_f32_e32 v18, 0xbfb8aa3b, v21
	v_exp_f32_e32 v18, v18
	v_mul_f32_e32 v21, v25, v34
	v_pk_add_f32 v[18:19], v[18:19], 1.0 op_sel_hi:[1,0]
	s_nop 0
	v_mul_f32_e32 v18, v18, v19
	v_rcp_f32_e32 v18, v18
	s_nop 0
	v_mul_f32_e32 v18, v21, v18
	v_cvt_pk_bf16_f32 v25, v20, v18
	v_lshlrev_b32_e32 v20, 16, v50
	v_exp_f32_e32 v18, v14
	v_mul_f32_e32 v14, 0xbfb8aa3b, v20
	v_exp_f32_e32 v19, v14
	v_lshlrev_b32_e32 v21, 16, v54
	v_mul_f32_e32 v14, v21, v20
	v_and_b32_e32 v20, 0xffff0000, v50
	v_pk_add_f32 v[18:19], v[18:19], 1.0 op_sel_hi:[1,0]
	global_store_dwordx4 v[108:109], v[22:25], off offset:256
	v_mul_f32_e32 v18, v18, v19
	v_rcp_f32_e32 v18, v18
	v_and_b32_e32 v19, 0xffff0000, v54
	v_mul_f32_e32 v19, v19, v20
	v_mul_f32_e32 v18, v14, v18
	v_mul_f32_e32 v14, 0xbfb8aa3b, v15
	v_mul_f32_e32 v15, 0xbfb8aa3b, v20
	v_exp_f32_e32 v14, v14
	v_exp_f32_e32 v15, v15
	v_lshlrev_b32_e32 v20, 16, v55
	v_pk_add_f32 v[14:15], v[14:15], 1.0 op_sel_hi:[1,0]
	s_nop 0
	v_mul_f32_e32 v14, v14, v15
	v_rcp_f32_e32 v14, v14
	v_lshlrev_b32_e32 v15, 16, v51
	v_mul_f32_e32 v14, v19, v14
	v_cvt_pk_bf16_f32 v14, v18, v14
	v_exp_f32_e32 v18, v16
	v_mul_f32_e32 v16, 0xbfb8aa3b, v15
	v_exp_f32_e32 v19, v16
	v_mul_f32_e32 v15, v20, v15
	v_pk_add_f32 v[18:19], v[18:19], 1.0 op_sel_hi:[1,0]
	s_nop 0
	v_mul_f32_e32 v16, v18, v19
	v_rcp_f32_e32 v16, v16
	v_and_b32_e32 v19, 0xffff0000, v51
	v_and_b32_e32 v18, 0xffff0000, v55
	v_mul_f32_e32 v18, v18, v19
	v_mul_f32_e32 v15, v15, v16
	v_mul_f32_e32 v16, 0xbfb8aa3b, v17
	v_mul_f32_e32 v17, 0xbfb8aa3b, v19
	v_exp_f32_e32 v16, v16
	v_exp_f32_e32 v17, v17
	v_lshlrev_b32_e32 v19, 16, v56
	v_pk_add_f32 v[16:17], v[16:17], 1.0 op_sel_hi:[1,0]
	s_nop 0
	v_mul_f32_e32 v16, v16, v17
	v_rcp_f32_e32 v16, v16
	s_nop 0
	v_mul_f32_e32 v16, v18, v16
	v_lshlrev_b32_e32 v18, 16, v52
	v_cvt_pk_bf16_f32 v15, v15, v16
	v_exp_f32_e32 v16, v10
	v_mul_f32_e32 v10, 0xbfb8aa3b, v18
	v_exp_f32_e32 v17, v10
	v_mul_f32_e32 v10, v19, v18
	v_and_b32_e32 v18, 0xffff0000, v52
	v_pk_add_f32 v[16:17], v[16:17], 1.0 op_sel_hi:[1,0]
	s_nop 0
	v_mul_f32_e32 v16, v16, v17
	v_rcp_f32_e32 v16, v16
	v_and_b32_e32 v17, 0xffff0000, v56
	v_mul_f32_e32 v17, v17, v18
	v_mul_f32_e32 v16, v10, v16
	v_mul_f32_e32 v10, 0xbfb8aa3b, v11
	v_mul_f32_e32 v11, 0xbfb8aa3b, v18
	v_exp_f32_e32 v10, v10
	v_exp_f32_e32 v11, v11
	v_lshlrev_b32_e32 v18, 16, v57
	v_pk_add_f32 v[10:11], v[10:11], 1.0 op_sel_hi:[1,0]
	s_nop 0
	v_mul_f32_e32 v10, v10, v11
	v_rcp_f32_e32 v10, v10
	s_nop 0
	v_mul_f32_e32 v10, v17, v10
	v_lshlrev_b32_e32 v17, 16, v53
	v_cvt_pk_bf16_f32 v16, v16, v10
	v_mul_f32_e32 v10, 0xbfb8aa3b, v12
	v_mul_f32_e32 v11, 0xbfb8aa3b, v17
	v_exp_f32_e32 v10, v10
	v_exp_f32_e32 v11, v11
	v_mul_f32_e32 v12, v18, v17
	v_and_b32_e32 v18, 0xffff0000, v53
	v_and_b32_e32 v17, 0xffff0000, v57
	v_pk_add_f32 v[10:11], v[10:11], 1.0 op_sel_hi:[1,0]
	s_nop 0
	v_mul_f32_e32 v10, v10, v11
	v_rcp_f32_e32 v10, v10
	v_mul_f32_e32 v11, 0xbfb8aa3b, v18
	v_exp_f32_e32 v11, v11
	v_mul_f32_e32 v12, v12, v10
	v_mul_f32_e32 v10, 0xbfb8aa3b, v13
	v_exp_f32_e32 v10, v10
	v_mul_f32_e32 v13, v17, v18
	v_pk_add_f32 v[10:11], v[10:11], 1.0 op_sel_hi:[1,0]
	s_nop 0
	v_mul_f32_e32 v10, v10, v11
	v_rcp_f32_e32 v10, v10
	s_nop 0
	v_mul_f32_e32 v10, v13, v10
	v_cvt_pk_bf16_f32 v17, v12, v10
	v_lshlrev_b32_e32 v12, 16, v42
	v_exp_f32_e32 v10, v6
	v_mul_f32_e32 v6, 0xbfb8aa3b, v12
	v_exp_f32_e32 v11, v6
	v_lshlrev_b32_e32 v13, 16, v46
	v_mul_f32_e32 v6, v13, v12
	v_and_b32_e32 v12, 0xffff0000, v42
	v_pk_add_f32 v[10:11], v[10:11], 1.0 op_sel_hi:[1,0]
	global_store_dwordx4 v[110:111], v[14:17], off offset:256
	v_mul_f32_e32 v10, v10, v11
	v_rcp_f32_e32 v10, v10
	v_and_b32_e32 v11, 0xffff0000, v46
	v_mul_f32_e32 v11, v11, v12
	v_mul_f32_e32 v10, v6, v10
	v_mul_f32_e32 v6, 0xbfb8aa3b, v7
	v_mul_f32_e32 v7, 0xbfb8aa3b, v12
	v_exp_f32_e32 v6, v6
	v_exp_f32_e32 v7, v7
	v_lshlrev_b32_e32 v12, 16, v47
	v_pk_add_f32 v[6:7], v[6:7], 1.0 op_sel_hi:[1,0]
	s_nop 0
	v_mul_f32_e32 v6, v6, v7
	v_rcp_f32_e32 v6, v6
	v_lshlrev_b32_e32 v7, 16, v43
	v_mul_f32_e32 v6, v11, v6
	v_cvt_pk_bf16_f32 v6, v10, v6
	v_exp_f32_e32 v10, v8
	v_mul_f32_e32 v8, 0xbfb8aa3b, v7
	v_exp_f32_e32 v11, v8
	v_mul_f32_e32 v7, v12, v7
	v_pk_add_f32 v[10:11], v[10:11], 1.0 op_sel_hi:[1,0]
	s_nop 0
	v_mul_f32_e32 v8, v10, v11
	v_rcp_f32_e32 v8, v8
	v_and_b32_e32 v11, 0xffff0000, v43
	v_and_b32_e32 v10, 0xffff0000, v47
	v_mul_f32_e32 v10, v10, v11
	v_mul_f32_e32 v7, v7, v8
	v_mul_f32_e32 v8, 0xbfb8aa3b, v9
	v_mul_f32_e32 v9, 0xbfb8aa3b, v11
	v_exp_f32_e32 v8, v8
	v_exp_f32_e32 v9, v9
	v_lshlrev_b32_e32 v11, 16, v48
	v_pk_add_f32 v[8:9], v[8:9], 1.0 op_sel_hi:[1,0]
	s_nop 0
	v_mul_f32_e32 v8, v8, v9
	v_rcp_f32_e32 v8, v8
	s_nop 0
	v_mul_f32_e32 v8, v10, v8
	v_lshlrev_b32_e32 v10, 16, v44
	v_cvt_pk_bf16_f32 v7, v7, v8
	v_exp_f32_e32 v8, v2
	v_mul_f32_e32 v2, 0xbfb8aa3b, v10
	v_exp_f32_e32 v9, v2
	v_mul_f32_e32 v2, v11, v10
	v_and_b32_e32 v10, 0xffff0000, v44
	v_pk_add_f32 v[8:9], v[8:9], 1.0 op_sel_hi:[1,0]
	s_nop 0
	v_mul_f32_e32 v8, v8, v9
	v_rcp_f32_e32 v8, v8
	v_and_b32_e32 v9, 0xffff0000, v48
	v_mul_f32_e32 v9, v9, v10
	v_mul_f32_e32 v8, v2, v8
	v_mul_f32_e32 v2, 0xbfb8aa3b, v3
	v_mul_f32_e32 v3, 0xbfb8aa3b, v10
	v_exp_f32_e32 v2, v2
	v_exp_f32_e32 v3, v3
	v_lshlrev_b32_e32 v10, 16, v49
	v_pk_add_f32 v[2:3], v[2:3], 1.0 op_sel_hi:[1,0]
	s_nop 0
	v_mul_f32_e32 v2, v2, v3
	v_rcp_f32_e32 v2, v2
	s_nop 0
	v_mul_f32_e32 v2, v9, v2
	v_lshlrev_b32_e32 v9, 16, v45
	v_cvt_pk_bf16_f32 v8, v8, v2
	v_mul_f32_e32 v2, 0xbfb8aa3b, v4
	v_mul_f32_e32 v3, 0xbfb8aa3b, v9
	v_exp_f32_e32 v2, v2
	v_exp_f32_e32 v3, v3
	v_mul_f32_e32 v4, v10, v9
	v_and_b32_e32 v10, 0xffff0000, v45
	v_and_b32_e32 v9, 0xffff0000, v49
	v_pk_add_f32 v[2:3], v[2:3], 1.0 op_sel_hi:[1,0]
	s_nop 0
	v_mul_f32_e32 v2, v2, v3
	v_rcp_f32_e32 v2, v2
	v_mul_f32_e32 v3, 0xbfb8aa3b, v10
	v_exp_f32_e32 v3, v3
	v_mul_f32_e32 v4, v4, v2
	v_mul_f32_e32 v2, 0xbfb8aa3b, v5
	v_exp_f32_e32 v2, v2
	v_mul_f32_e32 v5, v9, v10
	v_pk_add_f32 v[2:3], v[2:3], 1.0 op_sel_hi:[1,0]
	s_nop 0
	v_mul_f32_e32 v2, v2, v3
	v_rcp_f32_e32 v2, v2
	s_nop 0
	v_mul_f32_e32 v2, v5, v2
	v_cvt_pk_bf16_f32 v9, v4, v2
	global_store_dwordx4 v[112:113], v[6:9], off offset:256
	s_cbranch_vccz .LBB0_789
	s_waitcnt vmcnt(0)
	v_readlane_b32 s36, v254, 56
	s_cmpk_gt_u32 s18, 0xff
	v_readlane_b32 s37, v254, 57
	s_cbranch_scc1 .LBB0_800
	s_barrier
